# LayerNorm row assignment aligned to XCDs: prompt batch x is normalised by the workgroups of XCD x (where the neighbouring GEMM phases produce / consume it)
# baseline (speedup 1.0000x reference)
; __device__ __forceinline__ int otid() { int t = threadIdx.x; asm volatile("" : "+v"(t)); return t; }
; __device__ __forceinline__ void phase_ln(float* R, const float* __restrict__ g, const float* __restrict__ b, bf16_t* xbf, float samp_scale, const float* __restrict__ part, int nsplit, bool f32_all) {
;   const int tid = otid(), lane = tid & 63, gw = blockIdx.x * 8 + (tid >> 6), nw = gridDim.x * 8;
;   f32x4 gv[4], bv[4];
; #pragma unroll
;   for (int i = 0; i < 4; ++i) { gv[i] = *(const f32x4*)(g + i * 256 + lane * 4); bv[i] = *(const f32x4*)(b + i * 256 + lane * 4); }
;   for (int r = gw; r < MT; r += nw) {
;     float* row = R + (size_t)r * 1024;
;     f32x4 v[4];
; #pragma unroll
;     for (int i = 0; i < 4; ++i) v[i] = *(const f32x4*)(row + i * 256 + lane * 4);
;     if (r >= MP) {
;       for (int sp = 0; sp < nsplit; ++sp) {
;         const float* prow = part + ((size_t)sp * MS + (r - MP)) * 1024;
; #pragma unroll
;         for (int i = 0; i < 4; ++i) v[i] = v[i] + *(const f32x4*)(prow + i * 256 + lane * 4);
;       }
;     }
;     float s = 0.f;
; #pragma unroll
;     for (int i = 0; i < 4; ++i) s += v[i][0] + v[i][1] + v[i][2] + v[i][3];
; #pragma unroll
;     for (int o = 32; o >= 1; o >>= 1) s += __shfl_xor(s, o);
;     const float mean = s * (1.f / 1024.f);
;     float ss = 0.f;
; #pragma unroll
;     for (int i = 0; i < 4; ++i) { v[i] = v[i] - mean; ss += v[i][0] * v[i][0] + v[i][1] * v[i][1] + v[i][2] * v[i][2] + v[i][3] * v[i][3]; }
; #pragma unroll
;     for (int o = 32; o >= 1; o >>= 1) ss += __shfl_xor(ss, o);
;     const float rstd = rsqrtf(ss * (1.f / 1024.f) + LN_EPS);
; #pragma unroll
;     for (int i = 0; i < 4; ++i) {
;       const f32x4 y = v[i] * rstd * gv[i] + bv[i];
;       if (r >= MP) *(f32x4*)(row + i * 256 + lane * 4) = y * samp_scale;
;       else if (f32_all) *(f32x4*)(row + i * 256 + lane * 4) = y;
;       if (xbf) {
;         u32x2 wv;
;         wv[0] = cvt_pk_bf16(y[0], y[1]); wv[1] = cvt_pk_bf16(y[2], y[3]);
;         *(u32x2*)(xbf + (size_t)r * 1024 + i * 256 + lane * 4) = wv;
;       }
;     }
.LBB0_3720:
	s_or_b64 exec, exec, s[0:1]
	v_readlane_b32 s0, v254, 51
	s_nop 0
	s_cmp_lg_u32 s0, 0
	s_cbranch_scc1 .Lln1_orig
	v_readlane_b32 s6, v254, 2
	v_readlane_b32 s7, v254, 3
	v_readlane_b32 s8, v255, 22
	s_waitcnt lgkmcnt(0)
	s_barrier
	s_load_dwordx4 s[0:3], s[6:7], 0x78
	s_load_dwordx4 s[4:7], s[6:7], 0xa8
	v_readlane_b32 s9, v254, 15
	v_readfirstlane_b32 s10, v244
	v_lshlrev_b32_e32 v114, 4, v252
	v_lshlrev_b32_e32 v115, 3, v252
	s_lshr_b32 s10, s10, 6
	s_lshr_b32 s9, s9, 3
	s_and_b32 s11, s9, 7
	s_lshl_b32 s11, s11, 12
	s_lshr_b32 s9, s9, 3
	s_lshl_b32 s9, s9, 3
	s_add_i32 s9, s9, s11
	s_add_i32 s9, s9, s10
	s_lshl_b32 s11, s8, 12
	s_waitcnt lgkmcnt(0)
	s_add_u32 s0, s0, s11
	s_addc_u32 s1, s1, 0
	s_add_u32 s2, s2, s11
	s_addc_u32 s3, s3, 0
	global_load_dwordx4 v[34:37], v114, s[0:1] offset:0
	global_load_dwordx4 v[38:41], v114, s[0:1] offset:1024
	global_load_dwordx4 v[42:45], v114, s[0:1] offset:2048
	global_load_dwordx4 v[46:49], v114, s[0:1] offset:3072
	global_load_dwordx4 v[50:53], v114, s[2:3] offset:0
	global_load_dwordx4 v[54:57], v114, s[2:3] offset:1024
	global_load_dwordx4 v[58:61], v114, s[2:3] offset:2048
	global_load_dwordx4 v[62:65], v114, s[2:3] offset:3072
	s_lshl_b32 s11, s9, 12
	s_add_u32 s0, s4, s11
	s_addc_u32 s1, s5, 0
	s_lshl_b32 s11, s9, 11
	s_add_u32 s11, s11, 0x39c0000
	s_add_u32 s2, s6, s11
	s_addc_u32 s3, s7, 0
	global_load_dwordx4 v[0:3], v114, s[0:1] offset:0
	global_load_dwordx4 v[4:7], v114, s[0:1] offset:1024
	global_load_dwordx4 v[8:11], v114, s[0:1] offset:2048
	global_load_dwordx4 v[12:15], v114, s[0:1] offset:3072
	s_add_u32 s0, s0, 0x100000
	s_addc_u32 s1, s1, 0
	global_load_dwordx4 v[18:21], v114, s[0:1] offset:0
	global_load_dwordx4 v[22:25], v114, s[0:1] offset:1024
	global_load_dwordx4 v[26:29], v114, s[0:1] offset:2048
	global_load_dwordx4 v[30:33], v114, s[0:1] offset:3072
	s_waitcnt vmcnt(4)
	v_pk_add_f32 v[66:67], v[0:1], v[2:3]
	v_pk_add_f32 v[68:69], v[4:5], v[6:7]
	v_pk_add_f32 v[70:71], v[8:9], v[10:11]
	v_pk_add_f32 v[72:73], v[12:13], v[14:15]
	v_pk_add_f32 v[66:67], v[66:67], v[68:69]
	v_pk_add_f32 v[70:71], v[70:71], v[72:73]
	v_pk_add_f32 v[66:67], v[66:67], v[70:71]
	v_add_f32_e32 v66, v66, v67
	s_nop 1
	v_add_f32_dpp v66, v66, v66 row_shr:1 row_mask:0xf bank_mask:0xf bound_ctrl:1
	s_nop 1
	v_add_f32_dpp v66, v66, v66 row_shr:2 row_mask:0xf bank_mask:0xf bound_ctrl:1
	s_nop 1
	v_add_f32_dpp v66, v66, v66 row_shr:4 row_mask:0xf bank_mask:0xf bound_ctrl:1
	s_nop 1
	v_add_f32_dpp v66, v66, v66 row_shr:8 row_mask:0xf bank_mask:0xf bound_ctrl:1
	s_nop 0
	v_readlane_b32 s9, v66, 15
	v_readlane_b32 s10, v66, 31
	v_readlane_b32 s11, v66, 47
	v_readlane_b32 vcc_lo, v66, 63
	s_nop 1
	v_mov_b32_e32 v66, s9
	v_add_f32_e32 v66, s10, v66
	v_add_f32_e32 v66, s11, v66
	v_add_f32_e32 v66, vcc_lo, v66
	v_mul_f32_e32 v116, 0x3a800000, v66
	v_mov_b32_e32 v117, v116
	v_pk_add_f32 v[0:1], v[0:1], v[116:117] neg_lo:[0,1] neg_hi:[0,1]
	v_pk_add_f32 v[2:3], v[2:3], v[116:117] neg_lo:[0,1] neg_hi:[0,1]
	v_pk_add_f32 v[4:5], v[4:5], v[116:117] neg_lo:[0,1] neg_hi:[0,1]
	v_pk_add_f32 v[6:7], v[6:7], v[116:117] neg_lo:[0,1] neg_hi:[0,1]
	v_pk_add_f32 v[8:9], v[8:9], v[116:117] neg_lo:[0,1] neg_hi:[0,1]
	v_pk_add_f32 v[10:11], v[10:11], v[116:117] neg_lo:[0,1] neg_hi:[0,1]
	v_pk_add_f32 v[12:13], v[12:13], v[116:117] neg_lo:[0,1] neg_hi:[0,1]
	v_pk_add_f32 v[14:15], v[14:15], v[116:117] neg_lo:[0,1] neg_hi:[0,1]
	v_pk_mul_f32 v[66:67], v[0:1], v[0:1]
	v_pk_mul_f32 v[68:69], v[2:3], v[2:3]
	v_pk_fma_f32 v[66:67], v[4:5], v[4:5], v[66:67]
	v_pk_fma_f32 v[68:69], v[6:7], v[6:7], v[68:69]
	v_pk_fma_f32 v[66:67], v[8:9], v[8:9], v[66:67]
	v_pk_fma_f32 v[68:69], v[10:11], v[10:11], v[68:69]
	v_pk_fma_f32 v[66:67], v[12:13], v[12:13], v[66:67]
	v_pk_fma_f32 v[68:69], v[14:15], v[14:15], v[68:69]
	v_pk_add_f32 v[66:67], v[66:67], v[68:69]
	v_add_f32_e32 v66, v66, v67
	s_nop 1
	v_add_f32_dpp v66, v66, v66 row_shr:1 row_mask:0xf bank_mask:0xf bound_ctrl:1
	s_nop 1
	v_add_f32_dpp v66, v66, v66 row_shr:2 row_mask:0xf bank_mask:0xf bound_ctrl:1
	s_nop 1
	v_add_f32_dpp v66, v66, v66 row_shr:4 row_mask:0xf bank_mask:0xf bound_ctrl:1
	s_nop 1
	v_add_f32_dpp v66, v66, v66 row_shr:8 row_mask:0xf bank_mask:0xf bound_ctrl:1
	s_nop 0
	v_readlane_b32 s9, v66, 15
	v_readlane_b32 s10, v66, 31
	v_readlane_b32 s11, v66, 47
	v_readlane_b32 vcc_lo, v66, 63
	s_nop 1
	v_mov_b32_e32 v66, s9
	v_add_f32_e32 v66, s10, v66
	v_add_f32_e32 v66, s11, v66
	v_add_f32_e32 v66, vcc_lo, v66
	v_mul_f32_e32 v66, 0x3a800000, v66
	v_add_f32_e32 v66, 0x3727c5ac, v66
	v_rsq_f32_e32 v118, v66
	s_nop 0
	v_mov_b32_e32 v119, v118
	v_pk_mul_f32 v[0:1], v[0:1], v[118:119]
	v_pk_mul_f32 v[2:3], v[2:3], v[118:119]
	v_pk_mul_f32 v[4:5], v[4:5], v[118:119]
	v_pk_mul_f32 v[6:7], v[6:7], v[118:119]
	v_pk_mul_f32 v[8:9], v[8:9], v[118:119]
	v_pk_mul_f32 v[10:11], v[10:11], v[118:119]
	v_pk_mul_f32 v[12:13], v[12:13], v[118:119]
	v_pk_mul_f32 v[14:15], v[14:15], v[118:119]
	v_pk_fma_f32 v[76:77], v[0:1], v[34:35], v[50:51]
	v_pk_fma_f32 v[78:79], v[2:3], v[36:37], v[52:53]
	v_pk_fma_f32 v[80:81], v[4:5], v[38:39], v[54:55]
	v_pk_fma_f32 v[82:83], v[6:7], v[40:41], v[56:57]
	v_pk_fma_f32 v[84:85], v[8:9], v[42:43], v[58:59]
	v_pk_fma_f32 v[86:87], v[10:11], v[44:45], v[60:61]
	v_pk_fma_f32 v[88:89], v[12:13], v[46:47], v[62:63]
	v_pk_fma_f32 v[90:91], v[14:15], v[48:49], v[64:65]
	v_cvt_pk_bf16_f32 v92, v76, v77
	v_cvt_pk_bf16_f32 v93, v78, v79
	v_cvt_pk_bf16_f32 v94, v80, v81
	v_cvt_pk_bf16_f32 v95, v82, v83
	v_cvt_pk_bf16_f32 v96, v84, v85
	v_cvt_pk_bf16_f32 v97, v86, v87
	v_cvt_pk_bf16_f32 v98, v88, v89
	v_cvt_pk_bf16_f32 v99, v90, v91
	global_store_dwordx2 v115, v[92:93], s[2:3] offset:0
	global_store_dwordx2 v115, v[94:95], s[2:3] offset:512
	global_store_dwordx2 v115, v[96:97], s[2:3] offset:1024
	global_store_dwordx2 v115, v[98:99], s[2:3] offset:1536
	s_add_u32 s2, s2, 0x80000
	s_addc_u32 s3, s3, 0
	s_add_u32 s0, s0, 0x100000
	s_addc_u32 s1, s1, 0
	global_load_dwordx4 v[0:3], v114, s[0:1] offset:0
	global_load_dwordx4 v[4:7], v114, s[0:1] offset:1024
	global_load_dwordx4 v[8:11], v114, s[0:1] offset:2048
	global_load_dwordx4 v[12:15], v114, s[0:1] offset:3072
	s_waitcnt vmcnt(8)
; __device__ __forceinline__ void phase_ln(float* R, const float* __restrict__ g, const float* __restrict__ b, bf16_t* xbf, float samp_scale, const float* __restrict__ part, int nsplit, bool f32_all) {
;     ...
;   for (int r = gw; r < MT; r += nw) {
;     float* row = R + (size_t)r * 1024;
;     f32x4 v[4];
; #pragma unroll
;     for (int i = 0; i < 4; ++i) v[i] = *(const f32x4*)(row + i * 256 + lane * 4);
;     if (r >= MP) {
;       for (int sp = 0; sp < nsplit; ++sp) {
;         const float* prow = part + ((size_t)sp * MS + (r - MP)) * 1024;
; #pragma unroll
;         for (int i = 0; i < 4; ++i) v[i] = v[i] + *(const f32x4*)(prow + i * 256 + lane * 4);
;       }
;     }
;     float s = 0.f;
; #pragma unroll
;     for (int i = 0; i < 4; ++i) s += v[i][0] + v[i][1] + v[i][2] + v[i][3];
; #pragma unroll
;     for (int o = 32; o >= 1; o >>= 1) s += __shfl_xor(s, o);
;     const float mean = s * (1.f / 1024.f);
;     float ss = 0.f;
; #pragma unroll
;     for (int i = 0; i < 4; ++i) { v[i] = v[i] - mean; ss += v[i][0] * v[i][0] + v[i][1] * v[i][1] + v[i][2] * v[i][2] + v[i][3] * v[i][3]; }
; #pragma unroll
;     for (int o = 32; o >= 1; o >>= 1) ss += __shfl_xor(ss, o);
;     const float rstd = rsqrtf(ss * (1.f / 1024.f) + LN_EPS);
; #pragma unroll
;     for (int i = 0; i < 4; ++i) {
;       const f32x4 y = v[i] * rstd * gv[i] + bv[i];
;       if (r >= MP) *(f32x4*)(row + i * 256 + lane * 4) = y * samp_scale;
;       else if (f32_all) *(f32x4*)(row + i * 256 + lane * 4) = y;
;       if (xbf) {
;         u32x2 wv;
;         wv[0] = cvt_pk_bf16(y[0], y[1]); wv[1] = cvt_pk_bf16(y[2], y[3]);
;         *(u32x2*)(xbf + (size_t)r * 1024 + i * 256 + lane * 4) = wv;
;       }
;     }
	v_pk_add_f32 v[66:67], v[18:19], v[20:21]
	v_pk_add_f32 v[68:69], v[22:23], v[24:25]
	v_pk_add_f32 v[70:71], v[26:27], v[28:29]
	v_pk_add_f32 v[72:73], v[30:31], v[32:33]
	v_pk_add_f32 v[66:67], v[66:67], v[68:69]
	v_pk_add_f32 v[70:71], v[70:71], v[72:73]
	v_pk_add_f32 v[66:67], v[66:67], v[70:71]
	v_add_f32_e32 v66, v66, v67
	s_nop 1
	v_add_f32_dpp v66, v66, v66 row_shr:1 row_mask:0xf bank_mask:0xf bound_ctrl:1
	s_nop 1
	v_add_f32_dpp v66, v66, v66 row_shr:2 row_mask:0xf bank_mask:0xf bound_ctrl:1
	s_nop 1
	v_add_f32_dpp v66, v66, v66 row_shr:4 row_mask:0xf bank_mask:0xf bound_ctrl:1
	s_nop 1
	v_add_f32_dpp v66, v66, v66 row_shr:8 row_mask:0xf bank_mask:0xf bound_ctrl:1
	s_nop 0
	v_readlane_b32 s9, v66, 15
	v_readlane_b32 s10, v66, 31
	v_readlane_b32 s11, v66, 47
	v_readlane_b32 vcc_lo, v66, 63
	s_nop 1
	v_mov_b32_e32 v66, s9
	v_add_f32_e32 v66, s10, v66
	v_add_f32_e32 v66, s11, v66
	v_add_f32_e32 v66, vcc_lo, v66
	v_mul_f32_e32 v116, 0x3a800000, v66
	v_mov_b32_e32 v117, v116
	v_pk_add_f32 v[18:19], v[18:19], v[116:117] neg_lo:[0,1] neg_hi:[0,1]
	v_pk_add_f32 v[20:21], v[20:21], v[116:117] neg_lo:[0,1] neg_hi:[0,1]
	v_pk_add_f32 v[22:23], v[22:23], v[116:117] neg_lo:[0,1] neg_hi:[0,1]
	v_pk_add_f32 v[24:25], v[24:25], v[116:117] neg_lo:[0,1] neg_hi:[0,1]
	v_pk_add_f32 v[26:27], v[26:27], v[116:117] neg_lo:[0,1] neg_hi:[0,1]
	v_pk_add_f32 v[28:29], v[28:29], v[116:117] neg_lo:[0,1] neg_hi:[0,1]
	v_pk_add_f32 v[30:31], v[30:31], v[116:117] neg_lo:[0,1] neg_hi:[0,1]
	v_pk_add_f32 v[32:33], v[32:33], v[116:117] neg_lo:[0,1] neg_hi:[0,1]
	v_pk_mul_f32 v[66:67], v[18:19], v[18:19]
	v_pk_mul_f32 v[68:69], v[20:21], v[20:21]
	v_pk_fma_f32 v[66:67], v[22:23], v[22:23], v[66:67]
	v_pk_fma_f32 v[68:69], v[24:25], v[24:25], v[68:69]
	v_pk_fma_f32 v[66:67], v[26:27], v[26:27], v[66:67]
	v_pk_fma_f32 v[68:69], v[28:29], v[28:29], v[68:69]
	v_pk_fma_f32 v[66:67], v[30:31], v[30:31], v[66:67]
	v_pk_fma_f32 v[68:69], v[32:33], v[32:33], v[68:69]
	v_pk_add_f32 v[66:67], v[66:67], v[68:69]
	v_add_f32_e32 v66, v66, v67
	s_nop 1
	v_add_f32_dpp v66, v66, v66 row_shr:1 row_mask:0xf bank_mask:0xf bound_ctrl:1
	s_nop 1
	v_add_f32_dpp v66, v66, v66 row_shr:2 row_mask:0xf bank_mask:0xf bound_ctrl:1
	s_nop 1
	v_add_f32_dpp v66, v66, v66 row_shr:4 row_mask:0xf bank_mask:0xf bound_ctrl:1
	s_nop 1
	v_add_f32_dpp v66, v66, v66 row_shr:8 row_mask:0xf bank_mask:0xf bound_ctrl:1
	s_nop 0
	v_readlane_b32 s9, v66, 15
	v_readlane_b32 s10, v66, 31
	v_readlane_b32 s11, v66, 47
	v_readlane_b32 vcc_lo, v66, 63
	s_nop 1
	v_mov_b32_e32 v66, s9
	v_add_f32_e32 v66, s10, v66
	v_add_f32_e32 v66, s11, v66
	v_add_f32_e32 v66, vcc_lo, v66
	v_mul_f32_e32 v66, 0x3a800000, v66
	v_add_f32_e32 v66, 0x3727c5ac, v66
	v_rsq_f32_e32 v118, v66
	s_nop 0
	v_mov_b32_e32 v119, v118
	v_pk_mul_f32 v[18:19], v[18:19], v[118:119]
	v_pk_mul_f32 v[20:21], v[20:21], v[118:119]
	v_pk_mul_f32 v[22:23], v[22:23], v[118:119]
	v_pk_mul_f32 v[24:25], v[24:25], v[118:119]
	v_pk_mul_f32 v[26:27], v[26:27], v[118:119]
	v_pk_mul_f32 v[28:29], v[28:29], v[118:119]
	v_pk_mul_f32 v[30:31], v[30:31], v[118:119]
	v_pk_mul_f32 v[32:33], v[32:33], v[118:119]
	v_pk_fma_f32 v[76:77], v[18:19], v[34:35], v[50:51]
	v_pk_fma_f32 v[78:79], v[20:21], v[36:37], v[52:53]
	v_pk_fma_f32 v[80:81], v[22:23], v[38:39], v[54:55]
	v_pk_fma_f32 v[82:83], v[24:25], v[40:41], v[56:57]
	v_pk_fma_f32 v[84:85], v[26:27], v[42:43], v[58:59]
	v_pk_fma_f32 v[86:87], v[28:29], v[44:45], v[60:61]
	v_pk_fma_f32 v[88:89], v[30:31], v[46:47], v[62:63]
	v_pk_fma_f32 v[90:91], v[32:33], v[48:49], v[64:65]
	v_cvt_pk_bf16_f32 v92, v76, v77
	v_cvt_pk_bf16_f32 v93, v78, v79
	v_cvt_pk_bf16_f32 v94, v80, v81
	v_cvt_pk_bf16_f32 v95, v82, v83
	v_cvt_pk_bf16_f32 v96, v84, v85
	v_cvt_pk_bf16_f32 v97, v86, v87
	v_cvt_pk_bf16_f32 v98, v88, v89
	v_cvt_pk_bf16_f32 v99, v90, v91
	global_store_dwordx2 v115, v[92:93], s[2:3] offset:0
	global_store_dwordx2 v115, v[94:95], s[2:3] offset:512
	global_store_dwordx2 v115, v[96:97], s[2:3] offset:1024
	global_store_dwordx2 v115, v[98:99], s[2:3] offset:1536
	s_add_u32 s2, s2, 0x80000
	s_addc_u32 s3, s3, 0
	s_add_u32 s0, s0, 0x100000
	s_addc_u32 s1, s1, 0
	global_load_dwordx4 v[18:21], v114, s[0:1] offset:0
	global_load_dwordx4 v[22:25], v114, s[0:1] offset:1024
	global_load_dwordx4 v[26:29], v114, s[0:1] offset:2048
	global_load_dwordx4 v[30:33], v114, s[0:1] offset:3072
	s_waitcnt vmcnt(8)
; __device__ __forceinline__ void phase_ln(float* R, const float* __restrict__ g, const float* __restrict__ b, bf16_t* xbf, float samp_scale, const float* __restrict__ part, int nsplit, bool f32_all) {
;     ...
;   for (int r = gw; r < MT; r += nw) {
;     float* row = R + (size_t)r * 1024;
;     f32x4 v[4];
; #pragma unroll
;     for (int i = 0; i < 4; ++i) v[i] = *(const f32x4*)(row + i * 256 + lane * 4);
;     if (r >= MP) {
;       for (int sp = 0; sp < nsplit; ++sp) {
;         const float* prow = part + ((size_t)sp * MS + (r - MP)) * 1024;
; #pragma unroll
;         for (int i = 0; i < 4; ++i) v[i] = v[i] + *(const f32x4*)(prow + i * 256 + lane * 4);
;       }
;     }
;     float s = 0.f;
; #pragma unroll
;     for (int i = 0; i < 4; ++i) s += v[i][0] + v[i][1] + v[i][2] + v[i][3];
; #pragma unroll
;     for (int o = 32; o >= 1; o >>= 1) s += __shfl_xor(s, o);
;     const float mean = s * (1.f / 1024.f);
;     float ss = 0.f;
; #pragma unroll
;     for (int i = 0; i < 4; ++i) { v[i] = v[i] - mean; ss += v[i][0] * v[i][0] + v[i][1] * v[i][1] + v[i][2] * v[i][2] + v[i][3] * v[i][3]; }
; #pragma unroll
;     for (int o = 32; o >= 1; o >>= 1) ss += __shfl_xor(ss, o);
;     const float rstd = rsqrtf(ss * (1.f / 1024.f) + LN_EPS);
; #pragma unroll
;     for (int i = 0; i < 4; ++i) {
;       const f32x4 y = v[i] * rstd * gv[i] + bv[i];
;       if (r >= MP) *(f32x4*)(row + i * 256 + lane * 4) = y * samp_scale;
;       else if (f32_all) *(f32x4*)(row + i * 256 + lane * 4) = y;
;       if (xbf) {
;         u32x2 wv;
;         wv[0] = cvt_pk_bf16(y[0], y[1]); wv[1] = cvt_pk_bf16(y[2], y[3]);
;         *(u32x2*)(xbf + (size_t)r * 1024 + i * 256 + lane * 4) = wv;
;       }
;     }
	v_pk_add_f32 v[66:67], v[0:1], v[2:3]
	v_pk_add_f32 v[68:69], v[4:5], v[6:7]
	v_pk_add_f32 v[70:71], v[8:9], v[10:11]
	v_pk_add_f32 v[72:73], v[12:13], v[14:15]
	v_pk_add_f32 v[66:67], v[66:67], v[68:69]
	v_pk_add_f32 v[70:71], v[70:71], v[72:73]
	v_pk_add_f32 v[66:67], v[66:67], v[70:71]
	v_add_f32_e32 v66, v66, v67
	s_nop 1
	v_add_f32_dpp v66, v66, v66 row_shr:1 row_mask:0xf bank_mask:0xf bound_ctrl:1
	s_nop 1
	v_add_f32_dpp v66, v66, v66 row_shr:2 row_mask:0xf bank_mask:0xf bound_ctrl:1
	s_nop 1
	v_add_f32_dpp v66, v66, v66 row_shr:4 row_mask:0xf bank_mask:0xf bound_ctrl:1
	s_nop 1
	v_add_f32_dpp v66, v66, v66 row_shr:8 row_mask:0xf bank_mask:0xf bound_ctrl:1
	s_nop 0
	v_readlane_b32 s9, v66, 15
	v_readlane_b32 s10, v66, 31
	v_readlane_b32 s11, v66, 47
	v_readlane_b32 vcc_lo, v66, 63
	s_nop 1
	v_mov_b32_e32 v66, s9
	v_add_f32_e32 v66, s10, v66
	v_add_f32_e32 v66, s11, v66
	v_add_f32_e32 v66, vcc_lo, v66
	v_mul_f32_e32 v116, 0x3a800000, v66
	v_mov_b32_e32 v117, v116
	v_pk_add_f32 v[0:1], v[0:1], v[116:117] neg_lo:[0,1] neg_hi:[0,1]
	v_pk_add_f32 v[2:3], v[2:3], v[116:117] neg_lo:[0,1] neg_hi:[0,1]
	v_pk_add_f32 v[4:5], v[4:5], v[116:117] neg_lo:[0,1] neg_hi:[0,1]
	v_pk_add_f32 v[6:7], v[6:7], v[116:117] neg_lo:[0,1] neg_hi:[0,1]
	v_pk_add_f32 v[8:9], v[8:9], v[116:117] neg_lo:[0,1] neg_hi:[0,1]
	v_pk_add_f32 v[10:11], v[10:11], v[116:117] neg_lo:[0,1] neg_hi:[0,1]
	v_pk_add_f32 v[12:13], v[12:13], v[116:117] neg_lo:[0,1] neg_hi:[0,1]
	v_pk_add_f32 v[14:15], v[14:15], v[116:117] neg_lo:[0,1] neg_hi:[0,1]
	v_pk_mul_f32 v[66:67], v[0:1], v[0:1]
	v_pk_mul_f32 v[68:69], v[2:3], v[2:3]
	v_pk_fma_f32 v[66:67], v[4:5], v[4:5], v[66:67]
	v_pk_fma_f32 v[68:69], v[6:7], v[6:7], v[68:69]
	v_pk_fma_f32 v[66:67], v[8:9], v[8:9], v[66:67]
	v_pk_fma_f32 v[68:69], v[10:11], v[10:11], v[68:69]
	v_pk_fma_f32 v[66:67], v[12:13], v[12:13], v[66:67]
	v_pk_fma_f32 v[68:69], v[14:15], v[14:15], v[68:69]
	v_pk_add_f32 v[66:67], v[66:67], v[68:69]
	v_add_f32_e32 v66, v66, v67
	s_nop 1
	v_add_f32_dpp v66, v66, v66 row_shr:1 row_mask:0xf bank_mask:0xf bound_ctrl:1
	s_nop 1
	v_add_f32_dpp v66, v66, v66 row_shr:2 row_mask:0xf bank_mask:0xf bound_ctrl:1
	s_nop 1
	v_add_f32_dpp v66, v66, v66 row_shr:4 row_mask:0xf bank_mask:0xf bound_ctrl:1
	s_nop 1
	v_add_f32_dpp v66, v66, v66 row_shr:8 row_mask:0xf bank_mask:0xf bound_ctrl:1
	s_nop 0
	v_readlane_b32 s9, v66, 15
	v_readlane_b32 s10, v66, 31
	v_readlane_b32 s11, v66, 47
	v_readlane_b32 vcc_lo, v66, 63
	s_nop 1
	v_mov_b32_e32 v66, s9
	v_add_f32_e32 v66, s10, v66
	v_add_f32_e32 v66, s11, v66
	v_add_f32_e32 v66, vcc_lo, v66
	v_mul_f32_e32 v66, 0x3a800000, v66
	v_add_f32_e32 v66, 0x3727c5ac, v66
	v_rsq_f32_e32 v118, v66
	s_nop 0
	v_mov_b32_e32 v119, v118
	v_pk_mul_f32 v[0:1], v[0:1], v[118:119]
	v_pk_mul_f32 v[2:3], v[2:3], v[118:119]
	v_pk_mul_f32 v[4:5], v[4:5], v[118:119]
	v_pk_mul_f32 v[6:7], v[6:7], v[118:119]
	v_pk_mul_f32 v[8:9], v[8:9], v[118:119]
	v_pk_mul_f32 v[10:11], v[10:11], v[118:119]
	v_pk_mul_f32 v[12:13], v[12:13], v[118:119]
	v_pk_mul_f32 v[14:15], v[14:15], v[118:119]
	v_pk_fma_f32 v[76:77], v[0:1], v[34:35], v[50:51]
	v_pk_fma_f32 v[78:79], v[2:3], v[36:37], v[52:53]
	v_pk_fma_f32 v[80:81], v[4:5], v[38:39], v[54:55]
	v_pk_fma_f32 v[82:83], v[6:7], v[40:41], v[56:57]
	v_pk_fma_f32 v[84:85], v[8:9], v[42:43], v[58:59]
	v_pk_fma_f32 v[86:87], v[10:11], v[44:45], v[60:61]
	v_pk_fma_f32 v[88:89], v[12:13], v[46:47], v[62:63]
	v_pk_fma_f32 v[90:91], v[14:15], v[48:49], v[64:65]
	v_cvt_pk_bf16_f32 v92, v76, v77
	v_cvt_pk_bf16_f32 v93, v78, v79
	v_cvt_pk_bf16_f32 v94, v80, v81
	v_cvt_pk_bf16_f32 v95, v82, v83
	v_cvt_pk_bf16_f32 v96, v84, v85
	v_cvt_pk_bf16_f32 v97, v86, v87
	v_cvt_pk_bf16_f32 v98, v88, v89
	v_cvt_pk_bf16_f32 v99, v90, v91
	global_store_dwordx2 v115, v[92:93], s[2:3] offset:0
	global_store_dwordx2 v115, v[94:95], s[2:3] offset:512
	global_store_dwordx2 v115, v[96:97], s[2:3] offset:1024
	global_store_dwordx2 v115, v[98:99], s[2:3] offset:1536
	s_add_u32 s2, s2, 0x80000
	s_addc_u32 s3, s3, 0
	s_add_u32 s0, s0, 0x100000
	s_addc_u32 s1, s1, 0
	global_load_dwordx4 v[0:3], v114, s[0:1] offset:0
	global_load_dwordx4 v[4:7], v114, s[0:1] offset:1024
	global_load_dwordx4 v[8:11], v114, s[0:1] offset:2048
	global_load_dwordx4 v[12:15], v114, s[0:1] offset:3072
	s_waitcnt vmcnt(8)
; __device__ __forceinline__ void phase_ln(float* R, const float* __restrict__ g, const float* __restrict__ b, bf16_t* xbf, float samp_scale, const float* __restrict__ part, int nsplit, bool f32_all) {
;     ...
;   for (int r = gw; r < MT; r += nw) {
;     float* row = R + (size_t)r * 1024;
;     f32x4 v[4];
; #pragma unroll
;     for (int i = 0; i < 4; ++i) v[i] = *(const f32x4*)(row + i * 256 + lane * 4);
;     if (r >= MP) {
;       for (int sp = 0; sp < nsplit; ++sp) {
;         const float* prow = part + ((size_t)sp * MS + (r - MP)) * 1024;
; #pragma unroll
;         for (int i = 0; i < 4; ++i) v[i] = v[i] + *(const f32x4*)(prow + i * 256 + lane * 4);
;       }
;     }
;     float s = 0.f;
; #pragma unroll
;     for (int i = 0; i < 4; ++i) s += v[i][0] + v[i][1] + v[i][2] + v[i][3];
; #pragma unroll
;     for (int o = 32; o >= 1; o >>= 1) s += __shfl_xor(s, o);
;     const float mean = s * (1.f / 1024.f);
;     float ss = 0.f;
; #pragma unroll
;     for (int i = 0; i < 4; ++i) { v[i] = v[i] - mean; ss += v[i][0] * v[i][0] + v[i][1] * v[i][1] + v[i][2] * v[i][2] + v[i][3] * v[i][3]; }
; #pragma unroll
;     for (int o = 32; o >= 1; o >>= 1) ss += __shfl_xor(ss, o);
;     const float rstd = rsqrtf(ss * (1.f / 1024.f) + LN_EPS);
; #pragma unroll
;     for (int i = 0; i < 4; ++i) {
;       const f32x4 y = v[i] * rstd * gv[i] + bv[i];
;       if (r >= MP) *(f32x4*)(row + i * 256 + lane * 4) = y * samp_scale;
;       else if (f32_all) *(f32x4*)(row + i * 256 + lane * 4) = y;
;       if (xbf) {
;         u32x2 wv;
;         wv[0] = cvt_pk_bf16(y[0], y[1]); wv[1] = cvt_pk_bf16(y[2], y[3]);
;         *(u32x2*)(xbf + (size_t)r * 1024 + i * 256 + lane * 4) = wv;
;       }
;     }
	v_pk_add_f32 v[66:67], v[18:19], v[20:21]
	v_pk_add_f32 v[68:69], v[22:23], v[24:25]
	v_pk_add_f32 v[70:71], v[26:27], v[28:29]
	v_pk_add_f32 v[72:73], v[30:31], v[32:33]
	v_pk_add_f32 v[66:67], v[66:67], v[68:69]
	v_pk_add_f32 v[70:71], v[70:71], v[72:73]
	v_pk_add_f32 v[66:67], v[66:67], v[70:71]
	v_add_f32_e32 v66, v66, v67
	s_nop 1
	v_add_f32_dpp v66, v66, v66 row_shr:1 row_mask:0xf bank_mask:0xf bound_ctrl:1
	s_nop 1
	v_add_f32_dpp v66, v66, v66 row_shr:2 row_mask:0xf bank_mask:0xf bound_ctrl:1
	s_nop 1
	v_add_f32_dpp v66, v66, v66 row_shr:4 row_mask:0xf bank_mask:0xf bound_ctrl:1
	s_nop 1
	v_add_f32_dpp v66, v66, v66 row_shr:8 row_mask:0xf bank_mask:0xf bound_ctrl:1
	s_nop 0
	v_readlane_b32 s9, v66, 15
	v_readlane_b32 s10, v66, 31
	v_readlane_b32 s11, v66, 47
	v_readlane_b32 vcc_lo, v66, 63
	s_nop 1
	v_mov_b32_e32 v66, s9
	v_add_f32_e32 v66, s10, v66
	v_add_f32_e32 v66, s11, v66
	v_add_f32_e32 v66, vcc_lo, v66
	v_mul_f32_e32 v116, 0x3a800000, v66
	v_mov_b32_e32 v117, v116
	v_pk_add_f32 v[18:19], v[18:19], v[116:117] neg_lo:[0,1] neg_hi:[0,1]
	v_pk_add_f32 v[20:21], v[20:21], v[116:117] neg_lo:[0,1] neg_hi:[0,1]
	v_pk_add_f32 v[22:23], v[22:23], v[116:117] neg_lo:[0,1] neg_hi:[0,1]
	v_pk_add_f32 v[24:25], v[24:25], v[116:117] neg_lo:[0,1] neg_hi:[0,1]
	v_pk_add_f32 v[26:27], v[26:27], v[116:117] neg_lo:[0,1] neg_hi:[0,1]
	v_pk_add_f32 v[28:29], v[28:29], v[116:117] neg_lo:[0,1] neg_hi:[0,1]
	v_pk_add_f32 v[30:31], v[30:31], v[116:117] neg_lo:[0,1] neg_hi:[0,1]
	v_pk_add_f32 v[32:33], v[32:33], v[116:117] neg_lo:[0,1] neg_hi:[0,1]
	v_pk_mul_f32 v[66:67], v[18:19], v[18:19]
	v_pk_mul_f32 v[68:69], v[20:21], v[20:21]
	v_pk_fma_f32 v[66:67], v[22:23], v[22:23], v[66:67]
	v_pk_fma_f32 v[68:69], v[24:25], v[24:25], v[68:69]
	v_pk_fma_f32 v[66:67], v[26:27], v[26:27], v[66:67]
	v_pk_fma_f32 v[68:69], v[28:29], v[28:29], v[68:69]
	v_pk_fma_f32 v[66:67], v[30:31], v[30:31], v[66:67]
	v_pk_fma_f32 v[68:69], v[32:33], v[32:33], v[68:69]
	v_pk_add_f32 v[66:67], v[66:67], v[68:69]
	v_add_f32_e32 v66, v66, v67
	s_nop 1
	v_add_f32_dpp v66, v66, v66 row_shr:1 row_mask:0xf bank_mask:0xf bound_ctrl:1
	s_nop 1
	v_add_f32_dpp v66, v66, v66 row_shr:2 row_mask:0xf bank_mask:0xf bound_ctrl:1
	s_nop 1
	v_add_f32_dpp v66, v66, v66 row_shr:4 row_mask:0xf bank_mask:0xf bound_ctrl:1
	s_nop 1
	v_add_f32_dpp v66, v66, v66 row_shr:8 row_mask:0xf bank_mask:0xf bound_ctrl:1
	s_nop 0
	v_readlane_b32 s9, v66, 15
	v_readlane_b32 s10, v66, 31
	v_readlane_b32 s11, v66, 47
	v_readlane_b32 vcc_lo, v66, 63
	s_nop 1
	v_mov_b32_e32 v66, s9
	v_add_f32_e32 v66, s10, v66
	v_add_f32_e32 v66, s11, v66
	v_add_f32_e32 v66, vcc_lo, v66
	v_mul_f32_e32 v66, 0x3a800000, v66
	v_add_f32_e32 v66, 0x3727c5ac, v66
	v_rsq_f32_e32 v118, v66
	s_nop 0
	v_mov_b32_e32 v119, v118
	v_pk_mul_f32 v[18:19], v[18:19], v[118:119]
	v_pk_mul_f32 v[20:21], v[20:21], v[118:119]
	v_pk_mul_f32 v[22:23], v[22:23], v[118:119]
	v_pk_mul_f32 v[24:25], v[24:25], v[118:119]
	v_pk_mul_f32 v[26:27], v[26:27], v[118:119]
	v_pk_mul_f32 v[28:29], v[28:29], v[118:119]
	v_pk_mul_f32 v[30:31], v[30:31], v[118:119]
	v_pk_mul_f32 v[32:33], v[32:33], v[118:119]
	v_pk_fma_f32 v[76:77], v[18:19], v[34:35], v[50:51]
	v_pk_fma_f32 v[78:79], v[20:21], v[36:37], v[52:53]
	v_pk_fma_f32 v[80:81], v[22:23], v[38:39], v[54:55]
	v_pk_fma_f32 v[82:83], v[24:25], v[40:41], v[56:57]
	v_pk_fma_f32 v[84:85], v[26:27], v[42:43], v[58:59]
	v_pk_fma_f32 v[86:87], v[28:29], v[44:45], v[60:61]
	v_pk_fma_f32 v[88:89], v[30:31], v[46:47], v[62:63]
	v_pk_fma_f32 v[90:91], v[32:33], v[48:49], v[64:65]
	v_cvt_pk_bf16_f32 v92, v76, v77
	v_cvt_pk_bf16_f32 v93, v78, v79
	v_cvt_pk_bf16_f32 v94, v80, v81
	v_cvt_pk_bf16_f32 v95, v82, v83
	v_cvt_pk_bf16_f32 v96, v84, v85
	v_cvt_pk_bf16_f32 v97, v86, v87
	v_cvt_pk_bf16_f32 v98, v88, v89
	v_cvt_pk_bf16_f32 v99, v90, v91
	global_store_dwordx2 v115, v[92:93], s[2:3] offset:0
	global_store_dwordx2 v115, v[94:95], s[2:3] offset:512
	global_store_dwordx2 v115, v[96:97], s[2:3] offset:1024
	global_store_dwordx2 v115, v[98:99], s[2:3] offset:1536
	s_add_u32 s2, s2, 0x80000
	s_addc_u32 s3, s3, 0
	s_add_u32 s0, s0, 0x100000
	s_addc_u32 s1, s1, 0
	global_load_dwordx4 v[18:21], v114, s[0:1] offset:0
	global_load_dwordx4 v[22:25], v114, s[0:1] offset:1024
	global_load_dwordx4 v[26:29], v114, s[0:1] offset:2048
	global_load_dwordx4 v[30:33], v114, s[0:1] offset:3072
	s_waitcnt vmcnt(8)
; __device__ __forceinline__ void phase_ln(float* R, const float* __restrict__ g, const float* __restrict__ b, bf16_t* xbf, float samp_scale, const float* __restrict__ part, int nsplit, bool f32_all) {
;     ...
;   for (int r = gw; r < MT; r += nw) {
;     float* row = R + (size_t)r * 1024;
;     f32x4 v[4];
; #pragma unroll
;     for (int i = 0; i < 4; ++i) v[i] = *(const f32x4*)(row + i * 256 + lane * 4);
;     if (r >= MP) {
;       for (int sp = 0; sp < nsplit; ++sp) {
;         const float* prow = part + ((size_t)sp * MS + (r - MP)) * 1024;
; #pragma unroll
;         for (int i = 0; i < 4; ++i) v[i] = v[i] + *(const f32x4*)(prow + i * 256 + lane * 4);
;       }
;     }
;     float s = 0.f;
; #pragma unroll
;     for (int i = 0; i < 4; ++i) s += v[i][0] + v[i][1] + v[i][2] + v[i][3];
; #pragma unroll
;     for (int o = 32; o >= 1; o >>= 1) s += __shfl_xor(s, o);
;     const float mean = s * (1.f / 1024.f);
;     float ss = 0.f;
; #pragma unroll
;     for (int i = 0; i < 4; ++i) { v[i] = v[i] - mean; ss += v[i][0] * v[i][0] + v[i][1] * v[i][1] + v[i][2] * v[i][2] + v[i][3] * v[i][3]; }
; #pragma unroll
;     for (int o = 32; o >= 1; o >>= 1) ss += __shfl_xor(ss, o);
;     const float rstd = rsqrtf(ss * (1.f / 1024.f) + LN_EPS);
; #pragma unroll
;     for (int i = 0; i < 4; ++i) {
;       const f32x4 y = v[i] * rstd * gv[i] + bv[i];
;       if (r >= MP) *(f32x4*)(row + i * 256 + lane * 4) = y * samp_scale;
;       else if (f32_all) *(f32x4*)(row + i * 256 + lane * 4) = y;
;       if (xbf) {
;         u32x2 wv;
;         wv[0] = cvt_pk_bf16(y[0], y[1]); wv[1] = cvt_pk_bf16(y[2], y[3]);
;         *(u32x2*)(xbf + (size_t)r * 1024 + i * 256 + lane * 4) = wv;
;       }
;     }
	v_pk_add_f32 v[66:67], v[0:1], v[2:3]
	v_pk_add_f32 v[68:69], v[4:5], v[6:7]
	v_pk_add_f32 v[70:71], v[8:9], v[10:11]
	v_pk_add_f32 v[72:73], v[12:13], v[14:15]
	v_pk_add_f32 v[66:67], v[66:67], v[68:69]
	v_pk_add_f32 v[70:71], v[70:71], v[72:73]
	v_pk_add_f32 v[66:67], v[66:67], v[70:71]
	v_add_f32_e32 v66, v66, v67
	s_nop 1
	v_add_f32_dpp v66, v66, v66 row_shr:1 row_mask:0xf bank_mask:0xf bound_ctrl:1
	s_nop 1
	v_add_f32_dpp v66, v66, v66 row_shr:2 row_mask:0xf bank_mask:0xf bound_ctrl:1
	s_nop 1
	v_add_f32_dpp v66, v66, v66 row_shr:4 row_mask:0xf bank_mask:0xf bound_ctrl:1
	s_nop 1
	v_add_f32_dpp v66, v66, v66 row_shr:8 row_mask:0xf bank_mask:0xf bound_ctrl:1
	s_nop 0
	v_readlane_b32 s9, v66, 15
	v_readlane_b32 s10, v66, 31
	v_readlane_b32 s11, v66, 47
	v_readlane_b32 vcc_lo, v66, 63
	s_nop 1
	v_mov_b32_e32 v66, s9
	v_add_f32_e32 v66, s10, v66
	v_add_f32_e32 v66, s11, v66
	v_add_f32_e32 v66, vcc_lo, v66
	v_mul_f32_e32 v116, 0x3a800000, v66
	v_mov_b32_e32 v117, v116
	v_pk_add_f32 v[0:1], v[0:1], v[116:117] neg_lo:[0,1] neg_hi:[0,1]
	v_pk_add_f32 v[2:3], v[2:3], v[116:117] neg_lo:[0,1] neg_hi:[0,1]
	v_pk_add_f32 v[4:5], v[4:5], v[116:117] neg_lo:[0,1] neg_hi:[0,1]
	v_pk_add_f32 v[6:7], v[6:7], v[116:117] neg_lo:[0,1] neg_hi:[0,1]
	v_pk_add_f32 v[8:9], v[8:9], v[116:117] neg_lo:[0,1] neg_hi:[0,1]
	v_pk_add_f32 v[10:11], v[10:11], v[116:117] neg_lo:[0,1] neg_hi:[0,1]
	v_pk_add_f32 v[12:13], v[12:13], v[116:117] neg_lo:[0,1] neg_hi:[0,1]
	v_pk_add_f32 v[14:15], v[14:15], v[116:117] neg_lo:[0,1] neg_hi:[0,1]
	v_pk_mul_f32 v[66:67], v[0:1], v[0:1]
	v_pk_mul_f32 v[68:69], v[2:3], v[2:3]
	v_pk_fma_f32 v[66:67], v[4:5], v[4:5], v[66:67]
	v_pk_fma_f32 v[68:69], v[6:7], v[6:7], v[68:69]
	v_pk_fma_f32 v[66:67], v[8:9], v[8:9], v[66:67]
	v_pk_fma_f32 v[68:69], v[10:11], v[10:11], v[68:69]
	v_pk_fma_f32 v[66:67], v[12:13], v[12:13], v[66:67]
	v_pk_fma_f32 v[68:69], v[14:15], v[14:15], v[68:69]
	v_pk_add_f32 v[66:67], v[66:67], v[68:69]
	v_add_f32_e32 v66, v66, v67
	s_nop 1
	v_add_f32_dpp v66, v66, v66 row_shr:1 row_mask:0xf bank_mask:0xf bound_ctrl:1
	s_nop 1
	v_add_f32_dpp v66, v66, v66 row_shr:2 row_mask:0xf bank_mask:0xf bound_ctrl:1
	s_nop 1
	v_add_f32_dpp v66, v66, v66 row_shr:4 row_mask:0xf bank_mask:0xf bound_ctrl:1
	s_nop 1
	v_add_f32_dpp v66, v66, v66 row_shr:8 row_mask:0xf bank_mask:0xf bound_ctrl:1
	s_nop 0
	v_readlane_b32 s9, v66, 15
	v_readlane_b32 s10, v66, 31
	v_readlane_b32 s11, v66, 47
	v_readlane_b32 vcc_lo, v66, 63
	s_nop 1
	v_mov_b32_e32 v66, s9
	v_add_f32_e32 v66, s10, v66
	v_add_f32_e32 v66, s11, v66
	v_add_f32_e32 v66, vcc_lo, v66
	v_mul_f32_e32 v66, 0x3a800000, v66
	v_add_f32_e32 v66, 0x3727c5ac, v66
	v_rsq_f32_e32 v118, v66
	s_nop 0
	v_mov_b32_e32 v119, v118
	v_pk_mul_f32 v[0:1], v[0:1], v[118:119]
	v_pk_mul_f32 v[2:3], v[2:3], v[118:119]
	v_pk_mul_f32 v[4:5], v[4:5], v[118:119]
	v_pk_mul_f32 v[6:7], v[6:7], v[118:119]
	v_pk_mul_f32 v[8:9], v[8:9], v[118:119]
	v_pk_mul_f32 v[10:11], v[10:11], v[118:119]
	v_pk_mul_f32 v[12:13], v[12:13], v[118:119]
	v_pk_mul_f32 v[14:15], v[14:15], v[118:119]
	v_pk_fma_f32 v[76:77], v[0:1], v[34:35], v[50:51]
	v_pk_fma_f32 v[78:79], v[2:3], v[36:37], v[52:53]
	v_pk_fma_f32 v[80:81], v[4:5], v[38:39], v[54:55]
	v_pk_fma_f32 v[82:83], v[6:7], v[40:41], v[56:57]
	v_pk_fma_f32 v[84:85], v[8:9], v[42:43], v[58:59]
	v_pk_fma_f32 v[86:87], v[10:11], v[44:45], v[60:61]
	v_pk_fma_f32 v[88:89], v[12:13], v[46:47], v[62:63]
	v_pk_fma_f32 v[90:91], v[14:15], v[48:49], v[64:65]
	v_cvt_pk_bf16_f32 v92, v76, v77
	v_cvt_pk_bf16_f32 v93, v78, v79
	v_cvt_pk_bf16_f32 v94, v80, v81
	v_cvt_pk_bf16_f32 v95, v82, v83
	v_cvt_pk_bf16_f32 v96, v84, v85
	v_cvt_pk_bf16_f32 v97, v86, v87
	v_cvt_pk_bf16_f32 v98, v88, v89
	v_cvt_pk_bf16_f32 v99, v90, v91
	global_store_dwordx2 v115, v[92:93], s[2:3] offset:0
	global_store_dwordx2 v115, v[94:95], s[2:3] offset:512
	global_store_dwordx2 v115, v[96:97], s[2:3] offset:1024
	global_store_dwordx2 v115, v[98:99], s[2:3] offset:1536
	s_add_u32 s2, s2, 0x80000
	s_addc_u32 s3, s3, 0
	s_add_u32 s0, s0, 0x100000
	s_addc_u32 s1, s1, 0
	global_load_dwordx4 v[0:3], v114, s[0:1] offset:0
	global_load_dwordx4 v[4:7], v114, s[0:1] offset:1024
	global_load_dwordx4 v[8:11], v114, s[0:1] offset:2048
	global_load_dwordx4 v[12:15], v114, s[0:1] offset:3072
	s_waitcnt vmcnt(8)
; __device__ __forceinline__ void phase_ln(float* R, const float* __restrict__ g, const float* __restrict__ b, bf16_t* xbf, float samp_scale, const float* __restrict__ part, int nsplit, bool f32_all) {
;     ...
;   for (int r = gw; r < MT; r += nw) {
;     float* row = R + (size_t)r * 1024;
;     f32x4 v[4];
; #pragma unroll
;     for (int i = 0; i < 4; ++i) v[i] = *(const f32x4*)(row + i * 256 + lane * 4);
;     if (r >= MP) {
;       for (int sp = 0; sp < nsplit; ++sp) {
;         const float* prow = part + ((size_t)sp * MS + (r - MP)) * 1024;
; #pragma unroll
;         for (int i = 0; i < 4; ++i) v[i] = v[i] + *(const f32x4*)(prow + i * 256 + lane * 4);
;       }
;     }
;     float s = 0.f;
; #pragma unroll
;     for (int i = 0; i < 4; ++i) s += v[i][0] + v[i][1] + v[i][2] + v[i][3];
; #pragma unroll
;     for (int o = 32; o >= 1; o >>= 1) s += __shfl_xor(s, o);
;     const float mean = s * (1.f / 1024.f);
;     float ss = 0.f;
; #pragma unroll
;     for (int i = 0; i < 4; ++i) { v[i] = v[i] - mean; ss += v[i][0] * v[i][0] + v[i][1] * v[i][1] + v[i][2] * v[i][2] + v[i][3] * v[i][3]; }
; #pragma unroll
;     for (int o = 32; o >= 1; o >>= 1) ss += __shfl_xor(ss, o);
;     const float rstd = rsqrtf(ss * (1.f / 1024.f) + LN_EPS);
; #pragma unroll
;     for (int i = 0; i < 4; ++i) {
;       const f32x4 y = v[i] * rstd * gv[i] + bv[i];
;       if (r >= MP) *(f32x4*)(row + i * 256 + lane * 4) = y * samp_scale;
;       else if (f32_all) *(f32x4*)(row + i * 256 + lane * 4) = y;
;       if (xbf) {
;         u32x2 wv;
;         wv[0] = cvt_pk_bf16(y[0], y[1]); wv[1] = cvt_pk_bf16(y[2], y[3]);
;         *(u32x2*)(xbf + (size_t)r * 1024 + i * 256 + lane * 4) = wv;
;       }
;     }
	v_pk_add_f32 v[66:67], v[18:19], v[20:21]
	v_pk_add_f32 v[68:69], v[22:23], v[24:25]
	v_pk_add_f32 v[70:71], v[26:27], v[28:29]
	v_pk_add_f32 v[72:73], v[30:31], v[32:33]
	v_pk_add_f32 v[66:67], v[66:67], v[68:69]
	v_pk_add_f32 v[70:71], v[70:71], v[72:73]
	v_pk_add_f32 v[66:67], v[66:67], v[70:71]
	v_add_f32_e32 v66, v66, v67
	s_nop 1
	v_add_f32_dpp v66, v66, v66 row_shr:1 row_mask:0xf bank_mask:0xf bound_ctrl:1
	s_nop 1
	v_add_f32_dpp v66, v66, v66 row_shr:2 row_mask:0xf bank_mask:0xf bound_ctrl:1
	s_nop 1
	v_add_f32_dpp v66, v66, v66 row_shr:4 row_mask:0xf bank_mask:0xf bound_ctrl:1
	s_nop 1
	v_add_f32_dpp v66, v66, v66 row_shr:8 row_mask:0xf bank_mask:0xf bound_ctrl:1
	s_nop 0
	v_readlane_b32 s9, v66, 15
	v_readlane_b32 s10, v66, 31
	v_readlane_b32 s11, v66, 47
	v_readlane_b32 vcc_lo, v66, 63
	s_nop 1
	v_mov_b32_e32 v66, s9
	v_add_f32_e32 v66, s10, v66
	v_add_f32_e32 v66, s11, v66
	v_add_f32_e32 v66, vcc_lo, v66
	v_mul_f32_e32 v116, 0x3a800000, v66
	v_mov_b32_e32 v117, v116
	v_pk_add_f32 v[18:19], v[18:19], v[116:117] neg_lo:[0,1] neg_hi:[0,1]
	v_pk_add_f32 v[20:21], v[20:21], v[116:117] neg_lo:[0,1] neg_hi:[0,1]
	v_pk_add_f32 v[22:23], v[22:23], v[116:117] neg_lo:[0,1] neg_hi:[0,1]
	v_pk_add_f32 v[24:25], v[24:25], v[116:117] neg_lo:[0,1] neg_hi:[0,1]
	v_pk_add_f32 v[26:27], v[26:27], v[116:117] neg_lo:[0,1] neg_hi:[0,1]
	v_pk_add_f32 v[28:29], v[28:29], v[116:117] neg_lo:[0,1] neg_hi:[0,1]
	v_pk_add_f32 v[30:31], v[30:31], v[116:117] neg_lo:[0,1] neg_hi:[0,1]
	v_pk_add_f32 v[32:33], v[32:33], v[116:117] neg_lo:[0,1] neg_hi:[0,1]
	v_pk_mul_f32 v[66:67], v[18:19], v[18:19]
	v_pk_mul_f32 v[68:69], v[20:21], v[20:21]
	v_pk_fma_f32 v[66:67], v[22:23], v[22:23], v[66:67]
	v_pk_fma_f32 v[68:69], v[24:25], v[24:25], v[68:69]
	v_pk_fma_f32 v[66:67], v[26:27], v[26:27], v[66:67]
	v_pk_fma_f32 v[68:69], v[28:29], v[28:29], v[68:69]
	v_pk_fma_f32 v[66:67], v[30:31], v[30:31], v[66:67]
	v_pk_fma_f32 v[68:69], v[32:33], v[32:33], v[68:69]
	v_pk_add_f32 v[66:67], v[66:67], v[68:69]
	v_add_f32_e32 v66, v66, v67
	s_nop 1
	v_add_f32_dpp v66, v66, v66 row_shr:1 row_mask:0xf bank_mask:0xf bound_ctrl:1
	s_nop 1
	v_add_f32_dpp v66, v66, v66 row_shr:2 row_mask:0xf bank_mask:0xf bound_ctrl:1
	s_nop 1
	v_add_f32_dpp v66, v66, v66 row_shr:4 row_mask:0xf bank_mask:0xf bound_ctrl:1
	s_nop 1
	v_add_f32_dpp v66, v66, v66 row_shr:8 row_mask:0xf bank_mask:0xf bound_ctrl:1
	s_nop 0
	v_readlane_b32 s9, v66, 15
	v_readlane_b32 s10, v66, 31
	v_readlane_b32 s11, v66, 47
	v_readlane_b32 vcc_lo, v66, 63
	s_nop 1
	v_mov_b32_e32 v66, s9
	v_add_f32_e32 v66, s10, v66
	v_add_f32_e32 v66, s11, v66
	v_add_f32_e32 v66, vcc_lo, v66
	v_mul_f32_e32 v66, 0x3a800000, v66
	v_add_f32_e32 v66, 0x3727c5ac, v66
	v_rsq_f32_e32 v118, v66
	s_nop 0
	v_mov_b32_e32 v119, v118
	v_pk_mul_f32 v[18:19], v[18:19], v[118:119]
	v_pk_mul_f32 v[20:21], v[20:21], v[118:119]
	v_pk_mul_f32 v[22:23], v[22:23], v[118:119]
	v_pk_mul_f32 v[24:25], v[24:25], v[118:119]
	v_pk_mul_f32 v[26:27], v[26:27], v[118:119]
	v_pk_mul_f32 v[28:29], v[28:29], v[118:119]
	v_pk_mul_f32 v[30:31], v[30:31], v[118:119]
	v_pk_mul_f32 v[32:33], v[32:33], v[118:119]
	v_pk_fma_f32 v[76:77], v[18:19], v[34:35], v[50:51]
	v_pk_fma_f32 v[78:79], v[20:21], v[36:37], v[52:53]
	v_pk_fma_f32 v[80:81], v[22:23], v[38:39], v[54:55]
	v_pk_fma_f32 v[82:83], v[24:25], v[40:41], v[56:57]
	v_pk_fma_f32 v[84:85], v[26:27], v[42:43], v[58:59]
	v_pk_fma_f32 v[86:87], v[28:29], v[44:45], v[60:61]
	v_pk_fma_f32 v[88:89], v[30:31], v[46:47], v[62:63]
	v_pk_fma_f32 v[90:91], v[32:33], v[48:49], v[64:65]
	v_cvt_pk_bf16_f32 v92, v76, v77
	v_cvt_pk_bf16_f32 v93, v78, v79
	v_cvt_pk_bf16_f32 v94, v80, v81
	v_cvt_pk_bf16_f32 v95, v82, v83
	v_cvt_pk_bf16_f32 v96, v84, v85
	v_cvt_pk_bf16_f32 v97, v86, v87
	v_cvt_pk_bf16_f32 v98, v88, v89
	v_cvt_pk_bf16_f32 v99, v90, v91
	global_store_dwordx2 v115, v[92:93], s[2:3] offset:0
	global_store_dwordx2 v115, v[94:95], s[2:3] offset:512
	global_store_dwordx2 v115, v[96:97], s[2:3] offset:1024
	global_store_dwordx2 v115, v[98:99], s[2:3] offset:1536
	s_add_u32 s2, s2, 0x80000
	s_addc_u32 s3, s3, 0
	s_add_u32 s0, s0, 0x100000
	s_addc_u32 s1, s1, 0
	global_load_dwordx4 v[18:21], v114, s[0:1] offset:0
	global_load_dwordx4 v[22:25], v114, s[0:1] offset:1024
	global_load_dwordx4 v[26:29], v114, s[0:1] offset:2048
	global_load_dwordx4 v[30:33], v114, s[0:1] offset:3072
	s_waitcnt vmcnt(8)
; __device__ __forceinline__ void phase_ln(float* R, const float* __restrict__ g, const float* __restrict__ b, bf16_t* xbf, float samp_scale, const float* __restrict__ part, int nsplit, bool f32_all) {
;     ...
;   for (int r = gw; r < MT; r += nw) {
;     float* row = R + (size_t)r * 1024;
;     f32x4 v[4];
; #pragma unroll
;     for (int i = 0; i < 4; ++i) v[i] = *(const f32x4*)(row + i * 256 + lane * 4);
;     if (r >= MP) {
;       for (int sp = 0; sp < nsplit; ++sp) {
;         const float* prow = part + ((size_t)sp * MS + (r - MP)) * 1024;
; #pragma unroll
;         for (int i = 0; i < 4; ++i) v[i] = v[i] + *(const f32x4*)(prow + i * 256 + lane * 4);
;       }
;     }
;     float s = 0.f;
; #pragma unroll
;     for (int i = 0; i < 4; ++i) s += v[i][0] + v[i][1] + v[i][2] + v[i][3];
; #pragma unroll
;     for (int o = 32; o >= 1; o >>= 1) s += __shfl_xor(s, o);
;     const float mean = s * (1.f / 1024.f);
;     float ss = 0.f;
; #pragma unroll
;     for (int i = 0; i < 4; ++i) { v[i] = v[i] - mean; ss += v[i][0] * v[i][0] + v[i][1] * v[i][1] + v[i][2] * v[i][2] + v[i][3] * v[i][3]; }
; #pragma unroll
;     for (int o = 32; o >= 1; o >>= 1) ss += __shfl_xor(ss, o);
;     const float rstd = rsqrtf(ss * (1.f / 1024.f) + LN_EPS);
; #pragma unroll
;     for (int i = 0; i < 4; ++i) {
;       const f32x4 y = v[i] * rstd * gv[i] + bv[i];
;       if (r >= MP) *(f32x4*)(row + i * 256 + lane * 4) = y * samp_scale;
;       else if (f32_all) *(f32x4*)(row + i * 256 + lane * 4) = y;
;       if (xbf) {
;         u32x2 wv;
;         wv[0] = cvt_pk_bf16(y[0], y[1]); wv[1] = cvt_pk_bf16(y[2], y[3]);
;         *(u32x2*)(xbf + (size_t)r * 1024 + i * 256 + lane * 4) = wv;
;       }
;     }
	v_pk_add_f32 v[66:67], v[0:1], v[2:3]
	v_pk_add_f32 v[68:69], v[4:5], v[6:7]
	v_pk_add_f32 v[70:71], v[8:9], v[10:11]
	v_pk_add_f32 v[72:73], v[12:13], v[14:15]
	v_pk_add_f32 v[66:67], v[66:67], v[68:69]
	v_pk_add_f32 v[70:71], v[70:71], v[72:73]
	v_pk_add_f32 v[66:67], v[66:67], v[70:71]
	v_add_f32_e32 v66, v66, v67
	s_nop 1
	v_add_f32_dpp v66, v66, v66 row_shr:1 row_mask:0xf bank_mask:0xf bound_ctrl:1
	s_nop 1
	v_add_f32_dpp v66, v66, v66 row_shr:2 row_mask:0xf bank_mask:0xf bound_ctrl:1
	s_nop 1
	v_add_f32_dpp v66, v66, v66 row_shr:4 row_mask:0xf bank_mask:0xf bound_ctrl:1
	s_nop 1
	v_add_f32_dpp v66, v66, v66 row_shr:8 row_mask:0xf bank_mask:0xf bound_ctrl:1
	s_nop 0
	v_readlane_b32 s9, v66, 15
	v_readlane_b32 s10, v66, 31
	v_readlane_b32 s11, v66, 47
	v_readlane_b32 vcc_lo, v66, 63
	s_nop 1
	v_mov_b32_e32 v66, s9
	v_add_f32_e32 v66, s10, v66
	v_add_f32_e32 v66, s11, v66
	v_add_f32_e32 v66, vcc_lo, v66
	v_mul_f32_e32 v116, 0x3a800000, v66
	v_mov_b32_e32 v117, v116
	v_pk_add_f32 v[0:1], v[0:1], v[116:117] neg_lo:[0,1] neg_hi:[0,1]
	v_pk_add_f32 v[2:3], v[2:3], v[116:117] neg_lo:[0,1] neg_hi:[0,1]
	v_pk_add_f32 v[4:5], v[4:5], v[116:117] neg_lo:[0,1] neg_hi:[0,1]
	v_pk_add_f32 v[6:7], v[6:7], v[116:117] neg_lo:[0,1] neg_hi:[0,1]
	v_pk_add_f32 v[8:9], v[8:9], v[116:117] neg_lo:[0,1] neg_hi:[0,1]
	v_pk_add_f32 v[10:11], v[10:11], v[116:117] neg_lo:[0,1] neg_hi:[0,1]
	v_pk_add_f32 v[12:13], v[12:13], v[116:117] neg_lo:[0,1] neg_hi:[0,1]
	v_pk_add_f32 v[14:15], v[14:15], v[116:117] neg_lo:[0,1] neg_hi:[0,1]
	v_pk_mul_f32 v[66:67], v[0:1], v[0:1]
	v_pk_mul_f32 v[68:69], v[2:3], v[2:3]
	v_pk_fma_f32 v[66:67], v[4:5], v[4:5], v[66:67]
	v_pk_fma_f32 v[68:69], v[6:7], v[6:7], v[68:69]
	v_pk_fma_f32 v[66:67], v[8:9], v[8:9], v[66:67]
	v_pk_fma_f32 v[68:69], v[10:11], v[10:11], v[68:69]
	v_pk_fma_f32 v[66:67], v[12:13], v[12:13], v[66:67]
	v_pk_fma_f32 v[68:69], v[14:15], v[14:15], v[68:69]
	v_pk_add_f32 v[66:67], v[66:67], v[68:69]
	v_add_f32_e32 v66, v66, v67
	s_nop 1
	v_add_f32_dpp v66, v66, v66 row_shr:1 row_mask:0xf bank_mask:0xf bound_ctrl:1
	s_nop 1
	v_add_f32_dpp v66, v66, v66 row_shr:2 row_mask:0xf bank_mask:0xf bound_ctrl:1
	s_nop 1
	v_add_f32_dpp v66, v66, v66 row_shr:4 row_mask:0xf bank_mask:0xf bound_ctrl:1
	s_nop 1
	v_add_f32_dpp v66, v66, v66 row_shr:8 row_mask:0xf bank_mask:0xf bound_ctrl:1
	s_nop 0
	v_readlane_b32 s9, v66, 15
	v_readlane_b32 s10, v66, 31
	v_readlane_b32 s11, v66, 47
	v_readlane_b32 vcc_lo, v66, 63
	s_nop 1
	v_mov_b32_e32 v66, s9
	v_add_f32_e32 v66, s10, v66
	v_add_f32_e32 v66, s11, v66
	v_add_f32_e32 v66, vcc_lo, v66
	v_mul_f32_e32 v66, 0x3a800000, v66
	v_add_f32_e32 v66, 0x3727c5ac, v66
	v_rsq_f32_e32 v118, v66
	s_nop 0
	v_mov_b32_e32 v119, v118
	v_pk_mul_f32 v[0:1], v[0:1], v[118:119]
	v_pk_mul_f32 v[2:3], v[2:3], v[118:119]
	v_pk_mul_f32 v[4:5], v[4:5], v[118:119]
	v_pk_mul_f32 v[6:7], v[6:7], v[118:119]
	v_pk_mul_f32 v[8:9], v[8:9], v[118:119]
	v_pk_mul_f32 v[10:11], v[10:11], v[118:119]
	v_pk_mul_f32 v[12:13], v[12:13], v[118:119]
	v_pk_mul_f32 v[14:15], v[14:15], v[118:119]
	v_pk_fma_f32 v[76:77], v[0:1], v[34:35], v[50:51]
	v_pk_fma_f32 v[78:79], v[2:3], v[36:37], v[52:53]
	v_pk_fma_f32 v[80:81], v[4:5], v[38:39], v[54:55]
	v_pk_fma_f32 v[82:83], v[6:7], v[40:41], v[56:57]
	v_pk_fma_f32 v[84:85], v[8:9], v[42:43], v[58:59]
	v_pk_fma_f32 v[86:87], v[10:11], v[44:45], v[60:61]
	v_pk_fma_f32 v[88:89], v[12:13], v[46:47], v[62:63]
	v_pk_fma_f32 v[90:91], v[14:15], v[48:49], v[64:65]
	v_cvt_pk_bf16_f32 v92, v76, v77
	v_cvt_pk_bf16_f32 v93, v78, v79
	v_cvt_pk_bf16_f32 v94, v80, v81
	v_cvt_pk_bf16_f32 v95, v82, v83
	v_cvt_pk_bf16_f32 v96, v84, v85
	v_cvt_pk_bf16_f32 v97, v86, v87
	v_cvt_pk_bf16_f32 v98, v88, v89
	v_cvt_pk_bf16_f32 v99, v90, v91
	global_store_dwordx2 v115, v[92:93], s[2:3] offset:0
	global_store_dwordx2 v115, v[94:95], s[2:3] offset:512
	global_store_dwordx2 v115, v[96:97], s[2:3] offset:1024
	global_store_dwordx2 v115, v[98:99], s[2:3] offset:1536
	s_add_u32 s2, s2, 0x80000
	s_addc_u32 s3, s3, 0
	s_add_u32 s0, s0, 0x100000
	s_addc_u32 s1, s1, 0
	global_load_dwordx4 v[0:3], v114, s[0:1] offset:0
	global_load_dwordx4 v[4:7], v114, s[0:1] offset:1024
	global_load_dwordx4 v[8:11], v114, s[0:1] offset:2048
	global_load_dwordx4 v[12:15], v114, s[0:1] offset:3072
	s_waitcnt vmcnt(8)
; __device__ __forceinline__ void phase_ln(float* R, const float* __restrict__ g, const float* __restrict__ b, bf16_t* xbf, float samp_scale, const float* __restrict__ part, int nsplit, bool f32_all) {
;     ...
;   for (int r = gw; r < MT; r += nw) {
;     float* row = R + (size_t)r * 1024;
;     f32x4 v[4];
; #pragma unroll
;     for (int i = 0; i < 4; ++i) v[i] = *(const f32x4*)(row + i * 256 + lane * 4);
;     if (r >= MP) {
;       for (int sp = 0; sp < nsplit; ++sp) {
;         const float* prow = part + ((size_t)sp * MS + (r - MP)) * 1024;
; #pragma unroll
;         for (int i = 0; i < 4; ++i) v[i] = v[i] + *(const f32x4*)(prow + i * 256 + lane * 4);
;       }
;     }
;     float s = 0.f;
; #pragma unroll
;     for (int i = 0; i < 4; ++i) s += v[i][0] + v[i][1] + v[i][2] + v[i][3];
; #pragma unroll
;     for (int o = 32; o >= 1; o >>= 1) s += __shfl_xor(s, o);
;     const float mean = s * (1.f / 1024.f);
;     float ss = 0.f;
; #pragma unroll
;     for (int i = 0; i < 4; ++i) { v[i] = v[i] - mean; ss += v[i][0] * v[i][0] + v[i][1] * v[i][1] + v[i][2] * v[i][2] + v[i][3] * v[i][3]; }
; #pragma unroll
;     for (int o = 32; o >= 1; o >>= 1) ss += __shfl_xor(ss, o);
;     const float rstd = rsqrtf(ss * (1.f / 1024.f) + LN_EPS);
; #pragma unroll
;     for (int i = 0; i < 4; ++i) {
;       const f32x4 y = v[i] * rstd * gv[i] + bv[i];
;       if (r >= MP) *(f32x4*)(row + i * 256 + lane * 4) = y * samp_scale;
;       else if (f32_all) *(f32x4*)(row + i * 256 + lane * 4) = y;
;       if (xbf) {
;         u32x2 wv;
;         wv[0] = cvt_pk_bf16(y[0], y[1]); wv[1] = cvt_pk_bf16(y[2], y[3]);
;         *(u32x2*)(xbf + (size_t)r * 1024 + i * 256 + lane * 4) = wv;
;       }
;     }
	v_pk_add_f32 v[66:67], v[18:19], v[20:21]
	v_pk_add_f32 v[68:69], v[22:23], v[24:25]
	v_pk_add_f32 v[70:71], v[26:27], v[28:29]
	v_pk_add_f32 v[72:73], v[30:31], v[32:33]
	v_pk_add_f32 v[66:67], v[66:67], v[68:69]
	v_pk_add_f32 v[70:71], v[70:71], v[72:73]
	v_pk_add_f32 v[66:67], v[66:67], v[70:71]
	v_add_f32_e32 v66, v66, v67
	s_nop 1
	v_add_f32_dpp v66, v66, v66 row_shr:1 row_mask:0xf bank_mask:0xf bound_ctrl:1
	s_nop 1
	v_add_f32_dpp v66, v66, v66 row_shr:2 row_mask:0xf bank_mask:0xf bound_ctrl:1
	s_nop 1
	v_add_f32_dpp v66, v66, v66 row_shr:4 row_mask:0xf bank_mask:0xf bound_ctrl:1
	s_nop 1
	v_add_f32_dpp v66, v66, v66 row_shr:8 row_mask:0xf bank_mask:0xf bound_ctrl:1
	s_nop 0
	v_readlane_b32 s9, v66, 15
	v_readlane_b32 s10, v66, 31
	v_readlane_b32 s11, v66, 47
	v_readlane_b32 vcc_lo, v66, 63
	s_nop 1
	v_mov_b32_e32 v66, s9
	v_add_f32_e32 v66, s10, v66
	v_add_f32_e32 v66, s11, v66
	v_add_f32_e32 v66, vcc_lo, v66
	v_mul_f32_e32 v116, 0x3a800000, v66
	v_mov_b32_e32 v117, v116
	v_pk_add_f32 v[18:19], v[18:19], v[116:117] neg_lo:[0,1] neg_hi:[0,1]
	v_pk_add_f32 v[20:21], v[20:21], v[116:117] neg_lo:[0,1] neg_hi:[0,1]
	v_pk_add_f32 v[22:23], v[22:23], v[116:117] neg_lo:[0,1] neg_hi:[0,1]
	v_pk_add_f32 v[24:25], v[24:25], v[116:117] neg_lo:[0,1] neg_hi:[0,1]
	v_pk_add_f32 v[26:27], v[26:27], v[116:117] neg_lo:[0,1] neg_hi:[0,1]
	v_pk_add_f32 v[28:29], v[28:29], v[116:117] neg_lo:[0,1] neg_hi:[0,1]
	v_pk_add_f32 v[30:31], v[30:31], v[116:117] neg_lo:[0,1] neg_hi:[0,1]
	v_pk_add_f32 v[32:33], v[32:33], v[116:117] neg_lo:[0,1] neg_hi:[0,1]
	v_pk_mul_f32 v[66:67], v[18:19], v[18:19]
	v_pk_mul_f32 v[68:69], v[20:21], v[20:21]
	v_pk_fma_f32 v[66:67], v[22:23], v[22:23], v[66:67]
	v_pk_fma_f32 v[68:69], v[24:25], v[24:25], v[68:69]
	v_pk_fma_f32 v[66:67], v[26:27], v[26:27], v[66:67]
	v_pk_fma_f32 v[68:69], v[28:29], v[28:29], v[68:69]
	v_pk_fma_f32 v[66:67], v[30:31], v[30:31], v[66:67]
	v_pk_fma_f32 v[68:69], v[32:33], v[32:33], v[68:69]
	v_pk_add_f32 v[66:67], v[66:67], v[68:69]
	v_add_f32_e32 v66, v66, v67
	s_nop 1
	v_add_f32_dpp v66, v66, v66 row_shr:1 row_mask:0xf bank_mask:0xf bound_ctrl:1
	s_nop 1
	v_add_f32_dpp v66, v66, v66 row_shr:2 row_mask:0xf bank_mask:0xf bound_ctrl:1
	s_nop 1
	v_add_f32_dpp v66, v66, v66 row_shr:4 row_mask:0xf bank_mask:0xf bound_ctrl:1
	s_nop 1
	v_add_f32_dpp v66, v66, v66 row_shr:8 row_mask:0xf bank_mask:0xf bound_ctrl:1
	s_nop 0
	v_readlane_b32 s9, v66, 15
	v_readlane_b32 s10, v66, 31
	v_readlane_b32 s11, v66, 47
	v_readlane_b32 vcc_lo, v66, 63
	s_nop 1
	v_mov_b32_e32 v66, s9
	v_add_f32_e32 v66, s10, v66
	v_add_f32_e32 v66, s11, v66
	v_add_f32_e32 v66, vcc_lo, v66
	v_mul_f32_e32 v66, 0x3a800000, v66
	v_add_f32_e32 v66, 0x3727c5ac, v66
	v_rsq_f32_e32 v118, v66
	s_nop 0
	v_mov_b32_e32 v119, v118
	v_pk_mul_f32 v[18:19], v[18:19], v[118:119]
	v_pk_mul_f32 v[20:21], v[20:21], v[118:119]
	v_pk_mul_f32 v[22:23], v[22:23], v[118:119]
	v_pk_mul_f32 v[24:25], v[24:25], v[118:119]
	v_pk_mul_f32 v[26:27], v[26:27], v[118:119]
	v_pk_mul_f32 v[28:29], v[28:29], v[118:119]
	v_pk_mul_f32 v[30:31], v[30:31], v[118:119]
	v_pk_mul_f32 v[32:33], v[32:33], v[118:119]
	v_pk_fma_f32 v[76:77], v[18:19], v[34:35], v[50:51]
	v_pk_fma_f32 v[78:79], v[20:21], v[36:37], v[52:53]
	v_pk_fma_f32 v[80:81], v[22:23], v[38:39], v[54:55]
	v_pk_fma_f32 v[82:83], v[24:25], v[40:41], v[56:57]
	v_pk_fma_f32 v[84:85], v[26:27], v[42:43], v[58:59]
	v_pk_fma_f32 v[86:87], v[28:29], v[44:45], v[60:61]
	v_pk_fma_f32 v[88:89], v[30:31], v[46:47], v[62:63]
	v_pk_fma_f32 v[90:91], v[32:33], v[48:49], v[64:65]
	v_cvt_pk_bf16_f32 v92, v76, v77
	v_cvt_pk_bf16_f32 v93, v78, v79
	v_cvt_pk_bf16_f32 v94, v80, v81
	v_cvt_pk_bf16_f32 v95, v82, v83
	v_cvt_pk_bf16_f32 v96, v84, v85
	v_cvt_pk_bf16_f32 v97, v86, v87
	v_cvt_pk_bf16_f32 v98, v88, v89
	v_cvt_pk_bf16_f32 v99, v90, v91
	global_store_dwordx2 v115, v[92:93], s[2:3] offset:0
	global_store_dwordx2 v115, v[94:95], s[2:3] offset:512
	global_store_dwordx2 v115, v[96:97], s[2:3] offset:1024
	global_store_dwordx2 v115, v[98:99], s[2:3] offset:1536
	s_add_u32 s2, s2, 0x80000
	s_addc_u32 s3, s3, 0
	s_add_u32 s0, s0, 0x100000
	s_addc_u32 s1, s1, 0
	global_load_dwordx4 v[18:21], v114, s[0:1] offset:0
	global_load_dwordx4 v[22:25], v114, s[0:1] offset:1024
	global_load_dwordx4 v[26:29], v114, s[0:1] offset:2048
	global_load_dwordx4 v[30:33], v114, s[0:1] offset:3072
	s_waitcnt vmcnt(8)
; __device__ __forceinline__ void phase_ln(float* R, const float* __restrict__ g, const float* __restrict__ b, bf16_t* xbf, float samp_scale, const float* __restrict__ part, int nsplit, bool f32_all) {
;     ...
;   for (int r = gw; r < MT; r += nw) {
;     float* row = R + (size_t)r * 1024;
;     f32x4 v[4];
; #pragma unroll
;     for (int i = 0; i < 4; ++i) v[i] = *(const f32x4*)(row + i * 256 + lane * 4);
;     if (r >= MP) {
;       for (int sp = 0; sp < nsplit; ++sp) {
;         const float* prow = part + ((size_t)sp * MS + (r - MP)) * 1024;
; #pragma unroll
;         for (int i = 0; i < 4; ++i) v[i] = v[i] + *(const f32x4*)(prow + i * 256 + lane * 4);
;       }
;     }
;     float s = 0.f;
; #pragma unroll
;     for (int i = 0; i < 4; ++i) s += v[i][0] + v[i][1] + v[i][2] + v[i][3];
; #pragma unroll
;     for (int o = 32; o >= 1; o >>= 1) s += __shfl_xor(s, o);
;     const float mean = s * (1.f / 1024.f);
;     float ss = 0.f;
; #pragma unroll
;     for (int i = 0; i < 4; ++i) { v[i] = v[i] - mean; ss += v[i][0] * v[i][0] + v[i][1] * v[i][1] + v[i][2] * v[i][2] + v[i][3] * v[i][3]; }
; #pragma unroll
;     for (int o = 32; o >= 1; o >>= 1) ss += __shfl_xor(ss, o);
;     const float rstd = rsqrtf(ss * (1.f / 1024.f) + LN_EPS);
; #pragma unroll
;     for (int i = 0; i < 4; ++i) {
;       const f32x4 y = v[i] * rstd * gv[i] + bv[i];
;       if (r >= MP) *(f32x4*)(row + i * 256 + lane * 4) = y * samp_scale;
;       else if (f32_all) *(f32x4*)(row + i * 256 + lane * 4) = y;
;       if (xbf) {
;         u32x2 wv;
;         wv[0] = cvt_pk_bf16(y[0], y[1]); wv[1] = cvt_pk_bf16(y[2], y[3]);
;         *(u32x2*)(xbf + (size_t)r * 1024 + i * 256 + lane * 4) = wv;
;       }
;     }
	v_pk_add_f32 v[66:67], v[0:1], v[2:3]
	v_pk_add_f32 v[68:69], v[4:5], v[6:7]
	v_pk_add_f32 v[70:71], v[8:9], v[10:11]
	v_pk_add_f32 v[72:73], v[12:13], v[14:15]
	v_pk_add_f32 v[66:67], v[66:67], v[68:69]
	v_pk_add_f32 v[70:71], v[70:71], v[72:73]
	v_pk_add_f32 v[66:67], v[66:67], v[70:71]
	v_add_f32_e32 v66, v66, v67
	s_nop 1
	v_add_f32_dpp v66, v66, v66 row_shr:1 row_mask:0xf bank_mask:0xf bound_ctrl:1
	s_nop 1
	v_add_f32_dpp v66, v66, v66 row_shr:2 row_mask:0xf bank_mask:0xf bound_ctrl:1
	s_nop 1
	v_add_f32_dpp v66, v66, v66 row_shr:4 row_mask:0xf bank_mask:0xf bound_ctrl:1
	s_nop 1
	v_add_f32_dpp v66, v66, v66 row_shr:8 row_mask:0xf bank_mask:0xf bound_ctrl:1
	s_nop 0
	v_readlane_b32 s9, v66, 15
	v_readlane_b32 s10, v66, 31
	v_readlane_b32 s11, v66, 47
	v_readlane_b32 vcc_lo, v66, 63
	s_nop 1
	v_mov_b32_e32 v66, s9
	v_add_f32_e32 v66, s10, v66
	v_add_f32_e32 v66, s11, v66
	v_add_f32_e32 v66, vcc_lo, v66
	v_mul_f32_e32 v116, 0x3a800000, v66
	v_mov_b32_e32 v117, v116
	v_pk_add_f32 v[0:1], v[0:1], v[116:117] neg_lo:[0,1] neg_hi:[0,1]
	v_pk_add_f32 v[2:3], v[2:3], v[116:117] neg_lo:[0,1] neg_hi:[0,1]
	v_pk_add_f32 v[4:5], v[4:5], v[116:117] neg_lo:[0,1] neg_hi:[0,1]
	v_pk_add_f32 v[6:7], v[6:7], v[116:117] neg_lo:[0,1] neg_hi:[0,1]
	v_pk_add_f32 v[8:9], v[8:9], v[116:117] neg_lo:[0,1] neg_hi:[0,1]
	v_pk_add_f32 v[10:11], v[10:11], v[116:117] neg_lo:[0,1] neg_hi:[0,1]
	v_pk_add_f32 v[12:13], v[12:13], v[116:117] neg_lo:[0,1] neg_hi:[0,1]
	v_pk_add_f32 v[14:15], v[14:15], v[116:117] neg_lo:[0,1] neg_hi:[0,1]
	v_pk_mul_f32 v[66:67], v[0:1], v[0:1]
	v_pk_mul_f32 v[68:69], v[2:3], v[2:3]
	v_pk_fma_f32 v[66:67], v[4:5], v[4:5], v[66:67]
	v_pk_fma_f32 v[68:69], v[6:7], v[6:7], v[68:69]
	v_pk_fma_f32 v[66:67], v[8:9], v[8:9], v[66:67]
	v_pk_fma_f32 v[68:69], v[10:11], v[10:11], v[68:69]
	v_pk_fma_f32 v[66:67], v[12:13], v[12:13], v[66:67]
	v_pk_fma_f32 v[68:69], v[14:15], v[14:15], v[68:69]
	v_pk_add_f32 v[66:67], v[66:67], v[68:69]
	v_add_f32_e32 v66, v66, v67
	s_nop 1
	v_add_f32_dpp v66, v66, v66 row_shr:1 row_mask:0xf bank_mask:0xf bound_ctrl:1
	s_nop 1
	v_add_f32_dpp v66, v66, v66 row_shr:2 row_mask:0xf bank_mask:0xf bound_ctrl:1
	s_nop 1
	v_add_f32_dpp v66, v66, v66 row_shr:4 row_mask:0xf bank_mask:0xf bound_ctrl:1
	s_nop 1
	v_add_f32_dpp v66, v66, v66 row_shr:8 row_mask:0xf bank_mask:0xf bound_ctrl:1
	s_nop 0
	v_readlane_b32 s9, v66, 15
	v_readlane_b32 s10, v66, 31
	v_readlane_b32 s11, v66, 47
	v_readlane_b32 vcc_lo, v66, 63
	s_nop 1
	v_mov_b32_e32 v66, s9
	v_add_f32_e32 v66, s10, v66
	v_add_f32_e32 v66, s11, v66
	v_add_f32_e32 v66, vcc_lo, v66
	v_mul_f32_e32 v66, 0x3a800000, v66
	v_add_f32_e32 v66, 0x3727c5ac, v66
	v_rsq_f32_e32 v118, v66
	s_nop 0
	v_mov_b32_e32 v119, v118
	v_pk_mul_f32 v[0:1], v[0:1], v[118:119]
	v_pk_mul_f32 v[2:3], v[2:3], v[118:119]
	v_pk_mul_f32 v[4:5], v[4:5], v[118:119]
	v_pk_mul_f32 v[6:7], v[6:7], v[118:119]
	v_pk_mul_f32 v[8:9], v[8:9], v[118:119]
	v_pk_mul_f32 v[10:11], v[10:11], v[118:119]
	v_pk_mul_f32 v[12:13], v[12:13], v[118:119]
	v_pk_mul_f32 v[14:15], v[14:15], v[118:119]
	v_pk_fma_f32 v[76:77], v[0:1], v[34:35], v[50:51]
	v_pk_fma_f32 v[78:79], v[2:3], v[36:37], v[52:53]
	v_pk_fma_f32 v[80:81], v[4:5], v[38:39], v[54:55]
	v_pk_fma_f32 v[82:83], v[6:7], v[40:41], v[56:57]
	v_pk_fma_f32 v[84:85], v[8:9], v[42:43], v[58:59]
	v_pk_fma_f32 v[86:87], v[10:11], v[44:45], v[60:61]
	v_pk_fma_f32 v[88:89], v[12:13], v[46:47], v[62:63]
	v_pk_fma_f32 v[90:91], v[14:15], v[48:49], v[64:65]
	v_cvt_pk_bf16_f32 v92, v76, v77
	v_cvt_pk_bf16_f32 v93, v78, v79
	v_cvt_pk_bf16_f32 v94, v80, v81
	v_cvt_pk_bf16_f32 v95, v82, v83
	v_cvt_pk_bf16_f32 v96, v84, v85
	v_cvt_pk_bf16_f32 v97, v86, v87
	v_cvt_pk_bf16_f32 v98, v88, v89
	v_cvt_pk_bf16_f32 v99, v90, v91
	global_store_dwordx2 v115, v[92:93], s[2:3] offset:0
	global_store_dwordx2 v115, v[94:95], s[2:3] offset:512
	global_store_dwordx2 v115, v[96:97], s[2:3] offset:1024
	global_store_dwordx2 v115, v[98:99], s[2:3] offset:1536
	s_add_u32 s2, s2, 0x80000
	s_addc_u32 s3, s3, 0
	s_add_u32 s0, s0, 0x100000
	s_addc_u32 s1, s1, 0
	global_load_dwordx4 v[0:3], v114, s[0:1] offset:0
	global_load_dwordx4 v[4:7], v114, s[0:1] offset:1024
	global_load_dwordx4 v[8:11], v114, s[0:1] offset:2048
	global_load_dwordx4 v[12:15], v114, s[0:1] offset:3072
	s_waitcnt vmcnt(8)
; __device__ __forceinline__ void phase_ln(float* R, const float* __restrict__ g, const float* __restrict__ b, bf16_t* xbf, float samp_scale, const float* __restrict__ part, int nsplit, bool f32_all) {
;     ...
;   for (int r = gw; r < MT; r += nw) {
;     float* row = R + (size_t)r * 1024;
;     f32x4 v[4];
; #pragma unroll
;     for (int i = 0; i < 4; ++i) v[i] = *(const f32x4*)(row + i * 256 + lane * 4);
;     if (r >= MP) {
;       for (int sp = 0; sp < nsplit; ++sp) {
;         const float* prow = part + ((size_t)sp * MS + (r - MP)) * 1024;
; #pragma unroll
;         for (int i = 0; i < 4; ++i) v[i] = v[i] + *(const f32x4*)(prow + i * 256 + lane * 4);
;       }
;     }
;     float s = 0.f;
; #pragma unroll
;     for (int i = 0; i < 4; ++i) s += v[i][0] + v[i][1] + v[i][2] + v[i][3];
; #pragma unroll
;     for (int o = 32; o >= 1; o >>= 1) s += __shfl_xor(s, o);
;     const float mean = s * (1.f / 1024.f);
;     float ss = 0.f;
; #pragma unroll
;     for (int i = 0; i < 4; ++i) { v[i] = v[i] - mean; ss += v[i][0] * v[i][0] + v[i][1] * v[i][1] + v[i][2] * v[i][2] + v[i][3] * v[i][3]; }
; #pragma unroll
;     for (int o = 32; o >= 1; o >>= 1) ss += __shfl_xor(ss, o);
;     const float rstd = rsqrtf(ss * (1.f / 1024.f) + LN_EPS);
; #pragma unroll
;     for (int i = 0; i < 4; ++i) {
;       const f32x4 y = v[i] * rstd * gv[i] + bv[i];
;       if (r >= MP) *(f32x4*)(row + i * 256 + lane * 4) = y * samp_scale;
;       else if (f32_all) *(f32x4*)(row + i * 256 + lane * 4) = y;
;       if (xbf) {
;         u32x2 wv;
;         wv[0] = cvt_pk_bf16(y[0], y[1]); wv[1] = cvt_pk_bf16(y[2], y[3]);
;         *(u32x2*)(xbf + (size_t)r * 1024 + i * 256 + lane * 4) = wv;
;       }
;     }
	v_pk_add_f32 v[66:67], v[18:19], v[20:21]
	v_pk_add_f32 v[68:69], v[22:23], v[24:25]
	v_pk_add_f32 v[70:71], v[26:27], v[28:29]
	v_pk_add_f32 v[72:73], v[30:31], v[32:33]
	v_pk_add_f32 v[66:67], v[66:67], v[68:69]
	v_pk_add_f32 v[70:71], v[70:71], v[72:73]
	v_pk_add_f32 v[66:67], v[66:67], v[70:71]
	v_add_f32_e32 v66, v66, v67
	s_nop 1
	v_add_f32_dpp v66, v66, v66 row_shr:1 row_mask:0xf bank_mask:0xf bound_ctrl:1
	s_nop 1
	v_add_f32_dpp v66, v66, v66 row_shr:2 row_mask:0xf bank_mask:0xf bound_ctrl:1
	s_nop 1
	v_add_f32_dpp v66, v66, v66 row_shr:4 row_mask:0xf bank_mask:0xf bound_ctrl:1
	s_nop 1
	v_add_f32_dpp v66, v66, v66 row_shr:8 row_mask:0xf bank_mask:0xf bound_ctrl:1
	s_nop 0
	v_readlane_b32 s9, v66, 15
	v_readlane_b32 s10, v66, 31
	v_readlane_b32 s11, v66, 47
	v_readlane_b32 vcc_lo, v66, 63
	s_nop 1
	v_mov_b32_e32 v66, s9
	v_add_f32_e32 v66, s10, v66
	v_add_f32_e32 v66, s11, v66
	v_add_f32_e32 v66, vcc_lo, v66
	v_mul_f32_e32 v116, 0x3a800000, v66
	v_mov_b32_e32 v117, v116
	v_pk_add_f32 v[18:19], v[18:19], v[116:117] neg_lo:[0,1] neg_hi:[0,1]
	v_pk_add_f32 v[20:21], v[20:21], v[116:117] neg_lo:[0,1] neg_hi:[0,1]
	v_pk_add_f32 v[22:23], v[22:23], v[116:117] neg_lo:[0,1] neg_hi:[0,1]
	v_pk_add_f32 v[24:25], v[24:25], v[116:117] neg_lo:[0,1] neg_hi:[0,1]
	v_pk_add_f32 v[26:27], v[26:27], v[116:117] neg_lo:[0,1] neg_hi:[0,1]
	v_pk_add_f32 v[28:29], v[28:29], v[116:117] neg_lo:[0,1] neg_hi:[0,1]
	v_pk_add_f32 v[30:31], v[30:31], v[116:117] neg_lo:[0,1] neg_hi:[0,1]
	v_pk_add_f32 v[32:33], v[32:33], v[116:117] neg_lo:[0,1] neg_hi:[0,1]
	v_pk_mul_f32 v[66:67], v[18:19], v[18:19]
	v_pk_mul_f32 v[68:69], v[20:21], v[20:21]
	v_pk_fma_f32 v[66:67], v[22:23], v[22:23], v[66:67]
	v_pk_fma_f32 v[68:69], v[24:25], v[24:25], v[68:69]
	v_pk_fma_f32 v[66:67], v[26:27], v[26:27], v[66:67]
	v_pk_fma_f32 v[68:69], v[28:29], v[28:29], v[68:69]
	v_pk_fma_f32 v[66:67], v[30:31], v[30:31], v[66:67]
	v_pk_fma_f32 v[68:69], v[32:33], v[32:33], v[68:69]
	v_pk_add_f32 v[66:67], v[66:67], v[68:69]
	v_add_f32_e32 v66, v66, v67
	s_nop 1
	v_add_f32_dpp v66, v66, v66 row_shr:1 row_mask:0xf bank_mask:0xf bound_ctrl:1
	s_nop 1
	v_add_f32_dpp v66, v66, v66 row_shr:2 row_mask:0xf bank_mask:0xf bound_ctrl:1
	s_nop 1
	v_add_f32_dpp v66, v66, v66 row_shr:4 row_mask:0xf bank_mask:0xf bound_ctrl:1
	s_nop 1
	v_add_f32_dpp v66, v66, v66 row_shr:8 row_mask:0xf bank_mask:0xf bound_ctrl:1
	s_nop 0
	v_readlane_b32 s9, v66, 15
	v_readlane_b32 s10, v66, 31
	v_readlane_b32 s11, v66, 47
	v_readlane_b32 vcc_lo, v66, 63
	s_nop 1
	v_mov_b32_e32 v66, s9
	v_add_f32_e32 v66, s10, v66
	v_add_f32_e32 v66, s11, v66
	v_add_f32_e32 v66, vcc_lo, v66
	v_mul_f32_e32 v66, 0x3a800000, v66
	v_add_f32_e32 v66, 0x3727c5ac, v66
	v_rsq_f32_e32 v118, v66
	s_nop 0
	v_mov_b32_e32 v119, v118
	v_pk_mul_f32 v[18:19], v[18:19], v[118:119]
	v_pk_mul_f32 v[20:21], v[20:21], v[118:119]
	v_pk_mul_f32 v[22:23], v[22:23], v[118:119]
	v_pk_mul_f32 v[24:25], v[24:25], v[118:119]
	v_pk_mul_f32 v[26:27], v[26:27], v[118:119]
	v_pk_mul_f32 v[28:29], v[28:29], v[118:119]
	v_pk_mul_f32 v[30:31], v[30:31], v[118:119]
	v_pk_mul_f32 v[32:33], v[32:33], v[118:119]
	v_pk_fma_f32 v[76:77], v[18:19], v[34:35], v[50:51]
	v_pk_fma_f32 v[78:79], v[20:21], v[36:37], v[52:53]
	v_pk_fma_f32 v[80:81], v[22:23], v[38:39], v[54:55]
	v_pk_fma_f32 v[82:83], v[24:25], v[40:41], v[56:57]
	v_pk_fma_f32 v[84:85], v[26:27], v[42:43], v[58:59]
	v_pk_fma_f32 v[86:87], v[28:29], v[44:45], v[60:61]
	v_pk_fma_f32 v[88:89], v[30:31], v[46:47], v[62:63]
	v_pk_fma_f32 v[90:91], v[32:33], v[48:49], v[64:65]
	v_cvt_pk_bf16_f32 v92, v76, v77
	v_cvt_pk_bf16_f32 v93, v78, v79
	v_cvt_pk_bf16_f32 v94, v80, v81
	v_cvt_pk_bf16_f32 v95, v82, v83
	v_cvt_pk_bf16_f32 v96, v84, v85
	v_cvt_pk_bf16_f32 v97, v86, v87
	v_cvt_pk_bf16_f32 v98, v88, v89
	v_cvt_pk_bf16_f32 v99, v90, v91
	global_store_dwordx2 v115, v[92:93], s[2:3] offset:0
	global_store_dwordx2 v115, v[94:95], s[2:3] offset:512
	global_store_dwordx2 v115, v[96:97], s[2:3] offset:1024
	global_store_dwordx2 v115, v[98:99], s[2:3] offset:1536
	s_add_u32 s2, s2, 0x80000
	s_addc_u32 s3, s3, 0
	s_add_u32 s0, s0, 0x100000
	s_addc_u32 s1, s1, 0
	global_load_dwordx4 v[18:21], v114, s[0:1] offset:0
	global_load_dwordx4 v[22:25], v114, s[0:1] offset:1024
	global_load_dwordx4 v[26:29], v114, s[0:1] offset:2048
	global_load_dwordx4 v[30:33], v114, s[0:1] offset:3072
	s_waitcnt vmcnt(8)
; __device__ __forceinline__ void phase_ln(float* R, const float* __restrict__ g, const float* __restrict__ b, bf16_t* xbf, float samp_scale, const float* __restrict__ part, int nsplit, bool f32_all) {
;     ...
;   for (int r = gw; r < MT; r += nw) {
;     float* row = R + (size_t)r * 1024;
;     f32x4 v[4];
; #pragma unroll
;     for (int i = 0; i < 4; ++i) v[i] = *(const f32x4*)(row + i * 256 + lane * 4);
;     if (r >= MP) {
;       for (int sp = 0; sp < nsplit; ++sp) {
;         const float* prow = part + ((size_t)sp * MS + (r - MP)) * 1024;
; #pragma unroll
;         for (int i = 0; i < 4; ++i) v[i] = v[i] + *(const f32x4*)(prow + i * 256 + lane * 4);
;       }
;     }
;     float s = 0.f;
; #pragma unroll
;     for (int i = 0; i < 4; ++i) s += v[i][0] + v[i][1] + v[i][2] + v[i][3];
; #pragma unroll
;     for (int o = 32; o >= 1; o >>= 1) s += __shfl_xor(s, o);
;     const float mean = s * (1.f / 1024.f);
;     float ss = 0.f;
; #pragma unroll
;     for (int i = 0; i < 4; ++i) { v[i] = v[i] - mean; ss += v[i][0] * v[i][0] + v[i][1] * v[i][1] + v[i][2] * v[i][2] + v[i][3] * v[i][3]; }
; #pragma unroll
;     for (int o = 32; o >= 1; o >>= 1) ss += __shfl_xor(ss, o);
;     const float rstd = rsqrtf(ss * (1.f / 1024.f) + LN_EPS);
; #pragma unroll
;     for (int i = 0; i < 4; ++i) {
;       const f32x4 y = v[i] * rstd * gv[i] + bv[i];
;       if (r >= MP) *(f32x4*)(row + i * 256 + lane * 4) = y * samp_scale;
;       else if (f32_all) *(f32x4*)(row + i * 256 + lane * 4) = y;
;       if (xbf) {
;         u32x2 wv;
;         wv[0] = cvt_pk_bf16(y[0], y[1]); wv[1] = cvt_pk_bf16(y[2], y[3]);
;         *(u32x2*)(xbf + (size_t)r * 1024 + i * 256 + lane * 4) = wv;
;       }
;     }
	v_pk_add_f32 v[66:67], v[0:1], v[2:3]
	v_pk_add_f32 v[68:69], v[4:5], v[6:7]
	v_pk_add_f32 v[70:71], v[8:9], v[10:11]
	v_pk_add_f32 v[72:73], v[12:13], v[14:15]
	v_pk_add_f32 v[66:67], v[66:67], v[68:69]
	v_pk_add_f32 v[70:71], v[70:71], v[72:73]
	v_pk_add_f32 v[66:67], v[66:67], v[70:71]
	v_add_f32_e32 v66, v66, v67
	s_nop 1
	v_add_f32_dpp v66, v66, v66 row_shr:1 row_mask:0xf bank_mask:0xf bound_ctrl:1
	s_nop 1
	v_add_f32_dpp v66, v66, v66 row_shr:2 row_mask:0xf bank_mask:0xf bound_ctrl:1
	s_nop 1
	v_add_f32_dpp v66, v66, v66 row_shr:4 row_mask:0xf bank_mask:0xf bound_ctrl:1
	s_nop 1
	v_add_f32_dpp v66, v66, v66 row_shr:8 row_mask:0xf bank_mask:0xf bound_ctrl:1
	s_nop 0
	v_readlane_b32 s9, v66, 15
	v_readlane_b32 s10, v66, 31
	v_readlane_b32 s11, v66, 47
	v_readlane_b32 vcc_lo, v66, 63
	s_nop 1
	v_mov_b32_e32 v66, s9
	v_add_f32_e32 v66, s10, v66
	v_add_f32_e32 v66, s11, v66
	v_add_f32_e32 v66, vcc_lo, v66
	v_mul_f32_e32 v116, 0x3a800000, v66
	v_mov_b32_e32 v117, v116
	v_pk_add_f32 v[0:1], v[0:1], v[116:117] neg_lo:[0,1] neg_hi:[0,1]
	v_pk_add_f32 v[2:3], v[2:3], v[116:117] neg_lo:[0,1] neg_hi:[0,1]
	v_pk_add_f32 v[4:5], v[4:5], v[116:117] neg_lo:[0,1] neg_hi:[0,1]
	v_pk_add_f32 v[6:7], v[6:7], v[116:117] neg_lo:[0,1] neg_hi:[0,1]
	v_pk_add_f32 v[8:9], v[8:9], v[116:117] neg_lo:[0,1] neg_hi:[0,1]
	v_pk_add_f32 v[10:11], v[10:11], v[116:117] neg_lo:[0,1] neg_hi:[0,1]
	v_pk_add_f32 v[12:13], v[12:13], v[116:117] neg_lo:[0,1] neg_hi:[0,1]
	v_pk_add_f32 v[14:15], v[14:15], v[116:117] neg_lo:[0,1] neg_hi:[0,1]
	v_pk_mul_f32 v[66:67], v[0:1], v[0:1]
	v_pk_mul_f32 v[68:69], v[2:3], v[2:3]
	v_pk_fma_f32 v[66:67], v[4:5], v[4:5], v[66:67]
	v_pk_fma_f32 v[68:69], v[6:7], v[6:7], v[68:69]
	v_pk_fma_f32 v[66:67], v[8:9], v[8:9], v[66:67]
	v_pk_fma_f32 v[68:69], v[10:11], v[10:11], v[68:69]
	v_pk_fma_f32 v[66:67], v[12:13], v[12:13], v[66:67]
	v_pk_fma_f32 v[68:69], v[14:15], v[14:15], v[68:69]
	v_pk_add_f32 v[66:67], v[66:67], v[68:69]
	v_add_f32_e32 v66, v66, v67
	s_nop 1
	v_add_f32_dpp v66, v66, v66 row_shr:1 row_mask:0xf bank_mask:0xf bound_ctrl:1
	s_nop 1
	v_add_f32_dpp v66, v66, v66 row_shr:2 row_mask:0xf bank_mask:0xf bound_ctrl:1
	s_nop 1
	v_add_f32_dpp v66, v66, v66 row_shr:4 row_mask:0xf bank_mask:0xf bound_ctrl:1
	s_nop 1
	v_add_f32_dpp v66, v66, v66 row_shr:8 row_mask:0xf bank_mask:0xf bound_ctrl:1
	s_nop 0
	v_readlane_b32 s9, v66, 15
	v_readlane_b32 s10, v66, 31
	v_readlane_b32 s11, v66, 47
	v_readlane_b32 vcc_lo, v66, 63
	s_nop 1
	v_mov_b32_e32 v66, s9
	v_add_f32_e32 v66, s10, v66
	v_add_f32_e32 v66, s11, v66
	v_add_f32_e32 v66, vcc_lo, v66
	v_mul_f32_e32 v66, 0x3a800000, v66
	v_add_f32_e32 v66, 0x3727c5ac, v66
	v_rsq_f32_e32 v118, v66
	s_nop 0
	v_mov_b32_e32 v119, v118
	v_pk_mul_f32 v[0:1], v[0:1], v[118:119]
	v_pk_mul_f32 v[2:3], v[2:3], v[118:119]
	v_pk_mul_f32 v[4:5], v[4:5], v[118:119]
	v_pk_mul_f32 v[6:7], v[6:7], v[118:119]
	v_pk_mul_f32 v[8:9], v[8:9], v[118:119]
	v_pk_mul_f32 v[10:11], v[10:11], v[118:119]
	v_pk_mul_f32 v[12:13], v[12:13], v[118:119]
	v_pk_mul_f32 v[14:15], v[14:15], v[118:119]
	v_pk_fma_f32 v[76:77], v[0:1], v[34:35], v[50:51]
	v_pk_fma_f32 v[78:79], v[2:3], v[36:37], v[52:53]
	v_pk_fma_f32 v[80:81], v[4:5], v[38:39], v[54:55]
	v_pk_fma_f32 v[82:83], v[6:7], v[40:41], v[56:57]
	v_pk_fma_f32 v[84:85], v[8:9], v[42:43], v[58:59]
	v_pk_fma_f32 v[86:87], v[10:11], v[44:45], v[60:61]
	v_pk_fma_f32 v[88:89], v[12:13], v[46:47], v[62:63]
	v_pk_fma_f32 v[90:91], v[14:15], v[48:49], v[64:65]
	v_cvt_pk_bf16_f32 v92, v76, v77
	v_cvt_pk_bf16_f32 v93, v78, v79
	v_cvt_pk_bf16_f32 v94, v80, v81
	v_cvt_pk_bf16_f32 v95, v82, v83
	v_cvt_pk_bf16_f32 v96, v84, v85
	v_cvt_pk_bf16_f32 v97, v86, v87
	v_cvt_pk_bf16_f32 v98, v88, v89
	v_cvt_pk_bf16_f32 v99, v90, v91
	global_store_dwordx2 v115, v[92:93], s[2:3] offset:0
	global_store_dwordx2 v115, v[94:95], s[2:3] offset:512
	global_store_dwordx2 v115, v[96:97], s[2:3] offset:1024
	global_store_dwordx2 v115, v[98:99], s[2:3] offset:1536
	s_add_u32 s2, s2, 0x80000
	s_addc_u32 s3, s3, 0
	s_add_u32 s0, s0, 0x100000
	s_addc_u32 s1, s1, 0
	global_load_dwordx4 v[0:3], v114, s[0:1] offset:0
	global_load_dwordx4 v[4:7], v114, s[0:1] offset:1024
	global_load_dwordx4 v[8:11], v114, s[0:1] offset:2048
	global_load_dwordx4 v[12:15], v114, s[0:1] offset:3072
	s_waitcnt vmcnt(8)
; __device__ __forceinline__ void phase_ln(float* R, const float* __restrict__ g, const float* __restrict__ b, bf16_t* xbf, float samp_scale, const float* __restrict__ part, int nsplit, bool f32_all) {
;     ...
;   for (int r = gw; r < MT; r += nw) {
;     float* row = R + (size_t)r * 1024;
;     f32x4 v[4];
; #pragma unroll
;     for (int i = 0; i < 4; ++i) v[i] = *(const f32x4*)(row + i * 256 + lane * 4);
;     if (r >= MP) {
;       for (int sp = 0; sp < nsplit; ++sp) {
;         const float* prow = part + ((size_t)sp * MS + (r - MP)) * 1024;
; #pragma unroll
;         for (int i = 0; i < 4; ++i) v[i] = v[i] + *(const f32x4*)(prow + i * 256 + lane * 4);
;       }
;     }
;     float s = 0.f;
; #pragma unroll
;     for (int i = 0; i < 4; ++i) s += v[i][0] + v[i][1] + v[i][2] + v[i][3];
; #pragma unroll
;     for (int o = 32; o >= 1; o >>= 1) s += __shfl_xor(s, o);
;     const float mean = s * (1.f / 1024.f);
;     float ss = 0.f;
; #pragma unroll
;     for (int i = 0; i < 4; ++i) { v[i] = v[i] - mean; ss += v[i][0] * v[i][0] + v[i][1] * v[i][1] + v[i][2] * v[i][2] + v[i][3] * v[i][3]; }
; #pragma unroll
;     for (int o = 32; o >= 1; o >>= 1) ss += __shfl_xor(ss, o);
;     const float rstd = rsqrtf(ss * (1.f / 1024.f) + LN_EPS);
; #pragma unroll
;     for (int i = 0; i < 4; ++i) {
;       const f32x4 y = v[i] * rstd * gv[i] + bv[i];
;       if (r >= MP) *(f32x4*)(row + i * 256 + lane * 4) = y * samp_scale;
;       else if (f32_all) *(f32x4*)(row + i * 256 + lane * 4) = y;
;       if (xbf) {
;         u32x2 wv;
;         wv[0] = cvt_pk_bf16(y[0], y[1]); wv[1] = cvt_pk_bf16(y[2], y[3]);
;         *(u32x2*)(xbf + (size_t)r * 1024 + i * 256 + lane * 4) = wv;
;       }
;     }
	v_pk_add_f32 v[66:67], v[18:19], v[20:21]
	v_pk_add_f32 v[68:69], v[22:23], v[24:25]
	v_pk_add_f32 v[70:71], v[26:27], v[28:29]
	v_pk_add_f32 v[72:73], v[30:31], v[32:33]
	v_pk_add_f32 v[66:67], v[66:67], v[68:69]
	v_pk_add_f32 v[70:71], v[70:71], v[72:73]
	v_pk_add_f32 v[66:67], v[66:67], v[70:71]
	v_add_f32_e32 v66, v66, v67
	s_nop 1
	v_add_f32_dpp v66, v66, v66 row_shr:1 row_mask:0xf bank_mask:0xf bound_ctrl:1
	s_nop 1
	v_add_f32_dpp v66, v66, v66 row_shr:2 row_mask:0xf bank_mask:0xf bound_ctrl:1
	s_nop 1
	v_add_f32_dpp v66, v66, v66 row_shr:4 row_mask:0xf bank_mask:0xf bound_ctrl:1
	s_nop 1
	v_add_f32_dpp v66, v66, v66 row_shr:8 row_mask:0xf bank_mask:0xf bound_ctrl:1
	s_nop 0
	v_readlane_b32 s9, v66, 15
	v_readlane_b32 s10, v66, 31
	v_readlane_b32 s11, v66, 47
	v_readlane_b32 vcc_lo, v66, 63
	s_nop 1
	v_mov_b32_e32 v66, s9
	v_add_f32_e32 v66, s10, v66
	v_add_f32_e32 v66, s11, v66
	v_add_f32_e32 v66, vcc_lo, v66
	v_mul_f32_e32 v116, 0x3a800000, v66
	v_mov_b32_e32 v117, v116
	v_pk_add_f32 v[18:19], v[18:19], v[116:117] neg_lo:[0,1] neg_hi:[0,1]
	v_pk_add_f32 v[20:21], v[20:21], v[116:117] neg_lo:[0,1] neg_hi:[0,1]
	v_pk_add_f32 v[22:23], v[22:23], v[116:117] neg_lo:[0,1] neg_hi:[0,1]
	v_pk_add_f32 v[24:25], v[24:25], v[116:117] neg_lo:[0,1] neg_hi:[0,1]
	v_pk_add_f32 v[26:27], v[26:27], v[116:117] neg_lo:[0,1] neg_hi:[0,1]
	v_pk_add_f32 v[28:29], v[28:29], v[116:117] neg_lo:[0,1] neg_hi:[0,1]
	v_pk_add_f32 v[30:31], v[30:31], v[116:117] neg_lo:[0,1] neg_hi:[0,1]
	v_pk_add_f32 v[32:33], v[32:33], v[116:117] neg_lo:[0,1] neg_hi:[0,1]
	v_pk_mul_f32 v[66:67], v[18:19], v[18:19]
	v_pk_mul_f32 v[68:69], v[20:21], v[20:21]
	v_pk_fma_f32 v[66:67], v[22:23], v[22:23], v[66:67]
	v_pk_fma_f32 v[68:69], v[24:25], v[24:25], v[68:69]
	v_pk_fma_f32 v[66:67], v[26:27], v[26:27], v[66:67]
	v_pk_fma_f32 v[68:69], v[28:29], v[28:29], v[68:69]
	v_pk_fma_f32 v[66:67], v[30:31], v[30:31], v[66:67]
	v_pk_fma_f32 v[68:69], v[32:33], v[32:33], v[68:69]
	v_pk_add_f32 v[66:67], v[66:67], v[68:69]
	v_add_f32_e32 v66, v66, v67
	s_nop 1
	v_add_f32_dpp v66, v66, v66 row_shr:1 row_mask:0xf bank_mask:0xf bound_ctrl:1
	s_nop 1
	v_add_f32_dpp v66, v66, v66 row_shr:2 row_mask:0xf bank_mask:0xf bound_ctrl:1
	s_nop 1
	v_add_f32_dpp v66, v66, v66 row_shr:4 row_mask:0xf bank_mask:0xf bound_ctrl:1
	s_nop 1
	v_add_f32_dpp v66, v66, v66 row_shr:8 row_mask:0xf bank_mask:0xf bound_ctrl:1
	s_nop 0
	v_readlane_b32 s9, v66, 15
	v_readlane_b32 s10, v66, 31
	v_readlane_b32 s11, v66, 47
	v_readlane_b32 vcc_lo, v66, 63
	s_nop 1
	v_mov_b32_e32 v66, s9
	v_add_f32_e32 v66, s10, v66
	v_add_f32_e32 v66, s11, v66
	v_add_f32_e32 v66, vcc_lo, v66
	v_mul_f32_e32 v66, 0x3a800000, v66
	v_add_f32_e32 v66, 0x3727c5ac, v66
	v_rsq_f32_e32 v118, v66
	s_nop 0
	v_mov_b32_e32 v119, v118
	v_pk_mul_f32 v[18:19], v[18:19], v[118:119]
	v_pk_mul_f32 v[20:21], v[20:21], v[118:119]
	v_pk_mul_f32 v[22:23], v[22:23], v[118:119]
	v_pk_mul_f32 v[24:25], v[24:25], v[118:119]
	v_pk_mul_f32 v[26:27], v[26:27], v[118:119]
	v_pk_mul_f32 v[28:29], v[28:29], v[118:119]
	v_pk_mul_f32 v[30:31], v[30:31], v[118:119]
	v_pk_mul_f32 v[32:33], v[32:33], v[118:119]
	v_pk_fma_f32 v[76:77], v[18:19], v[34:35], v[50:51]
	v_pk_fma_f32 v[78:79], v[20:21], v[36:37], v[52:53]
	v_pk_fma_f32 v[80:81], v[22:23], v[38:39], v[54:55]
	v_pk_fma_f32 v[82:83], v[24:25], v[40:41], v[56:57]
	v_pk_fma_f32 v[84:85], v[26:27], v[42:43], v[58:59]
	v_pk_fma_f32 v[86:87], v[28:29], v[44:45], v[60:61]
	v_pk_fma_f32 v[88:89], v[30:31], v[46:47], v[62:63]
	v_pk_fma_f32 v[90:91], v[32:33], v[48:49], v[64:65]
	v_cvt_pk_bf16_f32 v92, v76, v77
	v_cvt_pk_bf16_f32 v93, v78, v79
	v_cvt_pk_bf16_f32 v94, v80, v81
	v_cvt_pk_bf16_f32 v95, v82, v83
	v_cvt_pk_bf16_f32 v96, v84, v85
	v_cvt_pk_bf16_f32 v97, v86, v87
	v_cvt_pk_bf16_f32 v98, v88, v89
	v_cvt_pk_bf16_f32 v99, v90, v91
	global_store_dwordx2 v115, v[92:93], s[2:3] offset:0
	global_store_dwordx2 v115, v[94:95], s[2:3] offset:512
	global_store_dwordx2 v115, v[96:97], s[2:3] offset:1024
	global_store_dwordx2 v115, v[98:99], s[2:3] offset:1536
	s_add_u32 s2, s2, 0x80000
	s_addc_u32 s3, s3, 0
	s_add_u32 s0, s0, 0x100000
	s_addc_u32 s1, s1, 0
	global_load_dwordx4 v[18:21], v114, s[0:1] offset:0
	global_load_dwordx4 v[22:25], v114, s[0:1] offset:1024
	global_load_dwordx4 v[26:29], v114, s[0:1] offset:2048
	global_load_dwordx4 v[30:33], v114, s[0:1] offset:3072
	s_waitcnt vmcnt(8)
; __device__ __forceinline__ void phase_ln(float* R, const float* __restrict__ g, const float* __restrict__ b, bf16_t* xbf, float samp_scale, const float* __restrict__ part, int nsplit, bool f32_all) {
;     ...
;   for (int r = gw; r < MT; r += nw) {
;     float* row = R + (size_t)r * 1024;
;     f32x4 v[4];
; #pragma unroll
;     for (int i = 0; i < 4; ++i) v[i] = *(const f32x4*)(row + i * 256 + lane * 4);
;     if (r >= MP) {
;       for (int sp = 0; sp < nsplit; ++sp) {
;         const float* prow = part + ((size_t)sp * MS + (r - MP)) * 1024;
; #pragma unroll
;         for (int i = 0; i < 4; ++i) v[i] = v[i] + *(const f32x4*)(prow + i * 256 + lane * 4);
;       }
;     }
;     float s = 0.f;
; #pragma unroll
;     for (int i = 0; i < 4; ++i) s += v[i][0] + v[i][1] + v[i][2] + v[i][3];
; #pragma unroll
;     for (int o = 32; o >= 1; o >>= 1) s += __shfl_xor(s, o);
;     const float mean = s * (1.f / 1024.f);
;     float ss = 0.f;
; #pragma unroll
;     for (int i = 0; i < 4; ++i) { v[i] = v[i] - mean; ss += v[i][0] * v[i][0] + v[i][1] * v[i][1] + v[i][2] * v[i][2] + v[i][3] * v[i][3]; }
; #pragma unroll
;     for (int o = 32; o >= 1; o >>= 1) ss += __shfl_xor(ss, o);
;     const float rstd = rsqrtf(ss * (1.f / 1024.f) + LN_EPS);
; #pragma unroll
;     for (int i = 0; i < 4; ++i) {
;       const f32x4 y = v[i] * rstd * gv[i] + bv[i];
;       if (r >= MP) *(f32x4*)(row + i * 256 + lane * 4) = y * samp_scale;
;       else if (f32_all) *(f32x4*)(row + i * 256 + lane * 4) = y;
;       if (xbf) {
;         u32x2 wv;
;         wv[0] = cvt_pk_bf16(y[0], y[1]); wv[1] = cvt_pk_bf16(y[2], y[3]);
;         *(u32x2*)(xbf + (size_t)r * 1024 + i * 256 + lane * 4) = wv;
;       }
;     }
	v_pk_add_f32 v[66:67], v[0:1], v[2:3]
	v_pk_add_f32 v[68:69], v[4:5], v[6:7]
	v_pk_add_f32 v[70:71], v[8:9], v[10:11]
	v_pk_add_f32 v[72:73], v[12:13], v[14:15]
	v_pk_add_f32 v[66:67], v[66:67], v[68:69]
	v_pk_add_f32 v[70:71], v[70:71], v[72:73]
	v_pk_add_f32 v[66:67], v[66:67], v[70:71]
	v_add_f32_e32 v66, v66, v67
	s_nop 1
	v_add_f32_dpp v66, v66, v66 row_shr:1 row_mask:0xf bank_mask:0xf bound_ctrl:1
	s_nop 1
	v_add_f32_dpp v66, v66, v66 row_shr:2 row_mask:0xf bank_mask:0xf bound_ctrl:1
	s_nop 1
	v_add_f32_dpp v66, v66, v66 row_shr:4 row_mask:0xf bank_mask:0xf bound_ctrl:1
	s_nop 1
	v_add_f32_dpp v66, v66, v66 row_shr:8 row_mask:0xf bank_mask:0xf bound_ctrl:1
	s_nop 0
	v_readlane_b32 s9, v66, 15
	v_readlane_b32 s10, v66, 31
	v_readlane_b32 s11, v66, 47
	v_readlane_b32 vcc_lo, v66, 63
	s_nop 1
	v_mov_b32_e32 v66, s9
	v_add_f32_e32 v66, s10, v66
	v_add_f32_e32 v66, s11, v66
	v_add_f32_e32 v66, vcc_lo, v66
	v_mul_f32_e32 v116, 0x3a800000, v66
	v_mov_b32_e32 v117, v116
	v_pk_add_f32 v[0:1], v[0:1], v[116:117] neg_lo:[0,1] neg_hi:[0,1]
	v_pk_add_f32 v[2:3], v[2:3], v[116:117] neg_lo:[0,1] neg_hi:[0,1]
	v_pk_add_f32 v[4:5], v[4:5], v[116:117] neg_lo:[0,1] neg_hi:[0,1]
	v_pk_add_f32 v[6:7], v[6:7], v[116:117] neg_lo:[0,1] neg_hi:[0,1]
	v_pk_add_f32 v[8:9], v[8:9], v[116:117] neg_lo:[0,1] neg_hi:[0,1]
	v_pk_add_f32 v[10:11], v[10:11], v[116:117] neg_lo:[0,1] neg_hi:[0,1]
	v_pk_add_f32 v[12:13], v[12:13], v[116:117] neg_lo:[0,1] neg_hi:[0,1]
	v_pk_add_f32 v[14:15], v[14:15], v[116:117] neg_lo:[0,1] neg_hi:[0,1]
	v_pk_mul_f32 v[66:67], v[0:1], v[0:1]
	v_pk_mul_f32 v[68:69], v[2:3], v[2:3]
	v_pk_fma_f32 v[66:67], v[4:5], v[4:5], v[66:67]
	v_pk_fma_f32 v[68:69], v[6:7], v[6:7], v[68:69]
	v_pk_fma_f32 v[66:67], v[8:9], v[8:9], v[66:67]
	v_pk_fma_f32 v[68:69], v[10:11], v[10:11], v[68:69]
	v_pk_fma_f32 v[66:67], v[12:13], v[12:13], v[66:67]
	v_pk_fma_f32 v[68:69], v[14:15], v[14:15], v[68:69]
	v_pk_add_f32 v[66:67], v[66:67], v[68:69]
	v_add_f32_e32 v66, v66, v67
	s_nop 1
	v_add_f32_dpp v66, v66, v66 row_shr:1 row_mask:0xf bank_mask:0xf bound_ctrl:1
	s_nop 1
	v_add_f32_dpp v66, v66, v66 row_shr:2 row_mask:0xf bank_mask:0xf bound_ctrl:1
	s_nop 1
	v_add_f32_dpp v66, v66, v66 row_shr:4 row_mask:0xf bank_mask:0xf bound_ctrl:1
	s_nop 1
	v_add_f32_dpp v66, v66, v66 row_shr:8 row_mask:0xf bank_mask:0xf bound_ctrl:1
	s_nop 0
	v_readlane_b32 s9, v66, 15
	v_readlane_b32 s10, v66, 31
	v_readlane_b32 s11, v66, 47
	v_readlane_b32 vcc_lo, v66, 63
	s_nop 1
	v_mov_b32_e32 v66, s9
	v_add_f32_e32 v66, s10, v66
	v_add_f32_e32 v66, s11, v66
	v_add_f32_e32 v66, vcc_lo, v66
	v_mul_f32_e32 v66, 0x3a800000, v66
	v_add_f32_e32 v66, 0x3727c5ac, v66
	v_rsq_f32_e32 v118, v66
	s_nop 0
	v_mov_b32_e32 v119, v118
	v_pk_mul_f32 v[0:1], v[0:1], v[118:119]
	v_pk_mul_f32 v[2:3], v[2:3], v[118:119]
	v_pk_mul_f32 v[4:5], v[4:5], v[118:119]
	v_pk_mul_f32 v[6:7], v[6:7], v[118:119]
	v_pk_mul_f32 v[8:9], v[8:9], v[118:119]
	v_pk_mul_f32 v[10:11], v[10:11], v[118:119]
	v_pk_mul_f32 v[12:13], v[12:13], v[118:119]
	v_pk_mul_f32 v[14:15], v[14:15], v[118:119]
	v_pk_fma_f32 v[76:77], v[0:1], v[34:35], v[50:51]
	v_pk_fma_f32 v[78:79], v[2:3], v[36:37], v[52:53]
	v_pk_fma_f32 v[80:81], v[4:5], v[38:39], v[54:55]
	v_pk_fma_f32 v[82:83], v[6:7], v[40:41], v[56:57]
	v_pk_fma_f32 v[84:85], v[8:9], v[42:43], v[58:59]
	v_pk_fma_f32 v[86:87], v[10:11], v[44:45], v[60:61]
	v_pk_fma_f32 v[88:89], v[12:13], v[46:47], v[62:63]
	v_pk_fma_f32 v[90:91], v[14:15], v[48:49], v[64:65]
	v_cvt_pk_bf16_f32 v92, v76, v77
	v_cvt_pk_bf16_f32 v93, v78, v79
	v_cvt_pk_bf16_f32 v94, v80, v81
	v_cvt_pk_bf16_f32 v95, v82, v83
	v_cvt_pk_bf16_f32 v96, v84, v85
	v_cvt_pk_bf16_f32 v97, v86, v87
	v_cvt_pk_bf16_f32 v98, v88, v89
	v_cvt_pk_bf16_f32 v99, v90, v91
	global_store_dwordx2 v115, v[92:93], s[2:3] offset:0
	global_store_dwordx2 v115, v[94:95], s[2:3] offset:512
	global_store_dwordx2 v115, v[96:97], s[2:3] offset:1024
	global_store_dwordx2 v115, v[98:99], s[2:3] offset:1536
	s_add_u32 s2, s2, 0x80000
	s_addc_u32 s3, s3, 0
	s_add_u32 s0, s0, 0x100000
	s_addc_u32 s1, s1, 0
	global_load_dwordx4 v[0:3], v114, s[0:1] offset:0
	global_load_dwordx4 v[4:7], v114, s[0:1] offset:1024
	global_load_dwordx4 v[8:11], v114, s[0:1] offset:2048
	global_load_dwordx4 v[12:15], v114, s[0:1] offset:3072
	s_waitcnt vmcnt(8)
; __device__ __forceinline__ void phase_ln(float* R, const float* __restrict__ g, const float* __restrict__ b, bf16_t* xbf, float samp_scale, const float* __restrict__ part, int nsplit, bool f32_all) {
;     ...
;   for (int r = gw; r < MT; r += nw) {
;     float* row = R + (size_t)r * 1024;
;     f32x4 v[4];
; #pragma unroll
;     for (int i = 0; i < 4; ++i) v[i] = *(const f32x4*)(row + i * 256 + lane * 4);
;     if (r >= MP) {
;       for (int sp = 0; sp < nsplit; ++sp) {
;         const float* prow = part + ((size_t)sp * MS + (r - MP)) * 1024;
; #pragma unroll
;         for (int i = 0; i < 4; ++i) v[i] = v[i] + *(const f32x4*)(prow + i * 256 + lane * 4);
;       }
;     }
;     float s = 0.f;
; #pragma unroll
;     for (int i = 0; i < 4; ++i) s += v[i][0] + v[i][1] + v[i][2] + v[i][3];
; #pragma unroll
;     for (int o = 32; o >= 1; o >>= 1) s += __shfl_xor(s, o);
;     const float mean = s * (1.f / 1024.f);
;     float ss = 0.f;
; #pragma unroll
;     for (int i = 0; i < 4; ++i) { v[i] = v[i] - mean; ss += v[i][0] * v[i][0] + v[i][1] * v[i][1] + v[i][2] * v[i][2] + v[i][3] * v[i][3]; }
; #pragma unroll
;     for (int o = 32; o >= 1; o >>= 1) ss += __shfl_xor(ss, o);
;     const float rstd = rsqrtf(ss * (1.f / 1024.f) + LN_EPS);
; #pragma unroll
;     for (int i = 0; i < 4; ++i) {
;       const f32x4 y = v[i] * rstd * gv[i] + bv[i];
;       if (r >= MP) *(f32x4*)(row + i * 256 + lane * 4) = y * samp_scale;
;       else if (f32_all) *(f32x4*)(row + i * 256 + lane * 4) = y;
;       if (xbf) {
;         u32x2 wv;
;         wv[0] = cvt_pk_bf16(y[0], y[1]); wv[1] = cvt_pk_bf16(y[2], y[3]);
;         *(u32x2*)(xbf + (size_t)r * 1024 + i * 256 + lane * 4) = wv;
;       }
;     }
	v_pk_add_f32 v[66:67], v[18:19], v[20:21]
	v_pk_add_f32 v[68:69], v[22:23], v[24:25]
	v_pk_add_f32 v[70:71], v[26:27], v[28:29]
	v_pk_add_f32 v[72:73], v[30:31], v[32:33]
	v_pk_add_f32 v[66:67], v[66:67], v[68:69]
	v_pk_add_f32 v[70:71], v[70:71], v[72:73]
	v_pk_add_f32 v[66:67], v[66:67], v[70:71]
	v_add_f32_e32 v66, v66, v67
	s_nop 1
	v_add_f32_dpp v66, v66, v66 row_shr:1 row_mask:0xf bank_mask:0xf bound_ctrl:1
	s_nop 1
	v_add_f32_dpp v66, v66, v66 row_shr:2 row_mask:0xf bank_mask:0xf bound_ctrl:1
	s_nop 1
	v_add_f32_dpp v66, v66, v66 row_shr:4 row_mask:0xf bank_mask:0xf bound_ctrl:1
	s_nop 1
	v_add_f32_dpp v66, v66, v66 row_shr:8 row_mask:0xf bank_mask:0xf bound_ctrl:1
	s_nop 0
	v_readlane_b32 s9, v66, 15
	v_readlane_b32 s10, v66, 31
	v_readlane_b32 s11, v66, 47
	v_readlane_b32 vcc_lo, v66, 63
	s_nop 1
	v_mov_b32_e32 v66, s9
	v_add_f32_e32 v66, s10, v66
	v_add_f32_e32 v66, s11, v66
	v_add_f32_e32 v66, vcc_lo, v66
	v_mul_f32_e32 v116, 0x3a800000, v66
	v_mov_b32_e32 v117, v116
	v_pk_add_f32 v[18:19], v[18:19], v[116:117] neg_lo:[0,1] neg_hi:[0,1]
	v_pk_add_f32 v[20:21], v[20:21], v[116:117] neg_lo:[0,1] neg_hi:[0,1]
	v_pk_add_f32 v[22:23], v[22:23], v[116:117] neg_lo:[0,1] neg_hi:[0,1]
	v_pk_add_f32 v[24:25], v[24:25], v[116:117] neg_lo:[0,1] neg_hi:[0,1]
	v_pk_add_f32 v[26:27], v[26:27], v[116:117] neg_lo:[0,1] neg_hi:[0,1]
	v_pk_add_f32 v[28:29], v[28:29], v[116:117] neg_lo:[0,1] neg_hi:[0,1]
	v_pk_add_f32 v[30:31], v[30:31], v[116:117] neg_lo:[0,1] neg_hi:[0,1]
	v_pk_add_f32 v[32:33], v[32:33], v[116:117] neg_lo:[0,1] neg_hi:[0,1]
	v_pk_mul_f32 v[66:67], v[18:19], v[18:19]
	v_pk_mul_f32 v[68:69], v[20:21], v[20:21]
	v_pk_fma_f32 v[66:67], v[22:23], v[22:23], v[66:67]
	v_pk_fma_f32 v[68:69], v[24:25], v[24:25], v[68:69]
	v_pk_fma_f32 v[66:67], v[26:27], v[26:27], v[66:67]
	v_pk_fma_f32 v[68:69], v[28:29], v[28:29], v[68:69]
	v_pk_fma_f32 v[66:67], v[30:31], v[30:31], v[66:67]
	v_pk_fma_f32 v[68:69], v[32:33], v[32:33], v[68:69]
	v_pk_add_f32 v[66:67], v[66:67], v[68:69]
	v_add_f32_e32 v66, v66, v67
	s_nop 1
	v_add_f32_dpp v66, v66, v66 row_shr:1 row_mask:0xf bank_mask:0xf bound_ctrl:1
	s_nop 1
	v_add_f32_dpp v66, v66, v66 row_shr:2 row_mask:0xf bank_mask:0xf bound_ctrl:1
	s_nop 1
	v_add_f32_dpp v66, v66, v66 row_shr:4 row_mask:0xf bank_mask:0xf bound_ctrl:1
	s_nop 1
	v_add_f32_dpp v66, v66, v66 row_shr:8 row_mask:0xf bank_mask:0xf bound_ctrl:1
	s_nop 0
	v_readlane_b32 s9, v66, 15
	v_readlane_b32 s10, v66, 31
	v_readlane_b32 s11, v66, 47
	v_readlane_b32 vcc_lo, v66, 63
	s_nop 1
	v_mov_b32_e32 v66, s9
	v_add_f32_e32 v66, s10, v66
	v_add_f32_e32 v66, s11, v66
	v_add_f32_e32 v66, vcc_lo, v66
	v_mul_f32_e32 v66, 0x3a800000, v66
	v_add_f32_e32 v66, 0x3727c5ac, v66
	v_rsq_f32_e32 v118, v66
	s_nop 0
	v_mov_b32_e32 v119, v118
	v_pk_mul_f32 v[18:19], v[18:19], v[118:119]
	v_pk_mul_f32 v[20:21], v[20:21], v[118:119]
	v_pk_mul_f32 v[22:23], v[22:23], v[118:119]
	v_pk_mul_f32 v[24:25], v[24:25], v[118:119]
	v_pk_mul_f32 v[26:27], v[26:27], v[118:119]
	v_pk_mul_f32 v[28:29], v[28:29], v[118:119]
	v_pk_mul_f32 v[30:31], v[30:31], v[118:119]
	v_pk_mul_f32 v[32:33], v[32:33], v[118:119]
	v_pk_fma_f32 v[76:77], v[18:19], v[34:35], v[50:51]
	v_pk_fma_f32 v[78:79], v[20:21], v[36:37], v[52:53]
	v_pk_fma_f32 v[80:81], v[22:23], v[38:39], v[54:55]
	v_pk_fma_f32 v[82:83], v[24:25], v[40:41], v[56:57]
	v_pk_fma_f32 v[84:85], v[26:27], v[42:43], v[58:59]
	v_pk_fma_f32 v[86:87], v[28:29], v[44:45], v[60:61]
	v_pk_fma_f32 v[88:89], v[30:31], v[46:47], v[62:63]
	v_pk_fma_f32 v[90:91], v[32:33], v[48:49], v[64:65]
	v_cvt_pk_bf16_f32 v92, v76, v77
	v_cvt_pk_bf16_f32 v93, v78, v79
	v_cvt_pk_bf16_f32 v94, v80, v81
	v_cvt_pk_bf16_f32 v95, v82, v83
	v_cvt_pk_bf16_f32 v96, v84, v85
	v_cvt_pk_bf16_f32 v97, v86, v87
	v_cvt_pk_bf16_f32 v98, v88, v89
	v_cvt_pk_bf16_f32 v99, v90, v91
	global_store_dwordx2 v115, v[92:93], s[2:3] offset:0
	global_store_dwordx2 v115, v[94:95], s[2:3] offset:512
	global_store_dwordx2 v115, v[96:97], s[2:3] offset:1024
	global_store_dwordx2 v115, v[98:99], s[2:3] offset:1536
	s_add_u32 s2, s2, 0x80000
	s_addc_u32 s3, s3, 0
	s_add_u32 s0, s0, 0x100000
	s_addc_u32 s1, s1, 0
	global_load_dwordx4 v[18:21], v114, s[0:1] offset:0
	global_load_dwordx4 v[22:25], v114, s[0:1] offset:1024
	global_load_dwordx4 v[26:29], v114, s[0:1] offset:2048
	global_load_dwordx4 v[30:33], v114, s[0:1] offset:3072
	s_waitcnt vmcnt(8)
; __device__ __forceinline__ void phase_ln(float* R, const float* __restrict__ g, const float* __restrict__ b, bf16_t* xbf, float samp_scale, const float* __restrict__ part, int nsplit, bool f32_all) {
;     ...
;   for (int r = gw; r < MT; r += nw) {
;     float* row = R + (size_t)r * 1024;
;     f32x4 v[4];
; #pragma unroll
;     for (int i = 0; i < 4; ++i) v[i] = *(const f32x4*)(row + i * 256 + lane * 4);
;     if (r >= MP) {
;       for (int sp = 0; sp < nsplit; ++sp) {
;         const float* prow = part + ((size_t)sp * MS + (r - MP)) * 1024;
; #pragma unroll
;         for (int i = 0; i < 4; ++i) v[i] = v[i] + *(const f32x4*)(prow + i * 256 + lane * 4);
;       }
;     }
;     float s = 0.f;
; #pragma unroll
;     for (int i = 0; i < 4; ++i) s += v[i][0] + v[i][1] + v[i][2] + v[i][3];
; #pragma unroll
;     for (int o = 32; o >= 1; o >>= 1) s += __shfl_xor(s, o);
;     const float mean = s * (1.f / 1024.f);
;     float ss = 0.f;
; #pragma unroll
;     for (int i = 0; i < 4; ++i) { v[i] = v[i] - mean; ss += v[i][0] * v[i][0] + v[i][1] * v[i][1] + v[i][2] * v[i][2] + v[i][3] * v[i][3]; }
; #pragma unroll
;     for (int o = 32; o >= 1; o >>= 1) ss += __shfl_xor(ss, o);
;     const float rstd = rsqrtf(ss * (1.f / 1024.f) + LN_EPS);
; #pragma unroll
;     for (int i = 0; i < 4; ++i) {
;       const f32x4 y = v[i] * rstd * gv[i] + bv[i];
;       if (r >= MP) *(f32x4*)(row + i * 256 + lane * 4) = y * samp_scale;
;       else if (f32_all) *(f32x4*)(row + i * 256 + lane * 4) = y;
;       if (xbf) {
;         u32x2 wv;
;         wv[0] = cvt_pk_bf16(y[0], y[1]); wv[1] = cvt_pk_bf16(y[2], y[3]);
;         *(u32x2*)(xbf + (size_t)r * 1024 + i * 256 + lane * 4) = wv;
;       }
;     }
	v_pk_add_f32 v[66:67], v[0:1], v[2:3]
	v_pk_add_f32 v[68:69], v[4:5], v[6:7]
	v_pk_add_f32 v[70:71], v[8:9], v[10:11]
	v_pk_add_f32 v[72:73], v[12:13], v[14:15]
	v_pk_add_f32 v[66:67], v[66:67], v[68:69]
	v_pk_add_f32 v[70:71], v[70:71], v[72:73]
	v_pk_add_f32 v[66:67], v[66:67], v[70:71]
	v_add_f32_e32 v66, v66, v67
	s_nop 1
	v_add_f32_dpp v66, v66, v66 row_shr:1 row_mask:0xf bank_mask:0xf bound_ctrl:1
	s_nop 1
	v_add_f32_dpp v66, v66, v66 row_shr:2 row_mask:0xf bank_mask:0xf bound_ctrl:1
	s_nop 1
	v_add_f32_dpp v66, v66, v66 row_shr:4 row_mask:0xf bank_mask:0xf bound_ctrl:1
	s_nop 1
	v_add_f32_dpp v66, v66, v66 row_shr:8 row_mask:0xf bank_mask:0xf bound_ctrl:1
	s_nop 0
	v_readlane_b32 s9, v66, 15
	v_readlane_b32 s10, v66, 31
	v_readlane_b32 s11, v66, 47
	v_readlane_b32 vcc_lo, v66, 63
	s_nop 1
	v_mov_b32_e32 v66, s9
	v_add_f32_e32 v66, s10, v66
	v_add_f32_e32 v66, s11, v66
	v_add_f32_e32 v66, vcc_lo, v66
	v_mul_f32_e32 v116, 0x3a800000, v66
	v_mov_b32_e32 v117, v116
	v_pk_add_f32 v[0:1], v[0:1], v[116:117] neg_lo:[0,1] neg_hi:[0,1]
	v_pk_add_f32 v[2:3], v[2:3], v[116:117] neg_lo:[0,1] neg_hi:[0,1]
	v_pk_add_f32 v[4:5], v[4:5], v[116:117] neg_lo:[0,1] neg_hi:[0,1]
	v_pk_add_f32 v[6:7], v[6:7], v[116:117] neg_lo:[0,1] neg_hi:[0,1]
	v_pk_add_f32 v[8:9], v[8:9], v[116:117] neg_lo:[0,1] neg_hi:[0,1]
	v_pk_add_f32 v[10:11], v[10:11], v[116:117] neg_lo:[0,1] neg_hi:[0,1]
	v_pk_add_f32 v[12:13], v[12:13], v[116:117] neg_lo:[0,1] neg_hi:[0,1]
	v_pk_add_f32 v[14:15], v[14:15], v[116:117] neg_lo:[0,1] neg_hi:[0,1]
	v_pk_mul_f32 v[66:67], v[0:1], v[0:1]
	v_pk_mul_f32 v[68:69], v[2:3], v[2:3]
	v_pk_fma_f32 v[66:67], v[4:5], v[4:5], v[66:67]
	v_pk_fma_f32 v[68:69], v[6:7], v[6:7], v[68:69]
	v_pk_fma_f32 v[66:67], v[8:9], v[8:9], v[66:67]
	v_pk_fma_f32 v[68:69], v[10:11], v[10:11], v[68:69]
	v_pk_fma_f32 v[66:67], v[12:13], v[12:13], v[66:67]
	v_pk_fma_f32 v[68:69], v[14:15], v[14:15], v[68:69]
	v_pk_add_f32 v[66:67], v[66:67], v[68:69]
	v_add_f32_e32 v66, v66, v67
	s_nop 1
	v_add_f32_dpp v66, v66, v66 row_shr:1 row_mask:0xf bank_mask:0xf bound_ctrl:1
	s_nop 1
	v_add_f32_dpp v66, v66, v66 row_shr:2 row_mask:0xf bank_mask:0xf bound_ctrl:1
	s_nop 1
	v_add_f32_dpp v66, v66, v66 row_shr:4 row_mask:0xf bank_mask:0xf bound_ctrl:1
	s_nop 1
	v_add_f32_dpp v66, v66, v66 row_shr:8 row_mask:0xf bank_mask:0xf bound_ctrl:1
	s_nop 0
	v_readlane_b32 s9, v66, 15
	v_readlane_b32 s10, v66, 31
	v_readlane_b32 s11, v66, 47
	v_readlane_b32 vcc_lo, v66, 63
	s_nop 1
	v_mov_b32_e32 v66, s9
	v_add_f32_e32 v66, s10, v66
	v_add_f32_e32 v66, s11, v66
	v_add_f32_e32 v66, vcc_lo, v66
	v_mul_f32_e32 v66, 0x3a800000, v66
	v_add_f32_e32 v66, 0x3727c5ac, v66
	v_rsq_f32_e32 v118, v66
	s_nop 0
	v_mov_b32_e32 v119, v118
	v_pk_mul_f32 v[0:1], v[0:1], v[118:119]
	v_pk_mul_f32 v[2:3], v[2:3], v[118:119]
	v_pk_mul_f32 v[4:5], v[4:5], v[118:119]
	v_pk_mul_f32 v[6:7], v[6:7], v[118:119]
	v_pk_mul_f32 v[8:9], v[8:9], v[118:119]
	v_pk_mul_f32 v[10:11], v[10:11], v[118:119]
	v_pk_mul_f32 v[12:13], v[12:13], v[118:119]
	v_pk_mul_f32 v[14:15], v[14:15], v[118:119]
	v_pk_fma_f32 v[76:77], v[0:1], v[34:35], v[50:51]
	v_pk_fma_f32 v[78:79], v[2:3], v[36:37], v[52:53]
	v_pk_fma_f32 v[80:81], v[4:5], v[38:39], v[54:55]
	v_pk_fma_f32 v[82:83], v[6:7], v[40:41], v[56:57]
	v_pk_fma_f32 v[84:85], v[8:9], v[42:43], v[58:59]
	v_pk_fma_f32 v[86:87], v[10:11], v[44:45], v[60:61]
	v_pk_fma_f32 v[88:89], v[12:13], v[46:47], v[62:63]
	v_pk_fma_f32 v[90:91], v[14:15], v[48:49], v[64:65]
	v_cvt_pk_bf16_f32 v92, v76, v77
	v_cvt_pk_bf16_f32 v93, v78, v79
	v_cvt_pk_bf16_f32 v94, v80, v81
	v_cvt_pk_bf16_f32 v95, v82, v83
	v_cvt_pk_bf16_f32 v96, v84, v85
	v_cvt_pk_bf16_f32 v97, v86, v87
	v_cvt_pk_bf16_f32 v98, v88, v89
	v_cvt_pk_bf16_f32 v99, v90, v91
	global_store_dwordx2 v115, v[92:93], s[2:3] offset:0
	global_store_dwordx2 v115, v[94:95], s[2:3] offset:512
	global_store_dwordx2 v115, v[96:97], s[2:3] offset:1024
	global_store_dwordx2 v115, v[98:99], s[2:3] offset:1536
	s_add_u32 s2, s2, 0x80000
	s_addc_u32 s3, s3, 0
	s_waitcnt vmcnt(4)
	v_pk_add_f32 v[66:67], v[18:19], v[20:21]
	v_pk_add_f32 v[68:69], v[22:23], v[24:25]
	v_pk_add_f32 v[70:71], v[26:27], v[28:29]
	v_pk_add_f32 v[72:73], v[30:31], v[32:33]
	v_pk_add_f32 v[66:67], v[66:67], v[68:69]
	v_pk_add_f32 v[70:71], v[70:71], v[72:73]
	v_pk_add_f32 v[66:67], v[66:67], v[70:71]
	v_add_f32_e32 v66, v66, v67
	s_nop 1
	v_add_f32_dpp v66, v66, v66 row_shr:1 row_mask:0xf bank_mask:0xf bound_ctrl:1
	s_nop 1
	v_add_f32_dpp v66, v66, v66 row_shr:2 row_mask:0xf bank_mask:0xf bound_ctrl:1
	s_nop 1
	v_add_f32_dpp v66, v66, v66 row_shr:4 row_mask:0xf bank_mask:0xf bound_ctrl:1
	s_nop 1
	v_add_f32_dpp v66, v66, v66 row_shr:8 row_mask:0xf bank_mask:0xf bound_ctrl:1
	s_nop 0
	v_readlane_b32 s9, v66, 15
	v_readlane_b32 s10, v66, 31
	v_readlane_b32 s11, v66, 47
	v_readlane_b32 vcc_lo, v66, 63
	s_nop 1
	v_mov_b32_e32 v66, s9
	v_add_f32_e32 v66, s10, v66
	v_add_f32_e32 v66, s11, v66
	v_add_f32_e32 v66, vcc_lo, v66
	v_mul_f32_e32 v116, 0x3a800000, v66
	v_mov_b32_e32 v117, v116
	v_pk_add_f32 v[18:19], v[18:19], v[116:117] neg_lo:[0,1] neg_hi:[0,1]
	v_pk_add_f32 v[20:21], v[20:21], v[116:117] neg_lo:[0,1] neg_hi:[0,1]
	v_pk_add_f32 v[22:23], v[22:23], v[116:117] neg_lo:[0,1] neg_hi:[0,1]
	v_pk_add_f32 v[24:25], v[24:25], v[116:117] neg_lo:[0,1] neg_hi:[0,1]
	v_pk_add_f32 v[26:27], v[26:27], v[116:117] neg_lo:[0,1] neg_hi:[0,1]
	v_pk_add_f32 v[28:29], v[28:29], v[116:117] neg_lo:[0,1] neg_hi:[0,1]
	v_pk_add_f32 v[30:31], v[30:31], v[116:117] neg_lo:[0,1] neg_hi:[0,1]
	v_pk_add_f32 v[32:33], v[32:33], v[116:117] neg_lo:[0,1] neg_hi:[0,1]
	v_pk_mul_f32 v[66:67], v[18:19], v[18:19]
; __device__ __forceinline__ void phase_ln(float* R, const float* __restrict__ g, const float* __restrict__ b, bf16_t* xbf, float samp_scale, const float* __restrict__ part, int nsplit, bool f32_all) {
;     ...
;   for (int r = gw; r < MT; r += nw) {
;     float* row = R + (size_t)r * 1024;
;     f32x4 v[4];
; #pragma unroll
;     for (int i = 0; i < 4; ++i) v[i] = *(const f32x4*)(row + i * 256 + lane * 4);
;     if (r >= MP) {
;       for (int sp = 0; sp < nsplit; ++sp) {
;         const float* prow = part + ((size_t)sp * MS + (r - MP)) * 1024;
; #pragma unroll
;         for (int i = 0; i < 4; ++i) v[i] = v[i] + *(const f32x4*)(prow + i * 256 + lane * 4);
;       }
;     }
;     ...
; #pragma unroll
;     for (int i = 0; i < 4; ++i) {
;       const f32x4 y = v[i] * rstd * gv[i] + bv[i];
;       if (r >= MP) *(f32x4*)(row + i * 256 + lane * 4) = y * samp_scale;
;       else if (f32_all) *(f32x4*)(row + i * 256 + lane * 4) = y;
;       if (xbf) {
;         u32x2 wv;
;         wv[0] = cvt_pk_bf16(y[0], y[1]); wv[1] = cvt_pk_bf16(y[2], y[3]);
;         *(u32x2*)(xbf + (size_t)r * 1024 + i * 256 + lane * 4) = wv;
;       }
;     }
	v_pk_mul_f32 v[68:69], v[20:21], v[20:21]
	v_pk_fma_f32 v[66:67], v[22:23], v[22:23], v[66:67]
	v_pk_fma_f32 v[68:69], v[24:25], v[24:25], v[68:69]
	v_pk_fma_f32 v[66:67], v[26:27], v[26:27], v[66:67]
	v_pk_fma_f32 v[68:69], v[28:29], v[28:29], v[68:69]
	v_pk_fma_f32 v[66:67], v[30:31], v[30:31], v[66:67]
	v_pk_fma_f32 v[68:69], v[32:33], v[32:33], v[68:69]
	v_pk_add_f32 v[66:67], v[66:67], v[68:69]
	v_add_f32_e32 v66, v66, v67
	s_nop 1
	v_add_f32_dpp v66, v66, v66 row_shr:1 row_mask:0xf bank_mask:0xf bound_ctrl:1
	s_nop 1
	v_add_f32_dpp v66, v66, v66 row_shr:2 row_mask:0xf bank_mask:0xf bound_ctrl:1
	s_nop 1
	v_add_f32_dpp v66, v66, v66 row_shr:4 row_mask:0xf bank_mask:0xf bound_ctrl:1
	s_nop 1
	v_add_f32_dpp v66, v66, v66 row_shr:8 row_mask:0xf bank_mask:0xf bound_ctrl:1
	s_nop 0
	v_readlane_b32 s9, v66, 15
	v_readlane_b32 s10, v66, 31
	v_readlane_b32 s11, v66, 47
	v_readlane_b32 vcc_lo, v66, 63
	s_nop 1
	v_mov_b32_e32 v66, s9
	v_add_f32_e32 v66, s10, v66
	v_add_f32_e32 v66, s11, v66
	v_add_f32_e32 v66, vcc_lo, v66
	v_mul_f32_e32 v66, 0x3a800000, v66
	v_add_f32_e32 v66, 0x3727c5ac, v66
	v_rsq_f32_e32 v118, v66
	s_nop 0
	v_mov_b32_e32 v119, v118
	v_pk_mul_f32 v[18:19], v[18:19], v[118:119]
	v_pk_mul_f32 v[20:21], v[20:21], v[118:119]
	v_pk_mul_f32 v[22:23], v[22:23], v[118:119]
	v_pk_mul_f32 v[24:25], v[24:25], v[118:119]
	v_pk_mul_f32 v[26:27], v[26:27], v[118:119]
	v_pk_mul_f32 v[28:29], v[28:29], v[118:119]
	v_pk_mul_f32 v[30:31], v[30:31], v[118:119]
	v_pk_mul_f32 v[32:33], v[32:33], v[118:119]
	v_pk_fma_f32 v[76:77], v[18:19], v[34:35], v[50:51]
	v_pk_fma_f32 v[78:79], v[20:21], v[36:37], v[52:53]
	v_pk_fma_f32 v[80:81], v[22:23], v[38:39], v[54:55]
	v_pk_fma_f32 v[82:83], v[24:25], v[40:41], v[56:57]
	v_pk_fma_f32 v[84:85], v[26:27], v[42:43], v[58:59]
	v_pk_fma_f32 v[86:87], v[28:29], v[44:45], v[60:61]
	v_pk_fma_f32 v[88:89], v[30:31], v[46:47], v[62:63]
	v_pk_fma_f32 v[90:91], v[32:33], v[48:49], v[64:65]
	v_cvt_pk_bf16_f32 v92, v76, v77
	v_cvt_pk_bf16_f32 v93, v78, v79
	v_cvt_pk_bf16_f32 v94, v80, v81
	v_cvt_pk_bf16_f32 v95, v82, v83
	v_cvt_pk_bf16_f32 v96, v84, v85
	v_cvt_pk_bf16_f32 v97, v86, v87
	v_cvt_pk_bf16_f32 v98, v88, v89
	v_cvt_pk_bf16_f32 v99, v90, v91
	global_store_dwordx2 v115, v[92:93], s[2:3] offset:0
	global_store_dwordx2 v115, v[94:95], s[2:3] offset:512
	global_store_dwordx2 v115, v[96:97], s[2:3] offset:1024
	global_store_dwordx2 v115, v[98:99], s[2:3] offset:1536
	s_add_u32 s2, s2, 0x80000
	s_addc_u32 s3, s3, 0
	v_readfirstlane_b32 s10, v244
	v_readlane_b32 s9, v254, 6
	s_lshr_b32 s10, s10, 6
	s_cmp_ge_u32 s10, 2
	s_cbranch_scc1 .Lln1_done
	s_lshl_b32 s9, s9, 1
	s_add_i32 s9, s9, s10
	s_lshl_b32 s11, s9, 12
	s_add_u32 s11, s11, 0x8000000
	s_add_u32 s0, s4, s11
	s_addc_u32 s1, s5, 0
	s_lshl_b32 s11, s9, 11
	s_add_u32 s11, s11, 0x79c0000
	s_add_u32 s2, s6, s11
	s_addc_u32 s3, s7, 0
	s_lshl_b32 s11, s9, 12
	s_add_u32 s11, s11, 0x1e482000
	s_add_u32 s10, s6, s11
	s_addc_u32 s11, s7, 0
	global_load_dwordx4 v[0:3], v114, s[0:1] offset:0
	global_load_dwordx4 v[4:7], v114, s[0:1] offset:1024
	global_load_dwordx4 v[8:11], v114, s[0:1] offset:2048
	global_load_dwordx4 v[12:15], v114, s[0:1] offset:3072
	global_load_dwordx4 v[18:21], v114, s[10:11] offset:0
	global_load_dwordx4 v[22:25], v114, s[10:11] offset:1024
	global_load_dwordx4 v[26:29], v114, s[10:11] offset:2048
	global_load_dwordx4 v[30:33], v114, s[10:11] offset:3072
	s_add_u32 s10, s10, 0x200000
	s_addc_u32 s11, s11, 0
	global_load_dwordx4 v[66:69], v114, s[10:11] offset:0
	global_load_dwordx4 v[70:73], v114, s[10:11] offset:1024
	global_load_dwordx4 v[74:77], v114, s[10:11] offset:2048
	global_load_dwordx4 v[78:81], v114, s[10:11] offset:3072
	s_add_u32 s10, s10, 0x200000
	s_addc_u32 s11, s11, 0
	global_load_dwordx4 v[82:85], v114, s[10:11] offset:0
	global_load_dwordx4 v[86:89], v114, s[10:11] offset:1024
	global_load_dwordx4 v[90:93], v114, s[10:11] offset:2048
	global_load_dwordx4 v[94:97], v114, s[10:11] offset:3072
	s_add_u32 s10, s10, 0x200000
	s_addc_u32 s11, s11, 0
	global_load_dwordx4 v[98:101], v114, s[10:11] offset:0
	global_load_dwordx4 v[102:105], v114, s[10:11] offset:1024
	global_load_dwordx4 v[106:109], v114, s[10:11] offset:2048
	global_load_dwordx4 v[110:113], v114, s[10:11] offset:3072
	s_add_u32 s10, s10, 0x200000
	s_addc_u32 s11, s11, 0
	s_waitcnt vmcnt(0)
; __device__ __forceinline__ void phase_ln(float* R, const float* __restrict__ g, const float* __restrict__ b, bf16_t* xbf, float samp_scale, const float* __restrict__ part, int nsplit, bool f32_all) {
;     ...
;       for (int sp = 0; sp < nsplit; ++sp) {
;         const float* prow = part + ((size_t)sp * MS + (r - MP)) * 1024;
; #pragma unroll
;         for (int i = 0; i < 4; ++i) v[i] = v[i] + *(const f32x4*)(prow + i * 256 + lane * 4);
;       }
;     }
;     float s = 0.f;
; #pragma unroll
;     for (int i = 0; i < 4; ++i) s += v[i][0] + v[i][1] + v[i][2] + v[i][3];
; #pragma unroll
;     for (int o = 32; o >= 1; o >>= 1) s += __shfl_xor(s, o);
;     const float mean = s * (1.f / 1024.f);
;     float ss = 0.f;
; #pragma unroll
;     for (int i = 0; i < 4; ++i) { v[i] = v[i] - mean; ss += v[i][0] * v[i][0] + v[i][1] * v[i][1] + v[i][2] * v[i][2] + v[i][3] * v[i][3]; }
; #pragma unroll
;     for (int o = 32; o >= 1; o >>= 1) ss += __shfl_xor(ss, o);
;     const float rstd = rsqrtf(ss * (1.f / 1024.f) + LN_EPS);
; #pragma unroll
;     for (int i = 0; i < 4; ++i) {
;       const f32x4 y = v[i] * rstd * gv[i] + bv[i];
;       if (r >= MP) *(f32x4*)(row + i * 256 + lane * 4) = y * samp_scale;
;       else if (f32_all) *(f32x4*)(row + i * 256 + lane * 4) = y;
;       if (xbf) {
;         u32x2 wv;
;         wv[0] = cvt_pk_bf16(y[0], y[1]); wv[1] = cvt_pk_bf16(y[2], y[3]);
;         *(u32x2*)(xbf + (size_t)r * 1024 + i * 256 + lane * 4) = wv;
;       }
;     }
	v_pk_add_f32 v[0:1], v[0:1], v[18:19]
	v_pk_add_f32 v[2:3], v[2:3], v[20:21]
	v_pk_add_f32 v[4:5], v[4:5], v[22:23]
	v_pk_add_f32 v[6:7], v[6:7], v[24:25]
	v_pk_add_f32 v[8:9], v[8:9], v[26:27]
	v_pk_add_f32 v[10:11], v[10:11], v[28:29]
	v_pk_add_f32 v[12:13], v[12:13], v[30:31]
	v_pk_add_f32 v[14:15], v[14:15], v[32:33]
	v_pk_add_f32 v[0:1], v[0:1], v[66:67]
	v_pk_add_f32 v[2:3], v[2:3], v[68:69]
	v_pk_add_f32 v[4:5], v[4:5], v[70:71]
	v_pk_add_f32 v[6:7], v[6:7], v[72:73]
	v_pk_add_f32 v[8:9], v[8:9], v[74:75]
	v_pk_add_f32 v[10:11], v[10:11], v[76:77]
	v_pk_add_f32 v[12:13], v[12:13], v[78:79]
	v_pk_add_f32 v[14:15], v[14:15], v[80:81]
	v_pk_add_f32 v[0:1], v[0:1], v[82:83]
	v_pk_add_f32 v[2:3], v[2:3], v[84:85]
	v_pk_add_f32 v[4:5], v[4:5], v[86:87]
	v_pk_add_f32 v[6:7], v[6:7], v[88:89]
	v_pk_add_f32 v[8:9], v[8:9], v[90:91]
	v_pk_add_f32 v[10:11], v[10:11], v[92:93]
	v_pk_add_f32 v[12:13], v[12:13], v[94:95]
	v_pk_add_f32 v[14:15], v[14:15], v[96:97]
	v_pk_add_f32 v[0:1], v[0:1], v[98:99]
	v_pk_add_f32 v[2:3], v[2:3], v[100:101]
	v_pk_add_f32 v[4:5], v[4:5], v[102:103]
	v_pk_add_f32 v[6:7], v[6:7], v[104:105]
	v_pk_add_f32 v[8:9], v[8:9], v[106:107]
	v_pk_add_f32 v[10:11], v[10:11], v[108:109]
	v_pk_add_f32 v[12:13], v[12:13], v[110:111]
	v_pk_add_f32 v[14:15], v[14:15], v[112:113]
	v_pk_add_f32 v[66:67], v[0:1], v[2:3]
	v_pk_add_f32 v[68:69], v[4:5], v[6:7]
	v_pk_add_f32 v[70:71], v[8:9], v[10:11]
	v_pk_add_f32 v[72:73], v[12:13], v[14:15]
	v_pk_add_f32 v[66:67], v[66:67], v[68:69]
	v_pk_add_f32 v[70:71], v[70:71], v[72:73]
	v_pk_add_f32 v[66:67], v[66:67], v[70:71]
	v_add_f32_e32 v66, v66, v67
	s_nop 1
	v_add_f32_dpp v66, v66, v66 row_shr:1 row_mask:0xf bank_mask:0xf bound_ctrl:1
	s_nop 1
	v_add_f32_dpp v66, v66, v66 row_shr:2 row_mask:0xf bank_mask:0xf bound_ctrl:1
	s_nop 1
	v_add_f32_dpp v66, v66, v66 row_shr:4 row_mask:0xf bank_mask:0xf bound_ctrl:1
	s_nop 1
	v_add_f32_dpp v66, v66, v66 row_shr:8 row_mask:0xf bank_mask:0xf bound_ctrl:1
	s_nop 0
	v_readlane_b32 s9, v66, 15
	v_readlane_b32 s10, v66, 31
	v_readlane_b32 s11, v66, 47
	v_readlane_b32 vcc_lo, v66, 63
	s_nop 1
	v_mov_b32_e32 v66, s9
	v_add_f32_e32 v66, s10, v66
	v_add_f32_e32 v66, s11, v66
	v_add_f32_e32 v66, vcc_lo, v66
	v_mul_f32_e32 v116, 0x3a800000, v66
	v_mov_b32_e32 v117, v116
	v_pk_add_f32 v[0:1], v[0:1], v[116:117] neg_lo:[0,1] neg_hi:[0,1]
	v_pk_add_f32 v[2:3], v[2:3], v[116:117] neg_lo:[0,1] neg_hi:[0,1]
	v_pk_add_f32 v[4:5], v[4:5], v[116:117] neg_lo:[0,1] neg_hi:[0,1]
	v_pk_add_f32 v[6:7], v[6:7], v[116:117] neg_lo:[0,1] neg_hi:[0,1]
	v_pk_add_f32 v[8:9], v[8:9], v[116:117] neg_lo:[0,1] neg_hi:[0,1]
	v_pk_add_f32 v[10:11], v[10:11], v[116:117] neg_lo:[0,1] neg_hi:[0,1]
	v_pk_add_f32 v[12:13], v[12:13], v[116:117] neg_lo:[0,1] neg_hi:[0,1]
	v_pk_add_f32 v[14:15], v[14:15], v[116:117] neg_lo:[0,1] neg_hi:[0,1]
	v_pk_mul_f32 v[66:67], v[0:1], v[0:1]
	v_pk_mul_f32 v[68:69], v[2:3], v[2:3]
	v_pk_fma_f32 v[66:67], v[4:5], v[4:5], v[66:67]
	v_pk_fma_f32 v[68:69], v[6:7], v[6:7], v[68:69]
	v_pk_fma_f32 v[66:67], v[8:9], v[8:9], v[66:67]
	v_pk_fma_f32 v[68:69], v[10:11], v[10:11], v[68:69]
	v_pk_fma_f32 v[66:67], v[12:13], v[12:13], v[66:67]
	v_pk_fma_f32 v[68:69], v[14:15], v[14:15], v[68:69]
	v_pk_add_f32 v[66:67], v[66:67], v[68:69]
	v_add_f32_e32 v66, v66, v67
	s_nop 1
	v_add_f32_dpp v66, v66, v66 row_shr:1 row_mask:0xf bank_mask:0xf bound_ctrl:1
	s_nop 1
	v_add_f32_dpp v66, v66, v66 row_shr:2 row_mask:0xf bank_mask:0xf bound_ctrl:1
	s_nop 1
	v_add_f32_dpp v66, v66, v66 row_shr:4 row_mask:0xf bank_mask:0xf bound_ctrl:1
	s_nop 1
	v_add_f32_dpp v66, v66, v66 row_shr:8 row_mask:0xf bank_mask:0xf bound_ctrl:1
	s_nop 0
	v_readlane_b32 s9, v66, 15
	v_readlane_b32 s10, v66, 31
	v_readlane_b32 s11, v66, 47
	v_readlane_b32 vcc_lo, v66, 63
	s_nop 1
	v_mov_b32_e32 v66, s9
	v_add_f32_e32 v66, s10, v66
	v_add_f32_e32 v66, s11, v66
	v_add_f32_e32 v66, vcc_lo, v66
	v_mul_f32_e32 v66, 0x3a800000, v66
	v_add_f32_e32 v66, 0x3727c5ac, v66
	v_rsq_f32_e32 v118, v66
	s_nop 0
	v_mov_b32_e32 v119, v118
	v_pk_mul_f32 v[0:1], v[0:1], v[118:119]
	v_pk_mul_f32 v[2:3], v[2:3], v[118:119]
	v_pk_mul_f32 v[4:5], v[4:5], v[118:119]
	v_pk_mul_f32 v[6:7], v[6:7], v[118:119]
	v_pk_mul_f32 v[8:9], v[8:9], v[118:119]
	v_pk_mul_f32 v[10:11], v[10:11], v[118:119]
	v_pk_mul_f32 v[12:13], v[12:13], v[118:119]
	v_pk_mul_f32 v[14:15], v[14:15], v[118:119]
	v_pk_fma_f32 v[76:77], v[0:1], v[34:35], v[50:51]
	v_pk_fma_f32 v[78:79], v[2:3], v[36:37], v[52:53]
	v_pk_fma_f32 v[80:81], v[4:5], v[38:39], v[54:55]
	v_pk_fma_f32 v[82:83], v[6:7], v[40:41], v[56:57]
	v_pk_fma_f32 v[84:85], v[8:9], v[42:43], v[58:59]
	v_pk_fma_f32 v[86:87], v[10:11], v[44:45], v[60:61]
	v_pk_fma_f32 v[88:89], v[12:13], v[46:47], v[62:63]
	v_pk_fma_f32 v[90:91], v[14:15], v[48:49], v[64:65]
	s_mov_b32 s9, 0x3fb504f3
	v_mov_b32_e32 v120, s9
	v_mov_b32_e32 v121, s9
	v_pk_mul_f32 v[0:1], v[76:77], v[120:121]
	v_pk_mul_f32 v[2:3], v[78:79], v[120:121]
	v_pk_mul_f32 v[4:5], v[80:81], v[120:121]
	v_pk_mul_f32 v[6:7], v[82:83], v[120:121]
	v_pk_mul_f32 v[8:9], v[84:85], v[120:121]
	v_pk_mul_f32 v[10:11], v[86:87], v[120:121]
	v_pk_mul_f32 v[12:13], v[88:89], v[120:121]
	v_pk_mul_f32 v[14:15], v[90:91], v[120:121]
	global_store_dwordx4 v114, v[0:3], s[0:1] offset:0
	global_store_dwordx4 v114, v[4:7], s[0:1] offset:1024
	global_store_dwordx4 v114, v[8:11], s[0:1] offset:2048
	global_store_dwordx4 v114, v[12:15], s[0:1] offset:3072
	v_cvt_pk_bf16_f32 v92, v76, v77
	v_cvt_pk_bf16_f32 v93, v78, v79
	v_cvt_pk_bf16_f32 v94, v80, v81
	v_cvt_pk_bf16_f32 v95, v82, v83
	v_cvt_pk_bf16_f32 v96, v84, v85
	v_cvt_pk_bf16_f32 v97, v86, v87
	v_cvt_pk_bf16_f32 v98, v88, v89
	v_cvt_pk_bf16_f32 v99, v90, v91
	global_store_dwordx2 v115, v[92:93], s[2:3] offset:0
	global_store_dwordx2 v115, v[94:95], s[2:3] offset:512
	global_store_dwordx2 v115, v[96:97], s[2:3] offset:1024
	global_store_dwordx2 v115, v[98:99], s[2:3] offset:1536

; __device__ __forceinline__ int otid() { int t = threadIdx.x; asm volatile("" : "+v"(t)); return t; }
; __device__ __forceinline__ void phase_ln(float* R, const float* __restrict__ g, const float* __restrict__ b, bf16_t* xbf, float samp_scale, const float* __restrict__ part, int nsplit, bool f32_all) {
;   const int tid = otid(), lane = tid & 63, gw = blockIdx.x * 8 + (tid >> 6), nw = gridDim.x * 8;
;   f32x4 gv[4], bv[4];
; #pragma unroll
;   for (int i = 0; i < 4; ++i) { gv[i] = *(const f32x4*)(g + i * 256 + lane * 4); bv[i] = *(const f32x4*)(b + i * 256 + lane * 4); }
;   for (int r = gw; r < MT; r += nw) {
;     float* row = R + (size_t)r * 1024;
;     f32x4 v[4];
; #pragma unroll
;     for (int i = 0; i < 4; ++i) v[i] = *(const f32x4*)(row + i * 256 + lane * 4);
;     if (r >= MP) {
;       for (int sp = 0; sp < nsplit; ++sp) {
;         const float* prow = part + ((size_t)sp * MS + (r - MP)) * 1024;
; #pragma unroll
;         for (int i = 0; i < 4; ++i) v[i] = v[i] + *(const f32x4*)(prow + i * 256 + lane * 4);
;       }
;     }
;     float s = 0.f;
; #pragma unroll
;     for (int i = 0; i < 4; ++i) s += v[i][0] + v[i][1] + v[i][2] + v[i][3];
; #pragma unroll
;     for (int o = 32; o >= 1; o >>= 1) s += __shfl_xor(s, o);
;     const float mean = s * (1.f / 1024.f);
;     float ss = 0.f;
; #pragma unroll
;     for (int i = 0; i < 4; ++i) { v[i] = v[i] - mean; ss += v[i][0] * v[i][0] + v[i][1] * v[i][1] + v[i][2] * v[i][2] + v[i][3] * v[i][3]; }
; #pragma unroll
;     for (int o = 32; o >= 1; o >>= 1) ss += __shfl_xor(ss, o);
;     const float rstd = rsqrtf(ss * (1.f / 1024.f) + LN_EPS);
; #pragma unroll
;     for (int i = 0; i < 4; ++i) {
;       const f32x4 y = v[i] * rstd * gv[i] + bv[i];
;       if (r >= MP) *(f32x4*)(row + i * 256 + lane * 4) = y * samp_scale;
;       else if (f32_all) *(f32x4*)(row + i * 256 + lane * 4) = y;
;       if (xbf) {
;         u32x2 wv;
;         wv[0] = cvt_pk_bf16(y[0], y[1]); wv[1] = cvt_pk_bf16(y[2], y[3]);
;         *(u32x2*)(xbf + (size_t)r * 1024 + i * 256 + lane * 4) = wv;
;       }
;     }
.LBB0_3944:
	s_or_b64 exec, exec, s[0:1]
	v_readlane_b32 s0, v254, 51
	s_nop 0
	s_cmp_lg_u32 s0, 0
	s_cbranch_scc1 .Lln2_orig
	v_readlane_b32 s6, v254, 2
	v_readlane_b32 s7, v254, 3
	v_readlane_b32 s8, v255, 22
	s_waitcnt lgkmcnt(0)
	s_barrier
	s_load_dwordx4 s[0:3], s[6:7], 0x98
	s_load_dwordx4 s[4:7], s[6:7], 0xa8
	v_readlane_b32 s9, v254, 15
	v_readfirstlane_b32 s10, v244
	v_lshlrev_b32_e32 v114, 4, v252
	v_lshlrev_b32_e32 v115, 3, v252
	s_lshr_b32 s10, s10, 6
	s_lshr_b32 s9, s9, 3
	s_and_b32 s11, s9, 7
	s_lshl_b32 s11, s11, 12
	s_lshr_b32 s9, s9, 3
	s_lshl_b32 s9, s9, 3
	s_add_i32 s9, s9, s11
	s_add_i32 s9, s9, s10
	s_lshl_b32 s11, s8, 12
	s_waitcnt lgkmcnt(0)
	s_add_u32 s0, s0, s11
	s_addc_u32 s1, s1, 0
	s_add_u32 s2, s2, s11
	s_addc_u32 s3, s3, 0
	global_load_dwordx4 v[34:37], v114, s[0:1] offset:0
	global_load_dwordx4 v[38:41], v114, s[0:1] offset:1024
	global_load_dwordx4 v[42:45], v114, s[0:1] offset:2048
	global_load_dwordx4 v[46:49], v114, s[0:1] offset:3072
	global_load_dwordx4 v[50:53], v114, s[2:3] offset:0
	global_load_dwordx4 v[54:57], v114, s[2:3] offset:1024
	global_load_dwordx4 v[58:61], v114, s[2:3] offset:2048
	global_load_dwordx4 v[62:65], v114, s[2:3] offset:3072
	s_lshl_b32 s11, s9, 12
	s_add_u32 s0, s4, s11
	s_addc_u32 s1, s5, 0
	s_lshl_b32 s11, s9, 11
	s_add_u32 s11, s11, 0x39c0000
	s_add_u32 s2, s6, s11
	s_addc_u32 s3, s7, 0
	global_load_dwordx4 v[0:3], v114, s[0:1] offset:0
	global_load_dwordx4 v[4:7], v114, s[0:1] offset:1024
	global_load_dwordx4 v[8:11], v114, s[0:1] offset:2048
	global_load_dwordx4 v[12:15], v114, s[0:1] offset:3072
	s_add_u32 s0, s0, 0x100000
	s_addc_u32 s1, s1, 0
	global_load_dwordx4 v[18:21], v114, s[0:1] offset:0
	global_load_dwordx4 v[22:25], v114, s[0:1] offset:1024
	global_load_dwordx4 v[26:29], v114, s[0:1] offset:2048
	global_load_dwordx4 v[30:33], v114, s[0:1] offset:3072
	s_waitcnt vmcnt(4)
	v_pk_add_f32 v[66:67], v[0:1], v[2:3]
	v_pk_add_f32 v[68:69], v[4:5], v[6:7]
	v_pk_add_f32 v[70:71], v[8:9], v[10:11]
	v_pk_add_f32 v[72:73], v[12:13], v[14:15]
	v_pk_add_f32 v[66:67], v[66:67], v[68:69]
	v_pk_add_f32 v[70:71], v[70:71], v[72:73]
	v_pk_add_f32 v[66:67], v[66:67], v[70:71]
	v_add_f32_e32 v66, v66, v67
	s_nop 1
	v_add_f32_dpp v66, v66, v66 row_shr:1 row_mask:0xf bank_mask:0xf bound_ctrl:1
	s_nop 1
	v_add_f32_dpp v66, v66, v66 row_shr:2 row_mask:0xf bank_mask:0xf bound_ctrl:1
	s_nop 1
	v_add_f32_dpp v66, v66, v66 row_shr:4 row_mask:0xf bank_mask:0xf bound_ctrl:1
	s_nop 1
	v_add_f32_dpp v66, v66, v66 row_shr:8 row_mask:0xf bank_mask:0xf bound_ctrl:1
	s_nop 0
	v_readlane_b32 s9, v66, 15
	v_readlane_b32 s10, v66, 31
	v_readlane_b32 s11, v66, 47
	v_readlane_b32 vcc_lo, v66, 63
	s_nop 1
	v_mov_b32_e32 v66, s9
	v_add_f32_e32 v66, s10, v66
	v_add_f32_e32 v66, s11, v66
	v_add_f32_e32 v66, vcc_lo, v66
	v_mul_f32_e32 v116, 0x3a800000, v66
	v_mov_b32_e32 v117, v116
	v_pk_add_f32 v[0:1], v[0:1], v[116:117] neg_lo:[0,1] neg_hi:[0,1]
	v_pk_add_f32 v[2:3], v[2:3], v[116:117] neg_lo:[0,1] neg_hi:[0,1]
	v_pk_add_f32 v[4:5], v[4:5], v[116:117] neg_lo:[0,1] neg_hi:[0,1]
	v_pk_add_f32 v[6:7], v[6:7], v[116:117] neg_lo:[0,1] neg_hi:[0,1]
	v_pk_add_f32 v[8:9], v[8:9], v[116:117] neg_lo:[0,1] neg_hi:[0,1]
	v_pk_add_f32 v[10:11], v[10:11], v[116:117] neg_lo:[0,1] neg_hi:[0,1]
	v_pk_add_f32 v[12:13], v[12:13], v[116:117] neg_lo:[0,1] neg_hi:[0,1]
	v_pk_add_f32 v[14:15], v[14:15], v[116:117] neg_lo:[0,1] neg_hi:[0,1]
	v_pk_mul_f32 v[66:67], v[0:1], v[0:1]
	v_pk_mul_f32 v[68:69], v[2:3], v[2:3]
	v_pk_fma_f32 v[66:67], v[4:5], v[4:5], v[66:67]
	v_pk_fma_f32 v[68:69], v[6:7], v[6:7], v[68:69]
	v_pk_fma_f32 v[66:67], v[8:9], v[8:9], v[66:67]
	v_pk_fma_f32 v[68:69], v[10:11], v[10:11], v[68:69]
	v_pk_fma_f32 v[66:67], v[12:13], v[12:13], v[66:67]
	v_pk_fma_f32 v[68:69], v[14:15], v[14:15], v[68:69]
	v_pk_add_f32 v[66:67], v[66:67], v[68:69]
	v_add_f32_e32 v66, v66, v67
	s_nop 1
	v_add_f32_dpp v66, v66, v66 row_shr:1 row_mask:0xf bank_mask:0xf bound_ctrl:1
	s_nop 1
	v_add_f32_dpp v66, v66, v66 row_shr:2 row_mask:0xf bank_mask:0xf bound_ctrl:1
	s_nop 1
	v_add_f32_dpp v66, v66, v66 row_shr:4 row_mask:0xf bank_mask:0xf bound_ctrl:1
	s_nop 1
	v_add_f32_dpp v66, v66, v66 row_shr:8 row_mask:0xf bank_mask:0xf bound_ctrl:1
	s_nop 0
	v_readlane_b32 s9, v66, 15
	v_readlane_b32 s10, v66, 31
	v_readlane_b32 s11, v66, 47
	v_readlane_b32 vcc_lo, v66, 63
	s_nop 1
	v_mov_b32_e32 v66, s9
	v_add_f32_e32 v66, s10, v66
	v_add_f32_e32 v66, s11, v66
	v_add_f32_e32 v66, vcc_lo, v66
	v_mul_f32_e32 v66, 0x3a800000, v66
	v_add_f32_e32 v66, 0x3727c5ac, v66
	v_rsq_f32_e32 v118, v66
	s_nop 0
	v_mov_b32_e32 v119, v118
	v_pk_mul_f32 v[0:1], v[0:1], v[118:119]
	v_pk_mul_f32 v[2:3], v[2:3], v[118:119]
	v_pk_mul_f32 v[4:5], v[4:5], v[118:119]
	v_pk_mul_f32 v[6:7], v[6:7], v[118:119]
	v_pk_mul_f32 v[8:9], v[8:9], v[118:119]
	v_pk_mul_f32 v[10:11], v[10:11], v[118:119]
	v_pk_mul_f32 v[12:13], v[12:13], v[118:119]
	v_pk_mul_f32 v[14:15], v[14:15], v[118:119]
	v_pk_fma_f32 v[76:77], v[0:1], v[34:35], v[50:51]
	v_pk_fma_f32 v[78:79], v[2:3], v[36:37], v[52:53]
	v_pk_fma_f32 v[80:81], v[4:5], v[38:39], v[54:55]
	v_pk_fma_f32 v[82:83], v[6:7], v[40:41], v[56:57]
	v_pk_fma_f32 v[84:85], v[8:9], v[42:43], v[58:59]
	v_pk_fma_f32 v[86:87], v[10:11], v[44:45], v[60:61]
	v_pk_fma_f32 v[88:89], v[12:13], v[46:47], v[62:63]
	v_pk_fma_f32 v[90:91], v[14:15], v[48:49], v[64:65]
	s_cmp_lg_u32 s8, 0
	s_cbranch_scc1 .Lln2_f32_0
	v_cvt_pk_bf16_f32 v92, v76, v77
	v_cvt_pk_bf16_f32 v93, v78, v79
	v_cvt_pk_bf16_f32 v94, v80, v81
	v_cvt_pk_bf16_f32 v95, v82, v83
	v_cvt_pk_bf16_f32 v96, v84, v85
	v_cvt_pk_bf16_f32 v97, v86, v87
	v_cvt_pk_bf16_f32 v98, v88, v89
	v_cvt_pk_bf16_f32 v99, v90, v91
	global_store_dwordx2 v115, v[92:93], s[2:3] offset:0
	global_store_dwordx2 v115, v[94:95], s[2:3] offset:512
	global_store_dwordx2 v115, v[96:97], s[2:3] offset:1024
	global_store_dwordx2 v115, v[98:99], s[2:3] offset:1536
	s_branch .Lln2_st_0
; __device__ __forceinline__ void phase_ln(float* R, const float* __restrict__ g, const float* __restrict__ b, bf16_t* xbf, float samp_scale, const float* __restrict__ part, int nsplit, bool f32_all) {
;     ...
;   for (int r = gw; r < MT; r += nw) {
;     float* row = R + (size_t)r * 1024;
;     f32x4 v[4];
; #pragma unroll
;     for (int i = 0; i < 4; ++i) v[i] = *(const f32x4*)(row + i * 256 + lane * 4);
;     if (r >= MP) {
;       for (int sp = 0; sp < nsplit; ++sp) {
;         const float* prow = part + ((size_t)sp * MS + (r - MP)) * 1024;
; #pragma unroll
;         for (int i = 0; i < 4; ++i) v[i] = v[i] + *(const f32x4*)(prow + i * 256 + lane * 4);
;       }
;     }
;     float s = 0.f;
; #pragma unroll
;     for (int i = 0; i < 4; ++i) s += v[i][0] + v[i][1] + v[i][2] + v[i][3];
; #pragma unroll
;     for (int o = 32; o >= 1; o >>= 1) s += __shfl_xor(s, o);
;     const float mean = s * (1.f / 1024.f);
;     float ss = 0.f;
; #pragma unroll
;     for (int i = 0; i < 4; ++i) { v[i] = v[i] - mean; ss += v[i][0] * v[i][0] + v[i][1] * v[i][1] + v[i][2] * v[i][2] + v[i][3] * v[i][3]; }
; #pragma unroll
;     for (int o = 32; o >= 1; o >>= 1) ss += __shfl_xor(ss, o);
;     const float rstd = rsqrtf(ss * (1.f / 1024.f) + LN_EPS);
; #pragma unroll
;     for (int i = 0; i < 4; ++i) {
;       const f32x4 y = v[i] * rstd * gv[i] + bv[i];
;       if (r >= MP) *(f32x4*)(row + i * 256 + lane * 4) = y * samp_scale;
;       else if (f32_all) *(f32x4*)(row + i * 256 + lane * 4) = y;
;       if (xbf) {
;         u32x2 wv;
;         wv[0] = cvt_pk_bf16(y[0], y[1]); wv[1] = cvt_pk_bf16(y[2], y[3]);
;         *(u32x2*)(xbf + (size_t)r * 1024 + i * 256 + lane * 4) = wv;
;       }
;     }
.Lln2_f32_0:
	s_sub_u32 s10, s0, 0x100000
	s_subb_u32 s11, s1, 0
	global_store_dwordx4 v114, v[76:79], s[10:11] offset:0
	global_store_dwordx4 v114, v[80:83], s[10:11] offset:1024
	global_store_dwordx4 v114, v[84:87], s[10:11] offset:2048
	global_store_dwordx4 v114, v[88:91], s[10:11] offset:3072
.Lln2_st_0:
	s_add_u32 s2, s2, 0x80000
	s_addc_u32 s3, s3, 0
	s_add_u32 s0, s0, 0x100000
	s_addc_u32 s1, s1, 0
	global_load_dwordx4 v[0:3], v114, s[0:1] offset:0
	global_load_dwordx4 v[4:7], v114, s[0:1] offset:1024
	global_load_dwordx4 v[8:11], v114, s[0:1] offset:2048
	global_load_dwordx4 v[12:15], v114, s[0:1] offset:3072
	s_waitcnt vmcnt(8)
	v_pk_add_f32 v[66:67], v[18:19], v[20:21]
	v_pk_add_f32 v[68:69], v[22:23], v[24:25]
	v_pk_add_f32 v[70:71], v[26:27], v[28:29]
	v_pk_add_f32 v[72:73], v[30:31], v[32:33]
	v_pk_add_f32 v[66:67], v[66:67], v[68:69]
	v_pk_add_f32 v[70:71], v[70:71], v[72:73]
	v_pk_add_f32 v[66:67], v[66:67], v[70:71]
	v_add_f32_e32 v66, v66, v67
	s_nop 1
	v_add_f32_dpp v66, v66, v66 row_shr:1 row_mask:0xf bank_mask:0xf bound_ctrl:1
	s_nop 1
	v_add_f32_dpp v66, v66, v66 row_shr:2 row_mask:0xf bank_mask:0xf bound_ctrl:1
	s_nop 1
	v_add_f32_dpp v66, v66, v66 row_shr:4 row_mask:0xf bank_mask:0xf bound_ctrl:1
	s_nop 1
	v_add_f32_dpp v66, v66, v66 row_shr:8 row_mask:0xf bank_mask:0xf bound_ctrl:1
	s_nop 0
	v_readlane_b32 s9, v66, 15
	v_readlane_b32 s10, v66, 31
	v_readlane_b32 s11, v66, 47
	v_readlane_b32 vcc_lo, v66, 63
	s_nop 1
	v_mov_b32_e32 v66, s9
	v_add_f32_e32 v66, s10, v66
	v_add_f32_e32 v66, s11, v66
	v_add_f32_e32 v66, vcc_lo, v66
	v_mul_f32_e32 v116, 0x3a800000, v66
	v_mov_b32_e32 v117, v116
	v_pk_add_f32 v[18:19], v[18:19], v[116:117] neg_lo:[0,1] neg_hi:[0,1]
	v_pk_add_f32 v[20:21], v[20:21], v[116:117] neg_lo:[0,1] neg_hi:[0,1]
	v_pk_add_f32 v[22:23], v[22:23], v[116:117] neg_lo:[0,1] neg_hi:[0,1]
	v_pk_add_f32 v[24:25], v[24:25], v[116:117] neg_lo:[0,1] neg_hi:[0,1]
	v_pk_add_f32 v[26:27], v[26:27], v[116:117] neg_lo:[0,1] neg_hi:[0,1]
	v_pk_add_f32 v[28:29], v[28:29], v[116:117] neg_lo:[0,1] neg_hi:[0,1]
	v_pk_add_f32 v[30:31], v[30:31], v[116:117] neg_lo:[0,1] neg_hi:[0,1]
	v_pk_add_f32 v[32:33], v[32:33], v[116:117] neg_lo:[0,1] neg_hi:[0,1]
	v_pk_mul_f32 v[66:67], v[18:19], v[18:19]
	v_pk_mul_f32 v[68:69], v[20:21], v[20:21]
	v_pk_fma_f32 v[66:67], v[22:23], v[22:23], v[66:67]
	v_pk_fma_f32 v[68:69], v[24:25], v[24:25], v[68:69]
	v_pk_fma_f32 v[66:67], v[26:27], v[26:27], v[66:67]
	v_pk_fma_f32 v[68:69], v[28:29], v[28:29], v[68:69]
	v_pk_fma_f32 v[66:67], v[30:31], v[30:31], v[66:67]
	v_pk_fma_f32 v[68:69], v[32:33], v[32:33], v[68:69]
	v_pk_add_f32 v[66:67], v[66:67], v[68:69]
	v_add_f32_e32 v66, v66, v67
	s_nop 1
	v_add_f32_dpp v66, v66, v66 row_shr:1 row_mask:0xf bank_mask:0xf bound_ctrl:1
	s_nop 1
	v_add_f32_dpp v66, v66, v66 row_shr:2 row_mask:0xf bank_mask:0xf bound_ctrl:1
	s_nop 1
	v_add_f32_dpp v66, v66, v66 row_shr:4 row_mask:0xf bank_mask:0xf bound_ctrl:1
	s_nop 1
	v_add_f32_dpp v66, v66, v66 row_shr:8 row_mask:0xf bank_mask:0xf bound_ctrl:1
	s_nop 0
	v_readlane_b32 s9, v66, 15
	v_readlane_b32 s10, v66, 31
	v_readlane_b32 s11, v66, 47
	v_readlane_b32 vcc_lo, v66, 63
	s_nop 1
	v_mov_b32_e32 v66, s9
	v_add_f32_e32 v66, s10, v66
	v_add_f32_e32 v66, s11, v66
	v_add_f32_e32 v66, vcc_lo, v66
	v_mul_f32_e32 v66, 0x3a800000, v66
	v_add_f32_e32 v66, 0x3727c5ac, v66
	v_rsq_f32_e32 v118, v66
	s_nop 0
	v_mov_b32_e32 v119, v118
	v_pk_mul_f32 v[18:19], v[18:19], v[118:119]
	v_pk_mul_f32 v[20:21], v[20:21], v[118:119]
	v_pk_mul_f32 v[22:23], v[22:23], v[118:119]
	v_pk_mul_f32 v[24:25], v[24:25], v[118:119]
	v_pk_mul_f32 v[26:27], v[26:27], v[118:119]
	v_pk_mul_f32 v[28:29], v[28:29], v[118:119]
	v_pk_mul_f32 v[30:31], v[30:31], v[118:119]
	v_pk_mul_f32 v[32:33], v[32:33], v[118:119]
	v_pk_fma_f32 v[76:77], v[18:19], v[34:35], v[50:51]
	v_pk_fma_f32 v[78:79], v[20:21], v[36:37], v[52:53]
	v_pk_fma_f32 v[80:81], v[22:23], v[38:39], v[54:55]
	v_pk_fma_f32 v[82:83], v[24:25], v[40:41], v[56:57]
	v_pk_fma_f32 v[84:85], v[26:27], v[42:43], v[58:59]
	v_pk_fma_f32 v[86:87], v[28:29], v[44:45], v[60:61]
	v_pk_fma_f32 v[88:89], v[30:31], v[46:47], v[62:63]
	v_pk_fma_f32 v[90:91], v[32:33], v[48:49], v[64:65]
	s_cmp_lg_u32 s8, 0
	s_cbranch_scc1 .Lln2_f32_1
	v_cvt_pk_bf16_f32 v92, v76, v77
	v_cvt_pk_bf16_f32 v93, v78, v79
	v_cvt_pk_bf16_f32 v94, v80, v81
	v_cvt_pk_bf16_f32 v95, v82, v83
	v_cvt_pk_bf16_f32 v96, v84, v85
	v_cvt_pk_bf16_f32 v97, v86, v87
	v_cvt_pk_bf16_f32 v98, v88, v89
	v_cvt_pk_bf16_f32 v99, v90, v91
	global_store_dwordx2 v115, v[92:93], s[2:3] offset:0
	global_store_dwordx2 v115, v[94:95], s[2:3] offset:512
	global_store_dwordx2 v115, v[96:97], s[2:3] offset:1024
	global_store_dwordx2 v115, v[98:99], s[2:3] offset:1536
	s_branch .Lln2_st_1

; __device__ __forceinline__ void phase_ln(float* R, const float* __restrict__ g, const float* __restrict__ b, bf16_t* xbf, float samp_scale, const float* __restrict__ part, int nsplit, bool f32_all) {
;     ...
;   for (int r = gw; r < MT; r += nw) {
;     float* row = R + (size_t)r * 1024;
;     f32x4 v[4];
; #pragma unroll
;     for (int i = 0; i < 4; ++i) v[i] = *(const f32x4*)(row + i * 256 + lane * 4);
;     if (r >= MP) {
;       for (int sp = 0; sp < nsplit; ++sp) {
;         const float* prow = part + ((size_t)sp * MS + (r - MP)) * 1024;
; #pragma unroll
;         for (int i = 0; i < 4; ++i) v[i] = v[i] + *(const f32x4*)(prow + i * 256 + lane * 4);
;       }
;     }
;     float s = 0.f;
; #pragma unroll
;     for (int i = 0; i < 4; ++i) s += v[i][0] + v[i][1] + v[i][2] + v[i][3];
; #pragma unroll
;     for (int o = 32; o >= 1; o >>= 1) s += __shfl_xor(s, o);
;     const float mean = s * (1.f / 1024.f);
;     float ss = 0.f;
; #pragma unroll
;     for (int i = 0; i < 4; ++i) { v[i] = v[i] - mean; ss += v[i][0] * v[i][0] + v[i][1] * v[i][1] + v[i][2] * v[i][2] + v[i][3] * v[i][3]; }
; #pragma unroll
;     for (int o = 32; o >= 1; o >>= 1) ss += __shfl_xor(ss, o);
;     const float rstd = rsqrtf(ss * (1.f / 1024.f) + LN_EPS);
; #pragma unroll
;     for (int i = 0; i < 4; ++i) {
;       const f32x4 y = v[i] * rstd * gv[i] + bv[i];
;       if (r >= MP) *(f32x4*)(row + i * 256 + lane * 4) = y * samp_scale;
;       else if (f32_all) *(f32x4*)(row + i * 256 + lane * 4) = y;
;       if (xbf) {
;         u32x2 wv;
;         wv[0] = cvt_pk_bf16(y[0], y[1]); wv[1] = cvt_pk_bf16(y[2], y[3]);
;         *(u32x2*)(xbf + (size_t)r * 1024 + i * 256 + lane * 4) = wv;
;       }
;     }
.Lln2_st_1:
	s_add_u32 s2, s2, 0x80000
	s_addc_u32 s3, s3, 0
	s_add_u32 s0, s0, 0x100000
	s_addc_u32 s1, s1, 0
	global_load_dwordx4 v[18:21], v114, s[0:1] offset:0
	global_load_dwordx4 v[22:25], v114, s[0:1] offset:1024
	global_load_dwordx4 v[26:29], v114, s[0:1] offset:2048
	global_load_dwordx4 v[30:33], v114, s[0:1] offset:3072
	s_waitcnt vmcnt(8)
	v_pk_add_f32 v[66:67], v[0:1], v[2:3]
	v_pk_add_f32 v[68:69], v[4:5], v[6:7]
	v_pk_add_f32 v[70:71], v[8:9], v[10:11]
	v_pk_add_f32 v[72:73], v[12:13], v[14:15]
	v_pk_add_f32 v[66:67], v[66:67], v[68:69]
	v_pk_add_f32 v[70:71], v[70:71], v[72:73]
	v_pk_add_f32 v[66:67], v[66:67], v[70:71]
	v_add_f32_e32 v66, v66, v67
	s_nop 1
	v_add_f32_dpp v66, v66, v66 row_shr:1 row_mask:0xf bank_mask:0xf bound_ctrl:1
	s_nop 1
	v_add_f32_dpp v66, v66, v66 row_shr:2 row_mask:0xf bank_mask:0xf bound_ctrl:1
	s_nop 1
	v_add_f32_dpp v66, v66, v66 row_shr:4 row_mask:0xf bank_mask:0xf bound_ctrl:1
	s_nop 1
	v_add_f32_dpp v66, v66, v66 row_shr:8 row_mask:0xf bank_mask:0xf bound_ctrl:1
	s_nop 0
	v_readlane_b32 s9, v66, 15
	v_readlane_b32 s10, v66, 31
	v_readlane_b32 s11, v66, 47
	v_readlane_b32 vcc_lo, v66, 63
	s_nop 1
	v_mov_b32_e32 v66, s9
	v_add_f32_e32 v66, s10, v66
	v_add_f32_e32 v66, s11, v66
	v_add_f32_e32 v66, vcc_lo, v66
	v_mul_f32_e32 v116, 0x3a800000, v66
	v_mov_b32_e32 v117, v116
	v_pk_add_f32 v[0:1], v[0:1], v[116:117] neg_lo:[0,1] neg_hi:[0,1]
	v_pk_add_f32 v[2:3], v[2:3], v[116:117] neg_lo:[0,1] neg_hi:[0,1]
	v_pk_add_f32 v[4:5], v[4:5], v[116:117] neg_lo:[0,1] neg_hi:[0,1]
	v_pk_add_f32 v[6:7], v[6:7], v[116:117] neg_lo:[0,1] neg_hi:[0,1]
	v_pk_add_f32 v[8:9], v[8:9], v[116:117] neg_lo:[0,1] neg_hi:[0,1]
	v_pk_add_f32 v[10:11], v[10:11], v[116:117] neg_lo:[0,1] neg_hi:[0,1]
	v_pk_add_f32 v[12:13], v[12:13], v[116:117] neg_lo:[0,1] neg_hi:[0,1]
	v_pk_add_f32 v[14:15], v[14:15], v[116:117] neg_lo:[0,1] neg_hi:[0,1]
	v_pk_mul_f32 v[66:67], v[0:1], v[0:1]
	v_pk_mul_f32 v[68:69], v[2:3], v[2:3]
	v_pk_fma_f32 v[66:67], v[4:5], v[4:5], v[66:67]
	v_pk_fma_f32 v[68:69], v[6:7], v[6:7], v[68:69]
	v_pk_fma_f32 v[66:67], v[8:9], v[8:9], v[66:67]
	v_pk_fma_f32 v[68:69], v[10:11], v[10:11], v[68:69]
	v_pk_fma_f32 v[66:67], v[12:13], v[12:13], v[66:67]
	v_pk_fma_f32 v[68:69], v[14:15], v[14:15], v[68:69]
	v_pk_add_f32 v[66:67], v[66:67], v[68:69]
	v_add_f32_e32 v66, v66, v67
	s_nop 1
	v_add_f32_dpp v66, v66, v66 row_shr:1 row_mask:0xf bank_mask:0xf bound_ctrl:1
	s_nop 1
	v_add_f32_dpp v66, v66, v66 row_shr:2 row_mask:0xf bank_mask:0xf bound_ctrl:1
	s_nop 1
	v_add_f32_dpp v66, v66, v66 row_shr:4 row_mask:0xf bank_mask:0xf bound_ctrl:1
	s_nop 1
	v_add_f32_dpp v66, v66, v66 row_shr:8 row_mask:0xf bank_mask:0xf bound_ctrl:1
	s_nop 0
	v_readlane_b32 s9, v66, 15
	v_readlane_b32 s10, v66, 31
	v_readlane_b32 s11, v66, 47
	v_readlane_b32 vcc_lo, v66, 63
	s_nop 1
	v_mov_b32_e32 v66, s9
	v_add_f32_e32 v66, s10, v66
	v_add_f32_e32 v66, s11, v66
	v_add_f32_e32 v66, vcc_lo, v66
	v_mul_f32_e32 v66, 0x3a800000, v66
	v_add_f32_e32 v66, 0x3727c5ac, v66
	v_rsq_f32_e32 v118, v66
	s_nop 0
	v_mov_b32_e32 v119, v118
	v_pk_mul_f32 v[0:1], v[0:1], v[118:119]
	v_pk_mul_f32 v[2:3], v[2:3], v[118:119]
	v_pk_mul_f32 v[4:5], v[4:5], v[118:119]
	v_pk_mul_f32 v[6:7], v[6:7], v[118:119]
	v_pk_mul_f32 v[8:9], v[8:9], v[118:119]
	v_pk_mul_f32 v[10:11], v[10:11], v[118:119]
	v_pk_mul_f32 v[12:13], v[12:13], v[118:119]
	v_pk_mul_f32 v[14:15], v[14:15], v[118:119]
	v_pk_fma_f32 v[76:77], v[0:1], v[34:35], v[50:51]
	v_pk_fma_f32 v[78:79], v[2:3], v[36:37], v[52:53]
	v_pk_fma_f32 v[80:81], v[4:5], v[38:39], v[54:55]
	v_pk_fma_f32 v[82:83], v[6:7], v[40:41], v[56:57]
	v_pk_fma_f32 v[84:85], v[8:9], v[42:43], v[58:59]
	v_pk_fma_f32 v[86:87], v[10:11], v[44:45], v[60:61]
	v_pk_fma_f32 v[88:89], v[12:13], v[46:47], v[62:63]
	v_pk_fma_f32 v[90:91], v[14:15], v[48:49], v[64:65]
	s_cmp_lg_u32 s8, 0
	s_cbranch_scc1 .Lln2_f32_2
	v_cvt_pk_bf16_f32 v92, v76, v77
	v_cvt_pk_bf16_f32 v93, v78, v79
	v_cvt_pk_bf16_f32 v94, v80, v81
	v_cvt_pk_bf16_f32 v95, v82, v83
	v_cvt_pk_bf16_f32 v96, v84, v85
	v_cvt_pk_bf16_f32 v97, v86, v87
	v_cvt_pk_bf16_f32 v98, v88, v89
	v_cvt_pk_bf16_f32 v99, v90, v91
	global_store_dwordx2 v115, v[92:93], s[2:3] offset:0
	global_store_dwordx2 v115, v[94:95], s[2:3] offset:512
	global_store_dwordx2 v115, v[96:97], s[2:3] offset:1024
	global_store_dwordx2 v115, v[98:99], s[2:3] offset:1536
	s_branch .Lln2_st_2

; __device__ __forceinline__ void phase_ln(float* R, const float* __restrict__ g, const float* __restrict__ b, bf16_t* xbf, float samp_scale, const float* __restrict__ part, int nsplit, bool f32_all) {
;     ...
;   for (int r = gw; r < MT; r += nw) {
;     float* row = R + (size_t)r * 1024;
;     f32x4 v[4];
; #pragma unroll
;     for (int i = 0; i < 4; ++i) v[i] = *(const f32x4*)(row + i * 256 + lane * 4);
;     if (r >= MP) {
;       for (int sp = 0; sp < nsplit; ++sp) {
;         const float* prow = part + ((size_t)sp * MS + (r - MP)) * 1024;
; #pragma unroll
;         for (int i = 0; i < 4; ++i) v[i] = v[i] + *(const f32x4*)(prow + i * 256 + lane * 4);
;       }
;     }
;     float s = 0.f;
; #pragma unroll
;     for (int i = 0; i < 4; ++i) s += v[i][0] + v[i][1] + v[i][2] + v[i][3];
; #pragma unroll
;     for (int o = 32; o >= 1; o >>= 1) s += __shfl_xor(s, o);
;     const float mean = s * (1.f / 1024.f);
;     float ss = 0.f;
; #pragma unroll
;     for (int i = 0; i < 4; ++i) { v[i] = v[i] - mean; ss += v[i][0] * v[i][0] + v[i][1] * v[i][1] + v[i][2] * v[i][2] + v[i][3] * v[i][3]; }
; #pragma unroll
;     for (int o = 32; o >= 1; o >>= 1) ss += __shfl_xor(ss, o);
;     const float rstd = rsqrtf(ss * (1.f / 1024.f) + LN_EPS);
; #pragma unroll
;     for (int i = 0; i < 4; ++i) {
;       const f32x4 y = v[i] * rstd * gv[i] + bv[i];
;       if (r >= MP) *(f32x4*)(row + i * 256 + lane * 4) = y * samp_scale;
;       else if (f32_all) *(f32x4*)(row + i * 256 + lane * 4) = y;
;       if (xbf) {
;         u32x2 wv;
;         wv[0] = cvt_pk_bf16(y[0], y[1]); wv[1] = cvt_pk_bf16(y[2], y[3]);
;         *(u32x2*)(xbf + (size_t)r * 1024 + i * 256 + lane * 4) = wv;
;       }
;     }
.Lln2_st_14:
	s_add_u32 s2, s2, 0x80000
	s_addc_u32 s3, s3, 0
	s_waitcnt vmcnt(4)
	v_pk_add_f32 v[66:67], v[18:19], v[20:21]
	v_pk_add_f32 v[68:69], v[22:23], v[24:25]
	v_pk_add_f32 v[70:71], v[26:27], v[28:29]
	v_pk_add_f32 v[72:73], v[30:31], v[32:33]
	v_pk_add_f32 v[66:67], v[66:67], v[68:69]
	v_pk_add_f32 v[70:71], v[70:71], v[72:73]
	v_pk_add_f32 v[66:67], v[66:67], v[70:71]
	v_add_f32_e32 v66, v66, v67
	s_nop 1
	v_add_f32_dpp v66, v66, v66 row_shr:1 row_mask:0xf bank_mask:0xf bound_ctrl:1
	s_nop 1
	v_add_f32_dpp v66, v66, v66 row_shr:2 row_mask:0xf bank_mask:0xf bound_ctrl:1
	s_nop 1
	v_add_f32_dpp v66, v66, v66 row_shr:4 row_mask:0xf bank_mask:0xf bound_ctrl:1
	s_nop 1
	v_add_f32_dpp v66, v66, v66 row_shr:8 row_mask:0xf bank_mask:0xf bound_ctrl:1
	s_nop 0
	v_readlane_b32 s9, v66, 15
	v_readlane_b32 s10, v66, 31
	v_readlane_b32 s11, v66, 47
	v_readlane_b32 vcc_lo, v66, 63
	s_nop 1
	v_mov_b32_e32 v66, s9
	v_add_f32_e32 v66, s10, v66
	v_add_f32_e32 v66, s11, v66
	v_add_f32_e32 v66, vcc_lo, v66
	v_mul_f32_e32 v116, 0x3a800000, v66
	v_mov_b32_e32 v117, v116
	v_pk_add_f32 v[18:19], v[18:19], v[116:117] neg_lo:[0,1] neg_hi:[0,1]
	v_pk_add_f32 v[20:21], v[20:21], v[116:117] neg_lo:[0,1] neg_hi:[0,1]
	v_pk_add_f32 v[22:23], v[22:23], v[116:117] neg_lo:[0,1] neg_hi:[0,1]
	v_pk_add_f32 v[24:25], v[24:25], v[116:117] neg_lo:[0,1] neg_hi:[0,1]
	v_pk_add_f32 v[26:27], v[26:27], v[116:117] neg_lo:[0,1] neg_hi:[0,1]
	v_pk_add_f32 v[28:29], v[28:29], v[116:117] neg_lo:[0,1] neg_hi:[0,1]
	v_pk_add_f32 v[30:31], v[30:31], v[116:117] neg_lo:[0,1] neg_hi:[0,1]
	v_pk_add_f32 v[32:33], v[32:33], v[116:117] neg_lo:[0,1] neg_hi:[0,1]
	v_pk_mul_f32 v[66:67], v[18:19], v[18:19]
	v_pk_mul_f32 v[68:69], v[20:21], v[20:21]
	v_pk_fma_f32 v[66:67], v[22:23], v[22:23], v[66:67]
	v_pk_fma_f32 v[68:69], v[24:25], v[24:25], v[68:69]
	v_pk_fma_f32 v[66:67], v[26:27], v[26:27], v[66:67]
	v_pk_fma_f32 v[68:69], v[28:29], v[28:29], v[68:69]
	v_pk_fma_f32 v[66:67], v[30:31], v[30:31], v[66:67]
	v_pk_fma_f32 v[68:69], v[32:33], v[32:33], v[68:69]
	v_pk_add_f32 v[66:67], v[66:67], v[68:69]
	v_add_f32_e32 v66, v66, v67
	s_nop 1
	v_add_f32_dpp v66, v66, v66 row_shr:1 row_mask:0xf bank_mask:0xf bound_ctrl:1
	s_nop 1
	v_add_f32_dpp v66, v66, v66 row_shr:2 row_mask:0xf bank_mask:0xf bound_ctrl:1
	s_nop 1
	v_add_f32_dpp v66, v66, v66 row_shr:4 row_mask:0xf bank_mask:0xf bound_ctrl:1
	s_nop 1
	v_add_f32_dpp v66, v66, v66 row_shr:8 row_mask:0xf bank_mask:0xf bound_ctrl:1
	s_nop 0
	v_readlane_b32 s9, v66, 15
	v_readlane_b32 s10, v66, 31
	v_readlane_b32 s11, v66, 47
	v_readlane_b32 vcc_lo, v66, 63
	s_nop 1
	v_mov_b32_e32 v66, s9
	v_add_f32_e32 v66, s10, v66
	v_add_f32_e32 v66, s11, v66
	v_add_f32_e32 v66, vcc_lo, v66
	v_mul_f32_e32 v66, 0x3a800000, v66
	v_add_f32_e32 v66, 0x3727c5ac, v66
	v_rsq_f32_e32 v118, v66
	s_nop 0
	v_mov_b32_e32 v119, v118
	v_pk_mul_f32 v[18:19], v[18:19], v[118:119]
	v_pk_mul_f32 v[20:21], v[20:21], v[118:119]
	v_pk_mul_f32 v[22:23], v[22:23], v[118:119]
	v_pk_mul_f32 v[24:25], v[24:25], v[118:119]
	v_pk_mul_f32 v[26:27], v[26:27], v[118:119]
	v_pk_mul_f32 v[28:29], v[28:29], v[118:119]
	v_pk_mul_f32 v[30:31], v[30:31], v[118:119]
	v_pk_mul_f32 v[32:33], v[32:33], v[118:119]
	v_pk_fma_f32 v[76:77], v[18:19], v[34:35], v[50:51]
	v_pk_fma_f32 v[78:79], v[20:21], v[36:37], v[52:53]
	v_pk_fma_f32 v[80:81], v[22:23], v[38:39], v[54:55]
	v_pk_fma_f32 v[82:83], v[24:25], v[40:41], v[56:57]
	v_pk_fma_f32 v[84:85], v[26:27], v[42:43], v[58:59]
	v_pk_fma_f32 v[86:87], v[28:29], v[44:45], v[60:61]
	v_pk_fma_f32 v[88:89], v[30:31], v[46:47], v[62:63]
	v_pk_fma_f32 v[90:91], v[32:33], v[48:49], v[64:65]
	s_cmp_lg_u32 s8, 0
	s_cbranch_scc1 .Lln2_f32_15
	v_cvt_pk_bf16_f32 v92, v76, v77
	v_cvt_pk_bf16_f32 v93, v78, v79
	v_cvt_pk_bf16_f32 v94, v80, v81
	v_cvt_pk_bf16_f32 v95, v82, v83
	v_cvt_pk_bf16_f32 v96, v84, v85
	v_cvt_pk_bf16_f32 v97, v86, v87
	v_cvt_pk_bf16_f32 v98, v88, v89
	v_cvt_pk_bf16_f32 v99, v90, v91
	global_store_dwordx2 v115, v[92:93], s[2:3] offset:0
	global_store_dwordx2 v115, v[94:95], s[2:3] offset:512
	global_store_dwordx2 v115, v[96:97], s[2:3] offset:1024
	global_store_dwordx2 v115, v[98:99], s[2:3] offset:1536
	s_branch .Lln2_st_15

; __device__ __forceinline__ void phase_ln(float* R, const float* __restrict__ g, const float* __restrict__ b, bf16_t* xbf, float samp_scale, const float* __restrict__ part, int nsplit, bool f32_all) {
;     ...
;   for (int r = gw; r < MT; r += nw) {
;     float* row = R + (size_t)r * 1024;
;     f32x4 v[4];
; #pragma unroll
;     for (int i = 0; i < 4; ++i) v[i] = *(const f32x4*)(row + i * 256 + lane * 4);
;     if (r >= MP) {
;       for (int sp = 0; sp < nsplit; ++sp) {
;         const float* prow = part + ((size_t)sp * MS + (r - MP)) * 1024;
; #pragma unroll
;         for (int i = 0; i < 4; ++i) v[i] = v[i] + *(const f32x4*)(prow + i * 256 + lane * 4);
;       }
;     }
.Lln2_st_15:
	s_add_u32 s2, s2, 0x80000
	s_addc_u32 s3, s3, 0
	v_readfirstlane_b32 s10, v244
	v_readlane_b32 s9, v254, 6
	s_lshr_b32 s10, s10, 6
	s_cmp_ge_u32 s10, 2
	s_cbranch_scc1 .Lln2_done
	s_lshl_b32 s9, s9, 1
	s_add_i32 s9, s9, s10
	s_lshl_b32 s11, s9, 12
	s_add_u32 s11, s11, 0x8000000
	s_add_u32 s0, s4, s11
	s_addc_u32 s1, s5, 0
	s_lshl_b32 s11, s9, 11
	s_add_u32 s11, s11, 0x79c0000
	s_add_u32 s2, s6, s11
	s_addc_u32 s3, s7, 0
	s_lshl_b32 s11, s9, 12
	s_add_u32 s11, s11, 0x1e482000
	s_add_u32 s10, s6, s11
	s_addc_u32 s11, s7, 0
	global_load_dwordx4 v[0:3], v114, s[0:1] offset:0
	global_load_dwordx4 v[4:7], v114, s[0:1] offset:1024
	global_load_dwordx4 v[8:11], v114, s[0:1] offset:2048
	global_load_dwordx4 v[12:15], v114, s[0:1] offset:3072
	global_load_dwordx4 v[18:21], v114, s[10:11] offset:0
	global_load_dwordx4 v[22:25], v114, s[10:11] offset:1024
	global_load_dwordx4 v[26:29], v114, s[10:11] offset:2048
	global_load_dwordx4 v[30:33], v114, s[10:11] offset:3072
	s_add_u32 s10, s10, 0x200000
	s_addc_u32 s11, s11, 0
	global_load_dwordx4 v[66:69], v114, s[10:11] offset:0
	global_load_dwordx4 v[70:73], v114, s[10:11] offset:1024
	global_load_dwordx4 v[74:77], v114, s[10:11] offset:2048
	global_load_dwordx4 v[78:81], v114, s[10:11] offset:3072
	s_add_u32 s10, s10, 0x200000
	s_addc_u32 s11, s11, 0
	global_load_dwordx4 v[82:85], v114, s[10:11] offset:0
	global_load_dwordx4 v[86:89], v114, s[10:11] offset:1024
	global_load_dwordx4 v[90:93], v114, s[10:11] offset:2048
	global_load_dwordx4 v[94:97], v114, s[10:11] offset:3072
	s_add_u32 s10, s10, 0x200000
	s_addc_u32 s11, s11, 0
	global_load_dwordx4 v[98:101], v114, s[10:11] offset:0
	global_load_dwordx4 v[102:105], v114, s[10:11] offset:1024
	global_load_dwordx4 v[106:109], v114, s[10:11] offset:2048
	global_load_dwordx4 v[110:113], v114, s[10:11] offset:3072
	s_add_u32 s10, s10, 0x200000
	s_addc_u32 s11, s11, 0
	s_waitcnt vmcnt(0)
	v_pk_add_f32 v[0:1], v[0:1], v[18:19]
	v_pk_add_f32 v[2:3], v[2:3], v[20:21]
	v_pk_add_f32 v[4:5], v[4:5], v[22:23]
	v_pk_add_f32 v[6:7], v[6:7], v[24:25]
	v_pk_add_f32 v[8:9], v[8:9], v[26:27]
	v_pk_add_f32 v[10:11], v[10:11], v[28:29]
	v_pk_add_f32 v[12:13], v[12:13], v[30:31]
	v_pk_add_f32 v[14:15], v[14:15], v[32:33]
	v_pk_add_f32 v[0:1], v[0:1], v[66:67]
	v_pk_add_f32 v[2:3], v[2:3], v[68:69]
	v_pk_add_f32 v[4:5], v[4:5], v[70:71]
	v_pk_add_f32 v[6:7], v[6:7], v[72:73]
	v_pk_add_f32 v[8:9], v[8:9], v[74:75]
	v_pk_add_f32 v[10:11], v[10:11], v[76:77]
	v_pk_add_f32 v[12:13], v[12:13], v[78:79]
	v_pk_add_f32 v[14:15], v[14:15], v[80:81]
	v_pk_add_f32 v[0:1], v[0:1], v[82:83]
	v_pk_add_f32 v[2:3], v[2:3], v[84:85]
	v_pk_add_f32 v[4:5], v[4:5], v[86:87]
	v_pk_add_f32 v[6:7], v[6:7], v[88:89]
	v_pk_add_f32 v[8:9], v[8:9], v[90:91]
	v_pk_add_f32 v[10:11], v[10:11], v[92:93]
	v_pk_add_f32 v[12:13], v[12:13], v[94:95]
	v_pk_add_f32 v[14:15], v[14:15], v[96:97]
	v_pk_add_f32 v[0:1], v[0:1], v[98:99]
	v_pk_add_f32 v[2:3], v[2:3], v[100:101]
	v_pk_add_f32 v[4:5], v[4:5], v[102:103]
	v_pk_add_f32 v[6:7], v[6:7], v[104:105]
	v_pk_add_f32 v[8:9], v[8:9], v[106:107]
	v_pk_add_f32 v[10:11], v[10:11], v[108:109]
	v_pk_add_f32 v[12:13], v[12:13], v[110:111]
	v_pk_add_f32 v[14:15], v[14:15], v[112:113]
	global_load_dwordx4 v[18:21], v114, s[10:11] offset:0
	global_load_dwordx4 v[22:25], v114, s[10:11] offset:1024
	global_load_dwordx4 v[26:29], v114, s[10:11] offset:2048
	global_load_dwordx4 v[30:33], v114, s[10:11] offset:3072
	s_add_u32 s10, s10, 0x200000
	s_addc_u32 s11, s11, 0
	global_load_dwordx4 v[66:69], v114, s[10:11] offset:0
	global_load_dwordx4 v[70:73], v114, s[10:11] offset:1024
	global_load_dwordx4 v[74:77], v114, s[10:11] offset:2048
	global_load_dwordx4 v[78:81], v114, s[10:11] offset:3072
	s_add_u32 s10, s10, 0x200000
	s_addc_u32 s11, s11, 0
	global_load_dwordx4 v[82:85], v114, s[10:11] offset:0
	global_load_dwordx4 v[86:89], v114, s[10:11] offset:1024
	global_load_dwordx4 v[90:93], v114, s[10:11] offset:2048
	global_load_dwordx4 v[94:97], v114, s[10:11] offset:3072
	s_add_u32 s10, s10, 0x200000
	s_addc_u32 s11, s11, 0
	global_load_dwordx4 v[98:101], v114, s[10:11] offset:0
	global_load_dwordx4 v[102:105], v114, s[10:11] offset:1024
	global_load_dwordx4 v[106:109], v114, s[10:11] offset:2048
	global_load_dwordx4 v[110:113], v114, s[10:11] offset:3072
	s_add_u32 s10, s10, 0x200000
	s_addc_u32 s11, s11, 0
	s_waitcnt vmcnt(0)
; __device__ __forceinline__ void phase_ln(float* R, const float* __restrict__ g, const float* __restrict__ b, bf16_t* xbf, float samp_scale, const float* __restrict__ part, int nsplit, bool f32_all) {
;     ...
;       for (int sp = 0; sp < nsplit; ++sp) {
;         const float* prow = part + ((size_t)sp * MS + (r - MP)) * 1024;
; #pragma unroll
;         for (int i = 0; i < 4; ++i) v[i] = v[i] + *(const f32x4*)(prow + i * 256 + lane * 4);
;       }
;     }
;     float s = 0.f;
; #pragma unroll
;     for (int i = 0; i < 4; ++i) s += v[i][0] + v[i][1] + v[i][2] + v[i][3];
; #pragma unroll
;     for (int o = 32; o >= 1; o >>= 1) s += __shfl_xor(s, o);
;     const float mean = s * (1.f / 1024.f);
;     float ss = 0.f;
; #pragma unroll
;     for (int i = 0; i < 4; ++i) { v[i] = v[i] - mean; ss += v[i][0] * v[i][0] + v[i][1] * v[i][1] + v[i][2] * v[i][2] + v[i][3] * v[i][3]; }
; #pragma unroll
;     for (int o = 32; o >= 1; o >>= 1) ss += __shfl_xor(ss, o);
;     const float rstd = rsqrtf(ss * (1.f / 1024.f) + LN_EPS);
; #pragma unroll
;     for (int i = 0; i < 4; ++i) {
;       const f32x4 y = v[i] * rstd * gv[i] + bv[i];
;       if (r >= MP) *(f32x4*)(row + i * 256 + lane * 4) = y * samp_scale;
;       else if (f32_all) *(f32x4*)(row + i * 256 + lane * 4) = y;
;       if (xbf) {
;         u32x2 wv;
;         wv[0] = cvt_pk_bf16(y[0], y[1]); wv[1] = cvt_pk_bf16(y[2], y[3]);
;         *(u32x2*)(xbf + (size_t)r * 1024 + i * 256 + lane * 4) = wv;
;       }
;     }
	v_pk_add_f32 v[0:1], v[0:1], v[18:19]
	v_pk_add_f32 v[2:3], v[2:3], v[20:21]
	v_pk_add_f32 v[4:5], v[4:5], v[22:23]
	v_pk_add_f32 v[6:7], v[6:7], v[24:25]
	v_pk_add_f32 v[8:9], v[8:9], v[26:27]
	v_pk_add_f32 v[10:11], v[10:11], v[28:29]
	v_pk_add_f32 v[12:13], v[12:13], v[30:31]
	v_pk_add_f32 v[14:15], v[14:15], v[32:33]
	v_pk_add_f32 v[0:1], v[0:1], v[66:67]
	v_pk_add_f32 v[2:3], v[2:3], v[68:69]
	v_pk_add_f32 v[4:5], v[4:5], v[70:71]
	v_pk_add_f32 v[6:7], v[6:7], v[72:73]
	v_pk_add_f32 v[8:9], v[8:9], v[74:75]
	v_pk_add_f32 v[10:11], v[10:11], v[76:77]
	v_pk_add_f32 v[12:13], v[12:13], v[78:79]
	v_pk_add_f32 v[14:15], v[14:15], v[80:81]
	v_pk_add_f32 v[0:1], v[0:1], v[82:83]
	v_pk_add_f32 v[2:3], v[2:3], v[84:85]
	v_pk_add_f32 v[4:5], v[4:5], v[86:87]
	v_pk_add_f32 v[6:7], v[6:7], v[88:89]
	v_pk_add_f32 v[8:9], v[8:9], v[90:91]
	v_pk_add_f32 v[10:11], v[10:11], v[92:93]
	v_pk_add_f32 v[12:13], v[12:13], v[94:95]
	v_pk_add_f32 v[14:15], v[14:15], v[96:97]
	v_pk_add_f32 v[0:1], v[0:1], v[98:99]
	v_pk_add_f32 v[2:3], v[2:3], v[100:101]
	v_pk_add_f32 v[4:5], v[4:5], v[102:103]
	v_pk_add_f32 v[6:7], v[6:7], v[104:105]
	v_pk_add_f32 v[8:9], v[8:9], v[106:107]
	v_pk_add_f32 v[10:11], v[10:11], v[108:109]
	v_pk_add_f32 v[12:13], v[12:13], v[110:111]
	v_pk_add_f32 v[14:15], v[14:15], v[112:113]
	v_pk_add_f32 v[66:67], v[0:1], v[2:3]
	v_pk_add_f32 v[68:69], v[4:5], v[6:7]
	v_pk_add_f32 v[70:71], v[8:9], v[10:11]
	v_pk_add_f32 v[72:73], v[12:13], v[14:15]
	v_pk_add_f32 v[66:67], v[66:67], v[68:69]
	v_pk_add_f32 v[70:71], v[70:71], v[72:73]
	v_pk_add_f32 v[66:67], v[66:67], v[70:71]
	v_add_f32_e32 v66, v66, v67
	s_nop 1
	v_add_f32_dpp v66, v66, v66 row_shr:1 row_mask:0xf bank_mask:0xf bound_ctrl:1
	s_nop 1
	v_add_f32_dpp v66, v66, v66 row_shr:2 row_mask:0xf bank_mask:0xf bound_ctrl:1
	s_nop 1
	v_add_f32_dpp v66, v66, v66 row_shr:4 row_mask:0xf bank_mask:0xf bound_ctrl:1
	s_nop 1
	v_add_f32_dpp v66, v66, v66 row_shr:8 row_mask:0xf bank_mask:0xf bound_ctrl:1
	s_nop 0
	v_readlane_b32 s9, v66, 15
	v_readlane_b32 s10, v66, 31
	v_readlane_b32 s11, v66, 47
	v_readlane_b32 vcc_lo, v66, 63
	s_nop 1
	v_mov_b32_e32 v66, s9
	v_add_f32_e32 v66, s10, v66
	v_add_f32_e32 v66, s11, v66
	v_add_f32_e32 v66, vcc_lo, v66
	v_mul_f32_e32 v116, 0x3a800000, v66
	v_mov_b32_e32 v117, v116
	v_pk_add_f32 v[0:1], v[0:1], v[116:117] neg_lo:[0,1] neg_hi:[0,1]
	v_pk_add_f32 v[2:3], v[2:3], v[116:117] neg_lo:[0,1] neg_hi:[0,1]
	v_pk_add_f32 v[4:5], v[4:5], v[116:117] neg_lo:[0,1] neg_hi:[0,1]
	v_pk_add_f32 v[6:7], v[6:7], v[116:117] neg_lo:[0,1] neg_hi:[0,1]
	v_pk_add_f32 v[8:9], v[8:9], v[116:117] neg_lo:[0,1] neg_hi:[0,1]
	v_pk_add_f32 v[10:11], v[10:11], v[116:117] neg_lo:[0,1] neg_hi:[0,1]
	v_pk_add_f32 v[12:13], v[12:13], v[116:117] neg_lo:[0,1] neg_hi:[0,1]
	v_pk_add_f32 v[14:15], v[14:15], v[116:117] neg_lo:[0,1] neg_hi:[0,1]
	v_pk_mul_f32 v[66:67], v[0:1], v[0:1]
	v_pk_mul_f32 v[68:69], v[2:3], v[2:3]
	v_pk_fma_f32 v[66:67], v[4:5], v[4:5], v[66:67]
	v_pk_fma_f32 v[68:69], v[6:7], v[6:7], v[68:69]
	v_pk_fma_f32 v[66:67], v[8:9], v[8:9], v[66:67]
	v_pk_fma_f32 v[68:69], v[10:11], v[10:11], v[68:69]
	v_pk_fma_f32 v[66:67], v[12:13], v[12:13], v[66:67]
	v_pk_fma_f32 v[68:69], v[14:15], v[14:15], v[68:69]
	v_pk_add_f32 v[66:67], v[66:67], v[68:69]
	v_add_f32_e32 v66, v66, v67
	s_nop 1
	v_add_f32_dpp v66, v66, v66 row_shr:1 row_mask:0xf bank_mask:0xf bound_ctrl:1
	s_nop 1
	v_add_f32_dpp v66, v66, v66 row_shr:2 row_mask:0xf bank_mask:0xf bound_ctrl:1
	s_nop 1
	v_add_f32_dpp v66, v66, v66 row_shr:4 row_mask:0xf bank_mask:0xf bound_ctrl:1
	s_nop 1
	v_add_f32_dpp v66, v66, v66 row_shr:8 row_mask:0xf bank_mask:0xf bound_ctrl:1
	s_nop 0
	v_readlane_b32 s9, v66, 15
	v_readlane_b32 s10, v66, 31
	v_readlane_b32 s11, v66, 47
	v_readlane_b32 vcc_lo, v66, 63
	s_nop 1
	v_mov_b32_e32 v66, s9
	v_add_f32_e32 v66, s10, v66
	v_add_f32_e32 v66, s11, v66
	v_add_f32_e32 v66, vcc_lo, v66
	v_mul_f32_e32 v66, 0x3a800000, v66
	v_add_f32_e32 v66, 0x3727c5ac, v66
	v_rsq_f32_e32 v118, v66
	s_nop 0
	v_mov_b32_e32 v119, v118
	v_pk_mul_f32 v[0:1], v[0:1], v[118:119]
	v_pk_mul_f32 v[2:3], v[2:3], v[118:119]
	v_pk_mul_f32 v[4:5], v[4:5], v[118:119]
	v_pk_mul_f32 v[6:7], v[6:7], v[118:119]
	v_pk_mul_f32 v[8:9], v[8:9], v[118:119]
	v_pk_mul_f32 v[10:11], v[10:11], v[118:119]
	v_pk_mul_f32 v[12:13], v[12:13], v[118:119]
	v_pk_mul_f32 v[14:15], v[14:15], v[118:119]
	v_pk_fma_f32 v[76:77], v[0:1], v[34:35], v[50:51]
	v_pk_fma_f32 v[78:79], v[2:3], v[36:37], v[52:53]
	v_pk_fma_f32 v[80:81], v[4:5], v[38:39], v[54:55]
	v_pk_fma_f32 v[82:83], v[6:7], v[40:41], v[56:57]
	v_pk_fma_f32 v[84:85], v[8:9], v[42:43], v[58:59]
	v_pk_fma_f32 v[86:87], v[10:11], v[44:45], v[60:61]
	v_pk_fma_f32 v[88:89], v[12:13], v[46:47], v[62:63]
	v_pk_fma_f32 v[90:91], v[14:15], v[48:49], v[64:65]
	s_cmp_lg_u32 s8, 0
	s_cselect_b32 s9, 1.0, 0x3fb504f3
	v_mov_b32_e32 v120, s9
	v_mov_b32_e32 v121, s9
	v_pk_mul_f32 v[0:1], v[76:77], v[120:121]
	v_pk_mul_f32 v[2:3], v[78:79], v[120:121]
	v_pk_mul_f32 v[4:5], v[80:81], v[120:121]
	v_pk_mul_f32 v[6:7], v[82:83], v[120:121]
	v_pk_mul_f32 v[8:9], v[84:85], v[120:121]
	v_pk_mul_f32 v[10:11], v[86:87], v[120:121]
	v_pk_mul_f32 v[12:13], v[88:89], v[120:121]
	v_pk_mul_f32 v[14:15], v[90:91], v[120:121]
	global_store_dwordx4 v114, v[0:3], s[0:1] offset:0
	global_store_dwordx4 v114, v[4:7], s[0:1] offset:1024
	global_store_dwordx4 v114, v[8:11], s[0:1] offset:2048
	global_store_dwordx4 v114, v[12:15], s[0:1] offset:3072
	s_cmp_lg_u32 s8, 0
	s_cbranch_scc1 .Lln2_done
	v_cvt_pk_bf16_f32 v92, v76, v77
	v_cvt_pk_bf16_f32 v93, v78, v79
	v_cvt_pk_bf16_f32 v94, v80, v81
	v_cvt_pk_bf16_f32 v95, v82, v83
	v_cvt_pk_bf16_f32 v96, v84, v85
	v_cvt_pk_bf16_f32 v97, v86, v87
	v_cvt_pk_bf16_f32 v98, v88, v89
	v_cvt_pk_bf16_f32 v99, v90, v91
	global_store_dwordx2 v115, v[92:93], s[2:3] offset:0
	global_store_dwordx2 v115, v[94:95], s[2:3] offset:512
	global_store_dwordx2 v115, v[96:97], s[2:3] offset:1024
	global_store_dwordx2 v115, v[98:99], s[2:3] offset:1536
